# combo5: combo3 + second LDS-DMA of the 8-read slots (P1/P3/P5/P7 stages) issued at the start of the next, lighter read slot; vmcnt(10)->(9)
# baseline (speedup 1.0000x reference)
; #define PG8_STAGE(bufoff, gbase, voff) do { _Pragma("unroll") for (int _i = 0; _i < 2; ++_i) \
;     __builtin_amdgcn_global_load_lds((const unsigned*)((const char*)(gbase) + (voff)[_i]), (LAS unsigned*)(lds + (bufoff) + ldsw + _i * 8192), 16, 0, 0); } while (0)
; #define PG8_LDA(dst, b, h) do { _Pragma("unroll") for (int m = 0; m < 4; ++m) _Pragma("unroll") for (int k = 0; k < 2; ++k) dst[m][k] = *(const LAS bf16x8*)(lds + PG8_SA(b, h) + aoff + m * 2048 + k * 1024); } while (0)
; #define PG8_LDB(dst, b, h) do { _Pragma("unroll") for (int n = 0; n < 2; ++n) _Pragma("unroll") for (int k = 0; k < 2; ++k) dst[n][k] = *(const LAS bf16x8*)(lds + PG8_SB(b, h) + boff + n * 2048 + k * 1024); } while (0)
; #define PG8_MMA(ai, bj, At, Bt) do { __builtin_amdgcn_s_setprio(1); _Pragma("unroll") for (int m = 0; m < 4; ++m) _Pragma("unroll") for (int n = 0; n < 2; ++n) _Pragma("unroll") for (int k = 0; k < 2; ++k) \
;     acc[ai][bj][m][n] = __builtin_amdgcn_mfma_f32_16x16x32_bf16(Bt[n][k], At[m][k], acc[ai][bj][m][n], 0, 0, 0); __builtin_amdgcn_s_setprio(0); } while (0)
; #define PG8_WAIT_V(n) asm volatile("s_waitcnt vmcnt(" #n ")" ::: "memory")
; #define PG8_WAIT_L(n) asm volatile("s_waitcnt lgkmcnt(" #n ")" ::: "memory")
; #define PG8_BAR __builtin_amdgcn_s_barrier()
; #define PG8_SCHED __builtin_amdgcn_sched_barrier(0)
; template <class Epi, class Sched = StaticOrder>
; DI void gemm_phase(LAS unsigned char* lds, const Gemm g, const Sched& S, const Epi& E) {
;     ...
;     for (int t = 0; t < nt; t += 2) {
;       const bool last = (t == nt - 2);
;       const char* a1 = cA + (size_t)(t + 1) * kstep;
;       const char* a2 = last ? nA : cA + (size_t)(t + 2) * kstep; const char* b2 = last ? nB : cB + (size_t)(t + 2) * kstep;
;       const char* a3 = a2 + kstep; const char* b3 = b2 + kstep;
;       PG8_LDB(B0, 0, 0); PG8_SCHED; PG8_LDA(At, 0, 0); PG8_STAGE(PG8_SA(1, 1), a1 + hstep, voffA);
;       PG8_WAIT_L(8); PG8_BAR; PG8_WAIT_L(0); PG8_MMA(0, 0, At, B0); PG8_BAR; PG8_SCHED;
;       PG8_LDB(B1, 0, 1); PG8_STAGE(PG8_SB(0, 0), b2, voffB);
;       PG8_BAR; PG8_WAIT_L(0); PG8_MMA(0, 1, At, B1); PG8_BAR;
;       PG8_LDA(At, 0, 1); PG8_STAGE(PG8_SA(0, 0), a2, voffA);
;       PG8_BAR; PG8_WAIT_L(0); PG8_MMA(1, 0, At, B0); PG8_BAR; PG8_SCHED;
;       PG8_STAGE(PG8_SB(0, 1), b2 + hstep, voffB);
;       PG8_WAIT_V(6); PG8_BAR; PG8_MMA(1, 1, At, B1); PG8_BAR;
.LBB0_346:
	s_add_u32 s8, s6, 0xfff80080
	s_addc_u32 s9, s7, -1
	s_cmp_eq_u32 s52, 28
	s_cselect_b32 s11, s31, s9
	s_cselect_b32 s10, s42, s8
	s_cselect_b32 s9, s29, s45
	s_cselect_b32 s8, s43, s44
	s_add_i32 m0, s48, 0xc000
	ds_read_b128 v[162:165], v174
	ds_read_b128 v[166:169], v174 offset:1024
	ds_read_b128 v[178:181], v174 offset:2048
	ds_read_b128 v[182:185], v174 offset:3072
	ds_read_b128 v[186:189], v174 offset:4096
	ds_read_b128 v[190:193], v174 offset:5120
	ds_read_b128 v[194:197], v174 offset:6144
	ds_read_b128 v[198:201], v174 offset:7168
	global_load_lds_dwordx4 v146, s[6:7]
	s_waitcnt lgkmcnt(0)
	s_setprio 1
	s_barrier
	v_mfma_f32_16x16x32_bf16 v[124:127], v[128:131], v[162:165], v[124:127]
	v_mfma_f32_16x16x32_bf16 v[120:123], v[154:157], v[162:165], v[120:123]
	v_mfma_f32_16x16x32_bf16 v[108:111], v[128:131], v[178:181], v[108:111]
	v_mfma_f32_16x16x32_bf16 v[104:107], v[154:157], v[178:181], v[104:107]
	v_mfma_f32_16x16x32_bf16 v[100:103], v[128:131], v[186:189], v[100:103]
	v_mfma_f32_16x16x32_bf16 v[92:95], v[154:157], v[186:189], v[92:95]
	v_mfma_f32_16x16x32_bf16 v[84:87], v[128:131], v[194:197], v[84:87]
	v_mfma_f32_16x16x32_bf16 v[76:79], v[154:157], v[194:197], v[76:79]
	v_mfma_f32_16x16x32_bf16 v[124:127], v[132:135], v[166:169], v[124:127]
	v_mfma_f32_16x16x32_bf16 v[120:123], v[158:161], v[166:169], v[120:123]
	v_mfma_f32_16x16x32_bf16 v[108:111], v[132:135], v[182:185], v[108:111]
	v_mfma_f32_16x16x32_bf16 v[104:107], v[158:161], v[182:185], v[104:107]
	v_mfma_f32_16x16x32_bf16 v[100:103], v[132:135], v[190:193], v[100:103]
	v_mfma_f32_16x16x32_bf16 v[92:95], v[158:161], v[190:193], v[92:95]
	v_mfma_f32_16x16x32_bf16 v[84:87], v[132:135], v[198:201], v[84:87]
	v_mfma_f32_16x16x32_bf16 v[76:79], v[158:161], v[198:201], v[76:79]
	s_barrier
	s_setprio 0
	s_add_i32 m0, s48, 0xe000
	s_nop 0
	global_load_lds_dwordx4 v148, s[6:7]
	s_add_i32 s53, s65, s41
	s_add_u32 s98, s8, 0x80
	s_addc_u32 s99, s9, 0
	s_add_u32 s100, s10, 0x80
	s_addc_u32 s101, s11, 0
	s_mov_b32 m0, s53
	ds_read_b128 v[202:205], v175
	ds_read_b128 v[206:209], v175 offset:1024
	ds_read_b128 v[212:215], v175 offset:2048
	ds_read_b128 v[216:219], v175 offset:3072
	global_load_lds_dwordx4 v140, s[8:9]
	s_add_i32 m0, s53, 0x2000
	s_nop 0
	global_load_lds_dwordx4 v136, s[8:9]
	s_waitcnt lgkmcnt(0)
	s_setprio 1
	s_barrier
	v_mfma_f32_16x16x32_bf16 v[116:119], v[202:205], v[162:165], v[116:119]
	v_mfma_f32_16x16x32_bf16 v[112:115], v[212:215], v[162:165], v[112:115]
	v_mfma_f32_16x16x32_bf16 v[96:99], v[202:205], v[178:181], v[96:99]
	v_mfma_f32_16x16x32_bf16 v[88:91], v[212:215], v[178:181], v[88:91]
	v_mfma_f32_16x16x32_bf16 v[80:83], v[202:205], v[186:189], v[80:83]
	v_mfma_f32_16x16x32_bf16 v[72:75], v[212:215], v[186:189], v[72:75]
	v_mfma_f32_16x16x32_bf16 v[68:71], v[202:205], v[194:197], v[68:71]
	v_mfma_f32_16x16x32_bf16 v[64:67], v[212:215], v[194:197], v[64:67]
	v_mfma_f32_16x16x32_bf16 v[116:119], v[206:209], v[166:169], v[116:119]
	v_mfma_f32_16x16x32_bf16 v[112:115], v[216:219], v[166:169], v[112:115]
	v_mfma_f32_16x16x32_bf16 v[96:99], v[206:209], v[182:185], v[96:99]
	v_mfma_f32_16x16x32_bf16 v[88:91], v[216:219], v[182:185], v[88:91]
	v_mfma_f32_16x16x32_bf16 v[80:83], v[206:209], v[190:193], v[80:83]
	v_mfma_f32_16x16x32_bf16 v[72:75], v[216:219], v[190:193], v[72:75]
	v_mfma_f32_16x16x32_bf16 v[68:71], v[206:209], v[198:201], v[68:71]
	v_mfma_f32_16x16x32_bf16 v[64:67], v[216:219], v[198:201], v[64:67]
	s_barrier
	s_setprio 0
	s_mov_b32 m0, s48
	ds_read_b128 v[162:165], v174 offset:16384
	ds_read_b128 v[166:169], v174 offset:17408
	ds_read_b128 v[178:181], v174 offset:18432
	ds_read_b128 v[182:185], v174 offset:19456
	ds_read_b128 v[186:189], v174 offset:20480
	ds_read_b128 v[190:193], v174 offset:21504
	ds_read_b128 v[194:197], v174 offset:22528
	ds_read_b128 v[198:201], v174 offset:23552
	global_load_lds_dwordx4 v142, s[10:11]
	s_waitcnt vmcnt(9)
	s_waitcnt lgkmcnt(0)
	s_setprio 1
	s_barrier
	v_mfma_f32_16x16x32_bf16 v[60:63], v[128:131], v[162:165], v[60:63]
	v_mfma_f32_16x16x32_bf16 v[56:59], v[154:157], v[162:165], v[56:59]
	v_mfma_f32_16x16x32_bf16 v[52:55], v[128:131], v[178:181], v[52:55]
	v_mfma_f32_16x16x32_bf16 v[44:47], v[154:157], v[178:181], v[44:47]
	v_mfma_f32_16x16x32_bf16 v[36:39], v[128:131], v[186:189], v[36:39]
	v_mfma_f32_16x16x32_bf16 v[28:31], v[154:157], v[186:189], v[28:31]
	v_mfma_f32_16x16x32_bf16 v[20:23], v[128:131], v[194:197], v[20:23]
	v_mfma_f32_16x16x32_bf16 v[12:15], v[154:157], v[194:197], v[12:15]
	v_mfma_f32_16x16x32_bf16 v[60:63], v[132:135], v[166:169], v[60:63]
	v_mfma_f32_16x16x32_bf16 v[56:59], v[158:161], v[166:169], v[56:59]
	v_mfma_f32_16x16x32_bf16 v[52:55], v[132:135], v[182:185], v[52:55]
	v_mfma_f32_16x16x32_bf16 v[44:47], v[158:161], v[182:185], v[44:47]
	v_mfma_f32_16x16x32_bf16 v[36:39], v[132:135], v[190:193], v[36:39]
	v_mfma_f32_16x16x32_bf16 v[28:31], v[158:161], v[190:193], v[28:31]
	v_mfma_f32_16x16x32_bf16 v[20:23], v[132:135], v[198:201], v[20:23]
	v_mfma_f32_16x16x32_bf16 v[12:15], v[158:161], v[198:201], v[12:15]
	s_barrier
	s_setprio 0
	s_mov_b32 m0, s49
	s_nop 0
	global_load_lds_dwordx4 v138, s[10:11]
	s_add_u32 s54, s8, 0x80000
	s_addc_u32 s55, s9, 0
	s_add_i32 s53, s72, s41
	s_mov_b32 m0, s53
	s_nop 0
	global_load_lds_dwordx4 v140, s[54:55]
	s_add_i32 m0, s53, 0x2000
	s_nop 0
	global_load_lds_dwordx4 v136, s[54:55]
	s_add_i32 s53, 0, 0x18000
	v_add_u32_e32 v158, s53, v171
	ds_read_b128 v[128:131], v158
	ds_read_b128 v[132:135], v158 offset:1024
	ds_read_b128 v[154:157], v158 offset:2048
	ds_read_b128 v[158:161], v158 offset:3072
	s_waitcnt vmcnt(6)
	s_setprio 1
	s_barrier
; #define PG8_STAGE(bufoff, gbase, voff) do { _Pragma("unroll") for (int _i = 0; _i < 2; ++_i) \
;     __builtin_amdgcn_global_load_lds((const unsigned*)((const char*)(gbase) + (voff)[_i]), (LAS unsigned*)(lds + (bufoff) + ldsw + _i * 8192), 16, 0, 0); } while (0)
; #define PG8_LDA(dst, b, h) do { _Pragma("unroll") for (int m = 0; m < 4; ++m) _Pragma("unroll") for (int k = 0; k < 2; ++k) dst[m][k] = *(const LAS bf16x8*)(lds + PG8_SA(b, h) + aoff + m * 2048 + k * 1024); } while (0)
; #define PG8_LDB(dst, b, h) do { _Pragma("unroll") for (int n = 0; n < 2; ++n) _Pragma("unroll") for (int k = 0; k < 2; ++k) dst[n][k] = *(const LAS bf16x8*)(lds + PG8_SB(b, h) + boff + n * 2048 + k * 1024); } while (0)
; #define PG8_MMA(ai, bj, At, Bt) do { __builtin_amdgcn_s_setprio(1); _Pragma("unroll") for (int m = 0; m < 4; ++m) _Pragma("unroll") for (int n = 0; n < 2; ++n) _Pragma("unroll") for (int k = 0; k < 2; ++k) \
;     acc[ai][bj][m][n] = __builtin_amdgcn_mfma_f32_16x16x32_bf16(Bt[n][k], At[m][k], acc[ai][bj][m][n], 0, 0, 0); __builtin_amdgcn_s_setprio(0); } while (0)
; #define PG8_WAIT_V(n) asm volatile("s_waitcnt vmcnt(" #n ")" ::: "memory")
; #define PG8_WAIT_L(n) asm volatile("s_waitcnt lgkmcnt(" #n ")" ::: "memory")
; #define PG8_BAR __builtin_amdgcn_s_barrier()
; #define PG8_SCHED __builtin_amdgcn_sched_barrier(0)
; template <class Epi, class Sched = StaticOrder>
; DI void gemm_phase(LAS unsigned char* lds, const Gemm g, const Sched& S, const Epi& E) {
;     ...
;       PG8_WAIT_V(6); PG8_BAR; PG8_MMA(1, 1, At, B1); PG8_BAR;
;       PG8_LDB(B0, 1, 0); PG8_SCHED; PG8_LDA(At, 1, 0); PG8_STAGE(PG8_SA(0, 1), a2 + hstep, voffA);
;       PG8_WAIT_L(8); PG8_BAR; PG8_WAIT_L(0); PG8_MMA(0, 0, At, B0); PG8_BAR; PG8_SCHED;
;       PG8_LDB(B1, 1, 1); PG8_STAGE(PG8_SB(1, 0), b3, voffB);
;       PG8_BAR; PG8_WAIT_L(0); PG8_MMA(0, 1, At, B1); PG8_BAR;
;       PG8_LDA(At, 1, 1); PG8_STAGE(PG8_SA(1, 0), a3, voffA);
;       PG8_BAR; PG8_WAIT_L(0); PG8_MMA(1, 0, At, B0); PG8_BAR; PG8_SCHED;
;       PG8_STAGE(PG8_SB(1, 1), b3 + hstep, voffB);
;       PG8_WAIT_V(6); PG8_BAR; PG8_MMA(1, 1, At, B1); PG8_BAR;
	v_mfma_f32_16x16x32_bf16 v[48:51], v[202:205], v[162:165], v[48:51]
	v_mfma_f32_16x16x32_bf16 v[40:43], v[212:215], v[162:165], v[40:43]
	v_mfma_f32_16x16x32_bf16 v[32:35], v[202:205], v[178:181], v[32:35]
	v_mfma_f32_16x16x32_bf16 v[24:27], v[212:215], v[178:181], v[24:27]
	v_mfma_f32_16x16x32_bf16 v[16:19], v[202:205], v[186:189], v[16:19]
	v_mfma_f32_16x16x32_bf16 v[8:11], v[212:215], v[186:189], v[8:11]
	v_mfma_f32_16x16x32_bf16 v[4:7], v[202:205], v[194:197], v[4:7]
	v_mfma_f32_16x16x32_bf16 v[0:3], v[212:215], v[194:197], v[0:3]
	v_mfma_f32_16x16x32_bf16 v[48:51], v[206:209], v[166:169], v[48:51]
	v_mfma_f32_16x16x32_bf16 v[40:43], v[216:219], v[166:169], v[40:43]
	v_mfma_f32_16x16x32_bf16 v[32:35], v[206:209], v[182:185], v[32:35]
	v_mfma_f32_16x16x32_bf16 v[24:27], v[216:219], v[182:185], v[24:27]
	v_mfma_f32_16x16x32_bf16 v[16:19], v[206:209], v[190:193], v[16:19]
	v_mfma_f32_16x16x32_bf16 v[8:11], v[216:219], v[190:193], v[8:11]
	v_mfma_f32_16x16x32_bf16 v[4:7], v[206:209], v[198:201], v[4:7]
	v_mfma_f32_16x16x32_bf16 v[0:3], v[216:219], v[198:201], v[0:3]
	s_barrier
	s_setprio 0
	s_add_u32 s10, s10, 0x80000
	s_addc_u32 s11, s11, 0
	s_mov_b32 m0, s50
	ds_read_b128 v[162:165], v174 offset:32768
	ds_read_b128 v[166:169], v174 offset:33792
	ds_read_b128 v[178:181], v174 offset:34816
	ds_read_b128 v[182:185], v174 offset:35840
	ds_read_b128 v[186:189], v174 offset:36864
	ds_read_b128 v[190:193], v174 offset:37888
	ds_read_b128 v[194:197], v174 offset:38912
	ds_read_b128 v[198:201], v174 offset:39936
	global_load_lds_dwordx4 v142, s[10:11]
	s_waitcnt lgkmcnt(0)
	s_setprio 1
	s_barrier
	v_mfma_f32_16x16x32_bf16 v[124:127], v[128:131], v[162:165], v[124:127]
	v_mfma_f32_16x16x32_bf16 v[120:123], v[154:157], v[162:165], v[120:123]
	v_mfma_f32_16x16x32_bf16 v[108:111], v[128:131], v[178:181], v[108:111]
	v_mfma_f32_16x16x32_bf16 v[104:107], v[154:157], v[178:181], v[104:107]
	v_mfma_f32_16x16x32_bf16 v[100:103], v[128:131], v[186:189], v[100:103]
	v_mfma_f32_16x16x32_bf16 v[92:95], v[154:157], v[186:189], v[92:95]
	v_mfma_f32_16x16x32_bf16 v[84:87], v[128:131], v[194:197], v[84:87]
	v_mfma_f32_16x16x32_bf16 v[76:79], v[154:157], v[194:197], v[76:79]
	v_mfma_f32_16x16x32_bf16 v[124:127], v[132:135], v[166:169], v[124:127]
	v_mfma_f32_16x16x32_bf16 v[120:123], v[158:161], v[166:169], v[120:123]
	v_mfma_f32_16x16x32_bf16 v[108:111], v[132:135], v[182:185], v[108:111]
	v_mfma_f32_16x16x32_bf16 v[104:107], v[158:161], v[182:185], v[104:107]
	v_mfma_f32_16x16x32_bf16 v[100:103], v[132:135], v[190:193], v[100:103]
	v_mfma_f32_16x16x32_bf16 v[92:95], v[158:161], v[190:193], v[92:95]
	v_mfma_f32_16x16x32_bf16 v[84:87], v[132:135], v[198:201], v[84:87]
	v_mfma_f32_16x16x32_bf16 v[76:79], v[158:161], v[198:201], v[76:79]
	s_barrier
	s_setprio 0
	s_mov_b32 m0, s51
	s_nop 0
	global_load_lds_dwordx4 v138, s[10:11]
	s_add_i32 s10, 0, 0x1c000
	s_add_i32 s11, s53, s41
	v_add_u32_e32 v177, s10, v171
	s_mov_b32 m0, s11
	ds_read_b128 v[202:205], v177
	ds_read_b128 v[206:209], v177 offset:1024
	ds_read_b128 v[212:215], v177 offset:2048
	ds_read_b128 v[216:219], v177 offset:3072
	global_load_lds_dwordx4 v140, s[98:99]
	s_add_i32 m0, s11, 0x2000
	s_nop 0
	global_load_lds_dwordx4 v136, s[98:99]
	s_waitcnt lgkmcnt(0)
	s_setprio 1
	s_barrier
	v_mfma_f32_16x16x32_bf16 v[116:119], v[202:205], v[162:165], v[116:119]
	v_mfma_f32_16x16x32_bf16 v[112:115], v[212:215], v[162:165], v[112:115]
	v_mfma_f32_16x16x32_bf16 v[96:99], v[202:205], v[178:181], v[96:99]
	v_mfma_f32_16x16x32_bf16 v[88:91], v[212:215], v[178:181], v[88:91]
	v_mfma_f32_16x16x32_bf16 v[80:83], v[202:205], v[186:189], v[80:83]
	v_mfma_f32_16x16x32_bf16 v[72:75], v[212:215], v[186:189], v[72:75]
	v_mfma_f32_16x16x32_bf16 v[68:71], v[202:205], v[194:197], v[68:71]
	v_mfma_f32_16x16x32_bf16 v[64:67], v[212:215], v[194:197], v[64:67]
	v_mfma_f32_16x16x32_bf16 v[116:119], v[206:209], v[166:169], v[116:119]
	v_mfma_f32_16x16x32_bf16 v[112:115], v[216:219], v[166:169], v[112:115]
	v_mfma_f32_16x16x32_bf16 v[96:99], v[206:209], v[182:185], v[96:99]
	v_mfma_f32_16x16x32_bf16 v[88:91], v[216:219], v[182:185], v[88:91]
	v_mfma_f32_16x16x32_bf16 v[80:83], v[206:209], v[190:193], v[80:83]
	v_mfma_f32_16x16x32_bf16 v[72:75], v[216:219], v[190:193], v[72:75]
	v_mfma_f32_16x16x32_bf16 v[68:71], v[206:209], v[198:201], v[68:71]
	v_mfma_f32_16x16x32_bf16 v[64:67], v[216:219], v[198:201], v[64:67]
	s_barrier
	s_setprio 0
	s_mov_b32 m0, s56
	ds_read_b128 v[162:165], v174 offset:49152
	ds_read_b128 v[166:169], v174 offset:50176
	ds_read_b128 v[178:181], v174 offset:51200
	ds_read_b128 v[182:185], v174 offset:52224
	ds_read_b128 v[186:189], v174 offset:53248
	ds_read_b128 v[190:193], v174 offset:54272
	ds_read_b128 v[194:197], v174 offset:55296
	ds_read_b128 v[198:201], v174 offset:56320
	global_load_lds_dwordx4 v142, s[100:101]
	s_waitcnt vmcnt(9)
	s_waitcnt lgkmcnt(0)
	s_setprio 1
	s_barrier
	v_mfma_f32_16x16x32_bf16 v[60:63], v[128:131], v[162:165], v[60:63]
	v_mfma_f32_16x16x32_bf16 v[56:59], v[154:157], v[162:165], v[56:59]
	v_mfma_f32_16x16x32_bf16 v[52:55], v[128:131], v[178:181], v[52:55]
	v_mfma_f32_16x16x32_bf16 v[44:47], v[154:157], v[178:181], v[44:47]
	v_mfma_f32_16x16x32_bf16 v[36:39], v[128:131], v[186:189], v[36:39]
	v_mfma_f32_16x16x32_bf16 v[28:31], v[154:157], v[186:189], v[28:31]
	v_mfma_f32_16x16x32_bf16 v[20:23], v[128:131], v[194:197], v[20:23]
	v_mfma_f32_16x16x32_bf16 v[12:15], v[154:157], v[194:197], v[12:15]
	v_mfma_f32_16x16x32_bf16 v[60:63], v[132:135], v[166:169], v[60:63]
	v_mfma_f32_16x16x32_bf16 v[56:59], v[158:161], v[166:169], v[56:59]
	v_mfma_f32_16x16x32_bf16 v[52:55], v[132:135], v[182:185], v[52:55]
	v_mfma_f32_16x16x32_bf16 v[44:47], v[158:161], v[182:185], v[44:47]
	v_mfma_f32_16x16x32_bf16 v[36:39], v[132:135], v[190:193], v[36:39]
	v_mfma_f32_16x16x32_bf16 v[28:31], v[158:161], v[190:193], v[28:31]
	v_mfma_f32_16x16x32_bf16 v[20:23], v[132:135], v[198:201], v[20:23]
	v_mfma_f32_16x16x32_bf16 v[12:15], v[158:161], v[198:201], v[12:15]
	s_barrier
; #define PG8_STAGE(bufoff, gbase, voff) do { _Pragma("unroll") for (int _i = 0; _i < 2; ++_i) \
;     __builtin_amdgcn_global_load_lds((const unsigned*)((const char*)(gbase) + (voff)[_i]), (LAS unsigned*)(lds + (bufoff) + ldsw + _i * 8192), 16, 0, 0); } while (0)
; #define PG8_MMA(ai, bj, At, Bt) do { __builtin_amdgcn_s_setprio(1); _Pragma("unroll") for (int m = 0; m < 4; ++m) _Pragma("unroll") for (int n = 0; n < 2; ++n) _Pragma("unroll") for (int k = 0; k < 2; ++k) \
;     acc[ai][bj][m][n] = __builtin_amdgcn_mfma_f32_16x16x32_bf16(Bt[n][k], At[m][k], acc[ai][bj][m][n], 0, 0, 0); __builtin_amdgcn_s_setprio(0); } while (0)
; #define PG8_WAIT_V(n) asm volatile("s_waitcnt vmcnt(" #n ")" ::: "memory")
; #define PG8_BAR __builtin_amdgcn_s_barrier()
; DI float row_rstd(const float* ssq, int row, int fq) {
;   const f32x4 a = *(const f32x4*)(ssq + (size_t)row * 32 + fq * 8), b = *(const f32x4*)(ssq + (size_t)row * 32 + fq * 8 + 4);
;   float sm = ((a[0] + a[1]) + (a[2] + a[3])) + ((b[0] + b[1]) + (b[2] + b[3]));
;   sm += __shfl_xor(sm, 16); sm += __shfl_xor(sm, 32);
;   return rsqrtf(sm * (1.0f / 2048.f) + 1e-6f);
; }
;   DI void operator()(const f32x4 (&acc)[2][2][4][2], const Unit& u, int wr, int wc, int fr, int fq) const {
;     const int row0 = u.pm * BM + wr * 64 + fr, col0 = u.pn * BM + wc * 32 + 8 * fq;
;     float rsv[2][4];
; #pragma unroll
;     for (int ai = 0; ai < 2; ++ai)
; #pragma unroll
;       for (int m = 0; m < 4; ++m) rsv[ai][m] = row_rstd(ssq, row0 + ai * HALF + m * 16, fq);
; template <class Epi, class Sched = StaticOrder>
; DI void gemm_phase(LAS unsigned char* lds, const Gemm g, const Sched& S, const Epi& E) {
;     ...
;       PG8_STAGE(PG8_SB(1, 1), b3 + hstep, voffB);
;       PG8_WAIT_V(6); PG8_BAR; PG8_MMA(1, 1, At, B1); PG8_BAR;
;     }
;     E(acc, cur, wr, wc, fr, fq);
	s_setprio 0
	s_mov_b32 m0, s57
	s_nop 0
	global_load_lds_dwordx4 v138, s[100:101]
	s_add_u32 s8, s8, 0x80080
	s_addc_u32 s9, s9, 0
	s_add_i32 s10, s10, s41
	s_mov_b32 m0, s10
	s_nop 0
	global_load_lds_dwordx4 v140, s[8:9]
	s_add_i32 m0, s10, 0x2000
	s_nop 0
	global_load_lds_dwordx4 v136, s[8:9]
	ds_read_b128 v[128:131], v173
	ds_read_b128 v[132:135], v173 offset:1024
	ds_read_b128 v[154:157], v173 offset:2048
	ds_read_b128 v[158:161], v173 offset:3072
	s_waitcnt vmcnt(6)
	s_setprio 1
	s_barrier
	v_mfma_f32_16x16x32_bf16 v[48:51], v[202:205], v[162:165], v[48:51]
	v_mfma_f32_16x16x32_bf16 v[40:43], v[212:215], v[162:165], v[40:43]
	v_mfma_f32_16x16x32_bf16 v[32:35], v[202:205], v[178:181], v[32:35]
	v_mfma_f32_16x16x32_bf16 v[24:27], v[212:215], v[178:181], v[24:27]
	v_mfma_f32_16x16x32_bf16 v[16:19], v[202:205], v[186:189], v[16:19]
	v_mfma_f32_16x16x32_bf16 v[8:11], v[212:215], v[186:189], v[8:11]
	v_mfma_f32_16x16x32_bf16 v[4:7], v[202:205], v[194:197], v[4:7]
	v_mfma_f32_16x16x32_bf16 v[0:3], v[212:215], v[194:197], v[0:3]
	v_mfma_f32_16x16x32_bf16 v[48:51], v[206:209], v[166:169], v[48:51]
	v_mfma_f32_16x16x32_bf16 v[40:43], v[216:219], v[166:169], v[40:43]
	v_mfma_f32_16x16x32_bf16 v[32:35], v[206:209], v[182:185], v[32:35]
	v_mfma_f32_16x16x32_bf16 v[24:27], v[216:219], v[182:185], v[24:27]
	v_mfma_f32_16x16x32_bf16 v[16:19], v[206:209], v[190:193], v[16:19]
	v_mfma_f32_16x16x32_bf16 v[8:11], v[216:219], v[190:193], v[8:11]
	v_mfma_f32_16x16x32_bf16 v[4:7], v[206:209], v[198:201], v[4:7]
	v_mfma_f32_16x16x32_bf16 v[0:3], v[216:219], v[198:201], v[0:3]
	s_add_i32 s52, s52, 2
	s_add_u32 s6, s6, 0x100
	s_addc_u32 s7, s7, 0
	s_add_u32 s44, s44, 0x100
	s_addc_u32 s45, s45, 0
	s_cmp_gt_u32 s52, 29
	s_barrier
	s_setprio 0
	s_cbranch_scc0 .LBB0_346
	s_waitcnt lgkmcnt(0)
	v_lshl_add_u32 v168, s4, 8, v170
	v_ashrrev_i32_e32 v169, 31, v168
	v_or_b32_e32 v154, 16, v168
	v_lshlrev_b64 v[128:129], 7, v[168:169]
	v_ashrrev_i32_e32 v155, 31, v154
	v_lshl_add_u64 v[128:129], v[144:145], 0, v[128:129]
	v_lshlrev_b64 v[156:157], 7, v[154:155]
	global_load_dwordx4 v[132:135], v[128:129], off
	s_nop 0
	global_load_dwordx4 v[128:131], v[128:129], off offset:16
	v_lshl_add_u64 v[156:157], v[144:145], 0, v[156:157]
	global_load_dwordx4 v[178:181], v[156:157], off
	global_load_dwordx4 v[182:185], v[156:157], off offset:16
	v_or_b32_e32 v160, 32, v168
	v_ashrrev_i32_e32 v161, 31, v160
	v_lshlrev_b64 v[156:157], 7, v[160:161]
	v_lshl_add_u64 v[156:157], v[144:145], 0, v[156:157]
	global_load_dwordx4 v[186:189], v[156:157], off
	global_load_dwordx4 v[190:193], v[156:157], off offset:16
	v_or_b32_e32 v156, 48, v168
	v_ashrrev_i32_e32 v157, 31, v156
	v_lshlrev_b64 v[158:159], 7, v[156:157]
	v_lshl_add_u64 v[158:159], v[144:145], 0, v[158:159]
	global_load_dwordx4 v[194:197], v[158:159], off
	global_load_dwordx4 v[198:201], v[158:159], off offset:16
	v_add_u32_e32 v164, 0x80, v168
	v_ashrrev_i32_e32 v165, 31, v164
	v_lshlrev_b64 v[158:159], 7, v[164:165]
	v_lshl_add_u64 v[158:159], v[144:145], 0, v[158:159]
	global_load_dwordx4 v[202:205], v[158:159], off
	global_load_dwordx4 v[206:209], v[158:159], off offset:16
	v_add_u32_e32 v158, 0x90, v168
	v_ashrrev_i32_e32 v159, 31, v158
	v_lshlrev_b64 v[162:163], 7, v[158:159]
	v_lshl_add_u64 v[162:163], v[144:145], 0, v[162:163]
	global_load_dwordx4 v[212:215], v[162:163], off
	global_load_dwordx4 v[216:219], v[162:163], off offset:16
	v_add_u32_e32 v166, 0xa0, v168
	v_ashrrev_i32_e32 v167, 31, v166
	v_lshlrev_b64 v[162:163], 7, v[166:167]
	v_lshl_add_u64 v[162:163], v[144:145], 0, v[162:163]
	global_load_dwordx4 v[220:223], v[162:163], off
	global_load_dwordx4 v[224:227], v[162:163], off offset:16
	v_add_u32_e32 v162, 0xb0, v168
	v_ashrrev_i32_e32 v163, 31, v162
	v_lshlrev_b64 v[228:229], 7, v[162:163]
	v_lshl_add_u64 v[232:233], v[144:145], 0, v[228:229]
	global_load_dwordx4 v[228:231], v[232:233], off
	s_nop 0
	global_load_dwordx4 v[232:235], v[232:233], off offset:16
	s_waitcnt vmcnt(0)
	v_mov_b32_e32 v236, v132
	v_mov_b32_e32 v237, v128
	v_mov_b32_e32 v128, v133
	v_mov_b32_e32 v132, v134
	v_mov_b32_e32 v133, v130
	v_mov_b32_e32 v130, v135
	v_pk_add_f32 v[130:131], v[132:133], v[130:131]
	v_mov_b32_e32 v132, v178
	v_mov_b32_e32 v133, v182
	v_mov_b32_e32 v182, v179
	v_mov_b32_e32 v134, v180
	v_mov_b32_e32 v135, v184
	v_mov_b32_e32 v184, v181
	v_pk_add_f32 v[128:129], v[236:237], v[128:129]
	v_pk_add_f32 v[132:133], v[132:133], v[182:183]
	v_pk_add_f32 v[134:135], v[134:135], v[184:185]
	v_pk_add_f32 v[128:129], v[128:129], v[130:131]
	v_pk_add_f32 v[130:131], v[132:133], v[134:135]
	v_mov_b32_e32 v133, v128
	v_mov_b32_e32 v132, v130
	v_and_b32_e32 v130, 64, v176
	v_add_u32_e32 v155, 64, v130
	v_xor_b32_e32 v130, 16, v176
	v_cmp_lt_i32_e32 vcc, v130, v155
	v_mov_b32_e32 v128, v131
	v_pk_add_f32 v[128:129], v[132:133], v[128:129]
	v_cndmask_b32_e32 v130, v176, v130, vcc
	v_lshlrev_b32_e32 v157, 2, v130
	ds_bpermute_b32 v131, v157, v129
	ds_bpermute_b32 v130, v157, v128
	v_mov_b32_e32 v178, v186
	v_mov_b32_e32 v179, v190
	v_mov_b32_e32 v190, v187
	v_mov_b32_e32 v186, v194
	s_waitcnt lgkmcnt(0)
	v_pk_add_f32 v[128:129], v[128:129], v[130:131]
	v_xor_b32_e32 v130, 32, v176
	v_cmp_lt_i32_e32 vcc, v130, v155
	v_mov_b32_e32 v187, v198
	v_mov_b32_e32 v198, v195
	v_cndmask_b32_e32 v130, v176, v130, vcc
	v_lshlrev_b32_e32 v155, 2, v130
	ds_bpermute_b32 v131, v155, v129
	ds_bpermute_b32 v130, v155, v128
	v_pk_add_f32 v[182:183], v[186:187], v[198:199]
	v_mov_b32_e32 v180, v188
	v_mov_b32_e32 v181, v192
	v_mov_b32_e32 v192, v189
	s_waitcnt lgkmcnt(0)
; DI unsigned pack2(float lo, float hi) { f32x2 v = {lo, hi}; bf16v2 r = __builtin_convertvector(v, bf16v2); return __builtin_bit_cast(unsigned, r); }
; DI float row_rstd(const float* ssq, int row, int fq) {
;   const f32x4 a = *(const f32x4*)(ssq + (size_t)row * 32 + fq * 8), b = *(const f32x4*)(ssq + (size_t)row * 32 + fq * 8 + 4);
;   float sm = ((a[0] + a[1]) + (a[2] + a[3])) + ((b[0] + b[1]) + (b[2] + b[3]));
;   sm += __shfl_xor(sm, 16); sm += __shfl_xor(sm, 32);
;   return rsqrtf(sm * (1.0f / 2048.f) + 1e-6f);
; }
;   DI void operator()(const f32x4 (&acc)[2][2][4][2], const Unit& u, int wr, int wc, int fr, int fq) const {
;     ...
;       for (int m = 0; m < 4; ++m) rsv[ai][m] = row_rstd(ssq, row0 + ai * HALF + m * 16, fq);
; #pragma unroll
;     for (int ai = 0; ai < 2; ++ai)
; #pragma unroll
;       for (int m = 0; m < 4; ++m) {
;         const int row = row0 + ai * HALF + m * 16;
;         const float rs = rsv[ai][m];
;         bf16_t* rowp = O + (size_t)row * ldc + col0;
; #pragma unroll
;         for (int bj = 0; bj < 2; ++bj) {
;           const f32x4 v0 = acc[ai][bj][m][0] * rs, v1 = acc[ai][bj][m][1] * rs;
;           u32x4 w; w.x = pack2(v0[0], v0[1]); w.y = pack2(v0[2], v0[3]); w.z = pack2(v1[0], v1[1]); w.w = pack2(v1[2], v1[3]);
;           *(u32x4*)(rowp + bj * HALF) = w;
;         }
;       }
	v_pk_add_f32 v[128:129], v[128:129], v[130:131]
	v_mov_b64_e32 v[130:131], s[26:27]
	v_pk_fma_f32 v[128:129], v[128:129], s[24:25], v[130:131] op_sel_hi:[1,0,0]
	v_mov_b32_e32 v188, v196
	v_mul_f32_e32 v159, 0x4b800000, v129
	v_cmp_gt_f32_e32 vcc, s73, v129
	v_mov_b32_e32 v189, v200
	v_mov_b32_e32 v200, v197
	v_cndmask_b32_e32 v129, v129, v159, vcc
	v_rsq_f32_e32 v129, v129
	v_pk_add_f32 v[178:179], v[178:179], v[190:191]
	v_pk_add_f32 v[180:181], v[180:181], v[192:193]
	v_pk_add_f32 v[184:185], v[188:189], v[200:201]
	v_mul_f32_e32 v159, 0x45800000, v129
	v_cndmask_b32_e32 v198, v129, v159, vcc
	v_pk_mul_f32 v[126:127], v[126:127], v[198:199] op_sel_hi:[1,0]
	v_pk_mul_f32 v[124:125], v[124:125], v[198:199] op_sel_hi:[1,0]
	v_pk_mul_f32 v[122:123], v[122:123], v[198:199] op_sel_hi:[1,0]
	v_pk_mul_f32 v[120:121], v[120:121], v[198:199] op_sel_hi:[1,0]
	v_cvt_pk_bf16_f32 v124, v124, v125
	v_cvt_pk_bf16_f32 v125, v126, v127
	v_cvt_pk_bf16_f32 v127, v122, v123
	v_lshl_or_b32 v122, s5, 8, v172
	v_cvt_pk_bf16_f32 v126, v120, v121
	v_ashrrev_i32_e32 v123, 31, v122
	v_mov_b64_e32 v[120:121], s[2:3]
	v_mad_i64_i32 v[168:169], s[4:5], v168, s76, v[120:121]
	v_lshlrev_b64 v[122:123], 1, v[122:123]
	v_lshl_add_u64 v[168:169], v[168:169], 0, v[122:123]
	global_store_dwordx4 v[168:169], v[124:127], off
	v_mov_b32_e32 v194, v202
	v_mov_b32_e32 v195, v206
	v_pk_add_f32 v[124:125], v[178:179], v[180:181]
	v_pk_add_f32 v[126:127], v[182:183], v[184:185]
	v_mov_b32_e32 v179, v124
	v_mov_b32_e32 v178, v126
	v_mov_b32_e32 v124, v127
	v_pk_add_f32 v[124:125], v[178:179], v[124:125]
	ds_bpermute_b32 v127, v157, v125
	ds_bpermute_b32 v126, v157, v124
	v_mov_b32_e32 v206, v203
	v_mov_b32_e32 v196, v204
	v_mov_b32_e32 v197, v208
	v_mov_b32_e32 v208, v205
	v_mov_b32_e32 v202, v212
	v_mov_b32_e32 v203, v216
	v_mov_b32_e32 v216, v213
	v_mov_b32_e32 v204, v214
	v_mov_b32_e32 v205, v218
	v_mov_b32_e32 v218, v215
	v_pk_add_f32 v[186:187], v[194:195], v[206:207]
	v_pk_add_f32 v[188:189], v[196:197], v[208:209]
	v_pk_add_f32 v[190:191], v[202:203], v[216:217]
	v_pk_add_f32 v[192:193], v[204:205], v[218:219]
	v_pk_mul_f32 v[178:179], v[114:115], v[198:199] op_sel_hi:[1,0]
	s_waitcnt lgkmcnt(0)
	v_pk_add_f32 v[114:115], v[124:125], v[126:127]
	v_pk_add_f32 v[126:127], v[186:187], v[188:189]
	v_pk_add_f32 v[180:181], v[190:191], v[192:193]
	v_mov_b32_e32 v183, v126
	v_mov_b32_e32 v182, v180
	v_mov_b32_e32 v126, v181
	v_pk_add_f32 v[126:127], v[182:183], v[126:127]
	ds_bpermute_b32 v125, v155, v115
	ds_bpermute_b32 v124, v155, v114
	ds_bpermute_b32 v181, v157, v127
	ds_bpermute_b32 v180, v157, v126
	v_mul_f32_e32 v129, 0x4b800000, v128
	v_cmp_gt_f32_e32 vcc, s73, v128
	s_waitcnt lgkmcnt(2)
	v_pk_add_f32 v[114:115], v[114:115], v[124:125]
	v_mov_b32_e32 v194, v220
	s_waitcnt lgkmcnt(0)
	v_pk_add_f32 v[124:125], v[126:127], v[180:181]
	ds_bpermute_b32 v127, v155, v125
	ds_bpermute_b32 v126, v155, v124
	v_pk_fma_f32 v[114:115], v[114:115], s[24:25], v[130:131] op_sel_hi:[1,0,0]
	v_cndmask_b32_e32 v159, v128, v129, vcc
	v_mul_f32_e32 v128, 0x4b800000, v115
	v_cmp_gt_f32_e64 s[4:5], s73, v115
	v_cmp_gt_f32_e64 s[6:7], s73, v114
	v_mov_b32_e32 v195, v224
	v_cndmask_b32_e64 v161, v115, v128, s[4:5]
	v_mul_f32_e32 v115, 0x4b800000, v114
	v_mov_b32_e32 v224, v221
	v_mov_b32_e32 v196, v222
	v_mov_b32_e32 v197, v226
	v_mov_b32_e32 v226, v223
	v_cndmask_b32_e64 v163, v114, v115, s[6:7]
	s_waitcnt lgkmcnt(0)
	v_pk_add_f32 v[114:115], v[124:125], v[126:127]
	v_pk_add_f32 v[132:133], v[194:195], v[224:225]
	v_pk_add_f32 v[134:135], v[196:197], v[226:227]
	v_mov_b32_e32 v194, v228
	v_mov_b32_e32 v195, v232
	v_mov_b32_e32 v232, v229
	v_mov_b32_e32 v196, v230
	v_mov_b32_e32 v197, v234
	v_mov_b32_e32 v234, v231
	v_pk_fma_f32 v[114:115], v[114:115], s[24:25], v[130:131] op_sel_hi:[1,0,0]
	v_pk_add_f32 v[194:195], v[194:195], v[232:233]
	v_pk_add_f32 v[196:197], v[196:197], v[234:235]
	v_mul_f32_e32 v124, 0x4b800000, v115
	v_cmp_gt_f32_e64 s[8:9], s73, v115
	v_pk_add_f32 v[126:127], v[194:195], v[196:197]
	v_cmp_gt_f32_e64 s[10:11], s73, v114
	v_cndmask_b32_e64 v165, v115, v124, s[8:9]
	v_pk_add_f32 v[124:125], v[132:133], v[134:135]
	v_mov_b32_e32 v128, v126
	v_mov_b32_e32 v129, v124
	v_mov_b32_e32 v124, v127
	v_pk_add_f32 v[124:125], v[128:129], v[124:125]
	ds_bpermute_b32 v127, v157, v125
	ds_bpermute_b32 v126, v157, v124
	v_rsq_f32_e32 v128, v159
	v_mul_f32_e32 v115, 0x4b800000, v114
	v_cndmask_b32_e64 v129, v114, v115, s[10:11]
	v_pk_mul_f32 v[116:117], v[116:117], v[198:199] op_sel_hi:[1,0]
	s_waitcnt lgkmcnt(0)
	v_pk_add_f32 v[114:115], v[124:125], v[126:127]
	ds_bpermute_b32 v125, v155, v115
	ds_bpermute_b32 v124, v155, v114
	v_mul_f32_e32 v126, 0x45800000, v128
	v_rsq_f32_e32 v127, v161
	v_cndmask_b32_e32 v126, v128, v126, vcc
	v_rsq_f32_e32 v128, v163
	s_waitcnt lgkmcnt(0)
; DI unsigned pack2(float lo, float hi) { f32x2 v = {lo, hi}; bf16v2 r = __builtin_convertvector(v, bf16v2); return __builtin_bit_cast(unsigned, r); }
;   DI void operator()(const f32x4 (&acc)[2][2][4][2], const Unit& u, int wr, int wc, int fr, int fq) const {
;     ...
;     for (int ai = 0; ai < 2; ++ai)
; #pragma unroll
;       for (int m = 0; m < 4; ++m) {
;         const int row = row0 + ai * HALF + m * 16;
;         const float rs = rsv[ai][m];
;         bf16_t* rowp = O + (size_t)row * ldc + col0;
; #pragma unroll
;         for (int bj = 0; bj < 2; ++bj) {
;           const f32x4 v0 = acc[ai][bj][m][0] * rs, v1 = acc[ai][bj][m][1] * rs;
;           u32x4 w; w.x = pack2(v0[0], v0[1]); w.y = pack2(v0[2], v0[3]); w.z = pack2(v1[0], v1[1]); w.w = pack2(v1[2], v1[3]);
;           *(u32x4*)(rowp + bj * HALF) = w;
;         }
;       }
	v_pk_add_f32 v[114:115], v[114:115], v[124:125]
	v_mul_f32_e32 v124, 0x45800000, v127
	v_cndmask_b32_e64 v124, v127, v124, s[4:5]
	v_mul_f32_e32 v127, 0x45800000, v128
	v_pk_fma_f32 v[114:115], v[114:115], s[24:25], v[130:131] op_sel_hi:[1,0,0]
	v_rsq_f32_e32 v125, v165
	v_cndmask_b32_e64 v128, v128, v127, s[6:7]
	v_rsq_f32_e32 v127, v129
	v_mul_f32_e32 v129, 0x4b800000, v115
	v_cmp_gt_f32_e32 vcc, s73, v115
	v_cmp_gt_f32_e64 s[4:5], s73, v114
	v_pk_mul_f32 v[118:119], v[118:119], v[198:199] op_sel_hi:[1,0]
	v_cndmask_b32_e32 v129, v115, v129, vcc
	v_mul_f32_e32 v115, 0x4b800000, v114
	v_cndmask_b32_e64 v131, v114, v115, s[4:5]
	v_cvt_pk_bf16_f32 v114, v116, v117
	v_rsq_f32_e32 v117, v129
	v_cvt_pk_bf16_f32 v115, v118, v119
	v_rsq_f32_e32 v119, v131
	v_mul_f32_e32 v116, 0x45800000, v125
	v_pk_mul_f32 v[112:113], v[112:113], v[198:199] op_sel_hi:[1,0]
	v_cndmask_b32_e64 v118, v125, v116, s[8:9]
	v_mul_f32_e32 v116, 0x45800000, v127
	v_cndmask_b32_e64 v130, v127, v116, s[10:11]
	v_cvt_pk_bf16_f32 v116, v112, v113
	v_mul_f32_e32 v112, 0x45800000, v117
	v_cndmask_b32_e32 v132, v117, v112, vcc
	v_mul_f32_e32 v112, 0x45800000, v119
	v_cvt_pk_bf16_f32 v117, v178, v179
	v_cndmask_b32_e64 v112, v119, v112, s[4:5]
	global_store_dwordx4 v[168:169], v[114:117], off offset:256
	v_pk_mul_f32 v[110:111], v[110:111], v[126:127] op_sel_hi:[1,0]
	v_pk_mul_f32 v[108:109], v[108:109], v[126:127] op_sel_hi:[1,0]
	v_mad_i64_i32 v[114:115], s[4:5], v154, s76, v[120:121]
	v_pk_mul_f32 v[116:117], v[106:107], v[126:127] op_sel_hi:[1,0]
	v_pk_mul_f32 v[106:107], v[104:105], v[126:127] op_sel_hi:[1,0]
	v_lshl_add_u64 v[114:115], v[114:115], 0, v[122:123]
	v_cvt_pk_bf16_f32 v104, v108, v109
	v_cvt_pk_bf16_f32 v105, v110, v111
	v_cvt_pk_bf16_f32 v106, v106, v107
	v_cvt_pk_bf16_f32 v107, v116, v117
	global_store_dwordx4 v[114:115], v[104:107], off
	v_pk_mul_f32 v[98:99], v[98:99], v[126:127] op_sel_hi:[1,0]
	v_pk_mul_f32 v[96:97], v[96:97], v[126:127] op_sel_hi:[1,0]
	v_pk_mul_f32 v[104:105], v[90:91], v[126:127] op_sel_hi:[1,0]
	v_pk_mul_f32 v[90:91], v[88:89], v[126:127] op_sel_hi:[1,0]
	v_cvt_pk_bf16_f32 v88, v96, v97
	v_cvt_pk_bf16_f32 v89, v98, v99
	v_cvt_pk_bf16_f32 v90, v90, v91
	v_cvt_pk_bf16_f32 v91, v104, v105
	global_store_dwordx4 v[114:115], v[88:91], off offset:256
	v_pk_mul_f32 v[94:95], v[94:95], v[124:125] op_sel_hi:[1,0]
	v_pk_mul_f32 v[92:93], v[92:93], v[124:125] op_sel_hi:[1,0]
	v_mad_i64_i32 v[88:89], s[4:5], v160, s76, v[120:121]
	v_lshl_add_u64 v[96:97], v[88:89], 0, v[122:123]
	v_pk_mul_f32 v[90:91], v[102:103], v[124:125] op_sel_hi:[1,0]
	v_pk_mul_f32 v[88:89], v[100:101], v[124:125] op_sel_hi:[1,0]
	v_pk_mul_f32 v[82:83], v[82:83], v[124:125] op_sel_hi:[1,0]
	v_cvt_pk_bf16_f32 v88, v88, v89
	v_cvt_pk_bf16_f32 v89, v90, v91
	v_cvt_pk_bf16_f32 v90, v92, v93
	v_cvt_pk_bf16_f32 v91, v94, v95
	global_store_dwordx4 v[96:97], v[88:91], off
	v_pk_mul_f32 v[80:81], v[80:81], v[124:125] op_sel_hi:[1,0]
	v_pk_mul_f32 v[78:79], v[78:79], v[128:129] op_sel_hi:[1,0]
	v_pk_mul_f32 v[88:89], v[74:75], v[124:125] op_sel_hi:[1,0]
	v_pk_mul_f32 v[74:75], v[72:73], v[124:125] op_sel_hi:[1,0]
	v_cvt_pk_bf16_f32 v72, v80, v81
	v_cvt_pk_bf16_f32 v73, v82, v83
	v_cvt_pk_bf16_f32 v74, v74, v75
	v_cvt_pk_bf16_f32 v75, v88, v89
	global_store_dwordx4 v[96:97], v[72:75], off offset:256
	v_pk_mul_f32 v[76:77], v[76:77], v[128:129] op_sel_hi:[1,0]
	v_pk_mul_f32 v[70:71], v[70:71], v[128:129] op_sel_hi:[1,0]
	v_mad_i64_i32 v[72:73], s[4:5], v156, s76, v[120:121]
	v_lshl_add_u64 v[80:81], v[72:73], 0, v[122:123]
	v_pk_mul_f32 v[74:75], v[86:87], v[128:129] op_sel_hi:[1,0]
	v_pk_mul_f32 v[72:73], v[84:85], v[128:129] op_sel_hi:[1,0]
	v_pk_mul_f32 v[68:69], v[68:69], v[128:129] op_sel_hi:[1,0]
	v_cvt_pk_bf16_f32 v72, v72, v73
	v_cvt_pk_bf16_f32 v73, v74, v75
	v_cvt_pk_bf16_f32 v74, v76, v77
	v_cvt_pk_bf16_f32 v75, v78, v79
	global_store_dwordx4 v[80:81], v[72:75], off
	v_pk_mul_f32 v[62:63], v[62:63], v[118:119] op_sel_hi:[1,0]
	v_pk_mul_f32 v[60:61], v[60:61], v[118:119] op_sel_hi:[1,0]
	v_pk_mul_f32 v[72:73], v[66:67], v[128:129] op_sel_hi:[1,0]
	v_pk_mul_f32 v[66:67], v[64:65], v[128:129] op_sel_hi:[1,0]
; DI unsigned pack2(float lo, float hi) { f32x2 v = {lo, hi}; bf16v2 r = __builtin_convertvector(v, bf16v2); return __builtin_bit_cast(unsigned, r); }
; #define PG8_WAIT_V(n) asm volatile("s_waitcnt vmcnt(" #n ")" ::: "memory")
; #define PG8_BAR __builtin_amdgcn_s_barrier()
;   DI void operator()(const f32x4 (&acc)[2][2][4][2], const Unit& u, int wr, int wc, int fr, int fq) const {
;     ...
;     for (int ai = 0; ai < 2; ++ai)
; #pragma unroll
;       for (int m = 0; m < 4; ++m) {
;         const int row = row0 + ai * HALF + m * 16;
;         const float rs = rsv[ai][m];
;         bf16_t* rowp = O + (size_t)row * ldc + col0;
; #pragma unroll
;         for (int bj = 0; bj < 2; ++bj) {
;           const f32x4 v0 = acc[ai][bj][m][0] * rs, v1 = acc[ai][bj][m][1] * rs;
;           u32x4 w; w.x = pack2(v0[0], v0[1]); w.y = pack2(v0[2], v0[3]); w.z = pack2(v1[0], v1[1]); w.w = pack2(v1[2], v1[3]);
;           *(u32x4*)(rowp + bj * HALF) = w;
;         }
;       }
; template <class Epi, class Sched = StaticOrder>
; DI void gemm_phase(LAS unsigned char* lds, const Gemm g, const Sched& S, const Epi& E) {
;     ...
;     E(acc, cur, wr, wc, fr, fq);
;     if (!has_next) break;
; #pragma unroll
;     for (int a = 0; a < 2; ++a)
; #pragma unroll
;       for (int b = 0; b < 2; ++b)
; #pragma unroll
;         for (int m = 0; m < 4; ++m)
; #pragma unroll
;           for (int n = 0; n < 2; ++n) acc[a][b][m][n] = (f32x4){0.f, 0.f, 0.f, 0.f};
;     cur = nxt; cA = nA; cB = nB; ++ui;
;   }
;   PG8_WAIT_V(0);
;   if (wr == 0) PG8_BAR;
;   PG8_BAR;
	v_cvt_pk_bf16_f32 v64, v68, v69
	v_cvt_pk_bf16_f32 v65, v70, v71
	v_cvt_pk_bf16_f32 v66, v66, v67
	v_cvt_pk_bf16_f32 v67, v72, v73
	global_store_dwordx4 v[80:81], v[64:67], off offset:256
	v_pk_mul_f32 v[50:51], v[50:51], v[118:119] op_sel_hi:[1,0]
	v_pk_mul_f32 v[48:49], v[48:49], v[118:119] op_sel_hi:[1,0]
	v_mad_i64_i32 v[64:65], s[4:5], v164, s76, v[120:121]
	v_pk_mul_f32 v[66:67], v[58:59], v[118:119] op_sel_hi:[1,0]
	v_pk_mul_f32 v[58:59], v[56:57], v[118:119] op_sel_hi:[1,0]
	v_lshl_add_u64 v[64:65], v[64:65], 0, v[122:123]
	v_cvt_pk_bf16_f32 v56, v60, v61
	v_cvt_pk_bf16_f32 v57, v62, v63
	v_cvt_pk_bf16_f32 v58, v58, v59
	v_cvt_pk_bf16_f32 v59, v66, v67
	global_store_dwordx4 v[64:65], v[56:59], off
	v_pk_mul_f32 v[46:47], v[46:47], v[130:131] op_sel_hi:[1,0]
	v_pk_mul_f32 v[44:45], v[44:45], v[130:131] op_sel_hi:[1,0]
	v_pk_mul_f32 v[56:57], v[42:43], v[118:119] op_sel_hi:[1,0]
	v_pk_mul_f32 v[42:43], v[40:41], v[118:119] op_sel_hi:[1,0]
	v_cvt_pk_bf16_f32 v40, v48, v49
	v_cvt_pk_bf16_f32 v41, v50, v51
	v_cvt_pk_bf16_f32 v42, v42, v43
	v_cvt_pk_bf16_f32 v43, v56, v57
	global_store_dwordx4 v[64:65], v[40:43], off offset:256
	v_pk_mul_f32 v[34:35], v[34:35], v[130:131] op_sel_hi:[1,0]
	v_pk_mul_f32 v[32:33], v[32:33], v[130:131] op_sel_hi:[1,0]
	v_mad_i64_i32 v[40:41], s[4:5], v158, s76, v[120:121]
	v_lshl_add_u64 v[48:49], v[40:41], 0, v[122:123]
	v_pk_mul_f32 v[42:43], v[54:55], v[130:131] op_sel_hi:[1,0]
	v_pk_mul_f32 v[40:41], v[52:53], v[130:131] op_sel_hi:[1,0]
	v_pk_mul_f32 v[30:31], v[30:31], v[132:133] op_sel_hi:[1,0]
	v_cvt_pk_bf16_f32 v40, v40, v41
	v_cvt_pk_bf16_f32 v41, v42, v43
	v_cvt_pk_bf16_f32 v42, v44, v45
	v_cvt_pk_bf16_f32 v43, v46, v47
	global_store_dwordx4 v[48:49], v[40:43], off
	v_pk_mul_f32 v[28:29], v[28:29], v[132:133] op_sel_hi:[1,0]
	v_pk_mul_f32 v[18:19], v[18:19], v[132:133] op_sel_hi:[1,0]
	v_pk_mul_f32 v[40:41], v[26:27], v[130:131] op_sel_hi:[1,0]
	v_pk_mul_f32 v[26:27], v[24:25], v[130:131] op_sel_hi:[1,0]
	v_cvt_pk_bf16_f32 v24, v32, v33
	v_cvt_pk_bf16_f32 v25, v34, v35
	v_cvt_pk_bf16_f32 v26, v26, v27
	v_cvt_pk_bf16_f32 v27, v40, v41
	global_store_dwordx4 v[48:49], v[24:27], off offset:256
	v_pk_mul_f32 v[16:17], v[16:17], v[132:133] op_sel_hi:[1,0]
	v_pk_mul_f32 v[14:15], v[14:15], v[112:113] op_sel_hi:[1,0]
	v_mad_i64_i32 v[24:25], s[4:5], v166, s76, v[120:121]
	v_lshl_add_u64 v[32:33], v[24:25], 0, v[122:123]
	v_pk_mul_f32 v[26:27], v[38:39], v[132:133] op_sel_hi:[1,0]
	v_pk_mul_f32 v[24:25], v[36:37], v[132:133] op_sel_hi:[1,0]
	v_pk_mul_f32 v[12:13], v[12:13], v[112:113] op_sel_hi:[1,0]
	v_cvt_pk_bf16_f32 v24, v24, v25
	v_cvt_pk_bf16_f32 v25, v26, v27
	v_cvt_pk_bf16_f32 v26, v28, v29
	v_cvt_pk_bf16_f32 v27, v30, v31
	global_store_dwordx4 v[32:33], v[24:27], off
	v_pk_mul_f32 v[6:7], v[6:7], v[112:113] op_sel_hi:[1,0]
	v_pk_mul_f32 v[4:5], v[4:5], v[112:113] op_sel_hi:[1,0]
	v_pk_mul_f32 v[24:25], v[10:11], v[132:133] op_sel_hi:[1,0]
	v_pk_mul_f32 v[10:11], v[8:9], v[132:133] op_sel_hi:[1,0]
	v_cvt_pk_bf16_f32 v8, v16, v17
	v_cvt_pk_bf16_f32 v9, v18, v19
	v_cvt_pk_bf16_f32 v10, v10, v11
	v_cvt_pk_bf16_f32 v11, v24, v25
	global_store_dwordx4 v[32:33], v[8:11], off offset:256
	s_and_b64 vcc, exec, s[0:1]
	s_mov_b64 s[8:9], s[36:37]
	v_mad_i64_i32 v[8:9], s[4:5], v162, s76, v[120:121]
	v_lshl_add_u64 v[16:17], v[8:9], 0, v[122:123]
	v_pk_mul_f32 v[10:11], v[22:23], v[112:113] op_sel_hi:[1,0]
	v_pk_mul_f32 v[8:9], v[20:21], v[112:113] op_sel_hi:[1,0]
	s_mov_b32 s5, s28
	v_cvt_pk_bf16_f32 v8, v8, v9
	v_cvt_pk_bf16_f32 v9, v10, v11
	v_cvt_pk_bf16_f32 v10, v12, v13
	v_cvt_pk_bf16_f32 v11, v14, v15
	global_store_dwordx4 v[16:17], v[8:11], off
	s_mov_b32 s4, s30
	s_mov_b64 s[6:7], s[34:35]
	v_pk_mul_f32 v[8:9], v[2:3], v[112:113] op_sel_hi:[1,0]
	v_pk_mul_f32 v[2:3], v[0:1], v[112:113] op_sel_hi:[1,0]
	v_cvt_pk_bf16_f32 v0, v4, v5
	v_cvt_pk_bf16_f32 v1, v6, v7
	v_cvt_pk_bf16_f32 v2, v2, v3
	v_cvt_pk_bf16_f32 v3, v8, v9
	global_store_dwordx4 v[16:17], v[0:3], off offset:256
	s_cbranch_vccz .LBB0_343
	s_waitcnt vmcnt(0)
	s_cmpk_gt_u32 s27, 0xff
	s_cbranch_scc1 .LBB0_350
	s_barrier

; #define PG8_STAGE(bufoff, gbase, voff) do { _Pragma("unroll") for (int _i = 0; _i < 2; ++_i) \
;     __builtin_amdgcn_global_load_lds((const unsigned*)((const char*)(gbase) + (voff)[_i]), (LAS unsigned*)(lds + (bufoff) + ldsw + _i * 8192), 16, 0, 0); } while (0)
; #define PG8_LDA(dst, b, h) do { _Pragma("unroll") for (int m = 0; m < 4; ++m) _Pragma("unroll") for (int k = 0; k < 2; ++k) dst[m][k] = *(const LAS bf16x8*)(lds + PG8_SA(b, h) + aoff + m * 2048 + k * 1024); } while (0)
; #define PG8_LDB(dst, b, h) do { _Pragma("unroll") for (int n = 0; n < 2; ++n) _Pragma("unroll") for (int k = 0; k < 2; ++k) dst[n][k] = *(const LAS bf16x8*)(lds + PG8_SB(b, h) + boff + n * 2048 + k * 1024); } while (0)
; #define PG8_MMA(ai, bj, At, Bt) do { __builtin_amdgcn_s_setprio(1); _Pragma("unroll") for (int m = 0; m < 4; ++m) _Pragma("unroll") for (int n = 0; n < 2; ++n) _Pragma("unroll") for (int k = 0; k < 2; ++k) \
;     acc[ai][bj][m][n] = __builtin_amdgcn_mfma_f32_16x16x32_bf16(Bt[n][k], At[m][k], acc[ai][bj][m][n], 0, 0, 0); __builtin_amdgcn_s_setprio(0); } while (0)
; #define PG8_WAIT_V(n) asm volatile("s_waitcnt vmcnt(" #n ")" ::: "memory")
; #define PG8_WAIT_L(n) asm volatile("s_waitcnt lgkmcnt(" #n ")" ::: "memory")
; #define PG8_BAR __builtin_amdgcn_s_barrier()
; #define PG8_SCHED __builtin_amdgcn_sched_barrier(0)
; template <class Epi, class Sched = StaticOrder>
; DI void gemm_phase(LAS unsigned char* lds, const Gemm g, const Sched& S, const Epi& E) {
;     ...
;     for (int t = 0; t < nt; t += 2) {
;       const bool last = (t == nt - 2);
;       const char* a1 = cA + (size_t)(t + 1) * kstep;
;       const char* a2 = last ? nA : cA + (size_t)(t + 2) * kstep; const char* b2 = last ? nB : cB + (size_t)(t + 2) * kstep;
;       const char* a3 = a2 + kstep; const char* b3 = b2 + kstep;
;       PG8_LDB(B0, 0, 0); PG8_SCHED; PG8_LDA(At, 0, 0); PG8_STAGE(PG8_SA(1, 1), a1 + hstep, voffA);
;       PG8_WAIT_L(8); PG8_BAR; PG8_WAIT_L(0); PG8_MMA(0, 0, At, B0); PG8_BAR; PG8_SCHED;
;       PG8_LDB(B1, 0, 1); PG8_STAGE(PG8_SB(0, 0), b2, voffB);
;       PG8_BAR; PG8_WAIT_L(0); PG8_MMA(0, 1, At, B1); PG8_BAR;
;       PG8_LDA(At, 0, 1); PG8_STAGE(PG8_SA(0, 0), a2, voffA);
;       PG8_BAR; PG8_WAIT_L(0); PG8_MMA(1, 0, At, B0); PG8_BAR; PG8_SCHED;
;       PG8_STAGE(PG8_SB(0, 1), b2 + hstep, voffB);
;       PG8_WAIT_V(6); PG8_BAR; PG8_MMA(1, 1, At, B1); PG8_BAR;
.LBB0_728:
	s_add_u32 s24, s22, 0xfff80080
	s_addc_u32 s25, s23, -1
	s_cmp_eq_u32 s53, 28
	s_cselect_b32 s27, s17, s25
	s_cselect_b32 s26, s43, s24
	s_cselect_b32 s25, s15, s52
	s_cselect_b32 s24, s44, s45
	s_add_i32 m0, s37, 0xc000
	ds_read_b128 v[144:147], v208
	ds_read_b128 v[148:151], v208 offset:1024
	ds_read_b128 v[152:155], v208 offset:2048
	ds_read_b128 v[156:159], v208 offset:3072
	ds_read_b128 v[160:163], v208 offset:4096
	ds_read_b128 v[164:167], v208 offset:5120
	ds_read_b128 v[168:171], v208 offset:6144
	ds_read_b128 v[172:175], v208 offset:7168
	global_load_lds_dwordx4 v184, s[22:23]
	s_waitcnt lgkmcnt(0)
	s_setprio 1
	s_barrier
	v_mfma_f32_16x16x32_bf16 v[124:127], v[128:131], v[144:147], v[124:127]
	v_mfma_f32_16x16x32_bf16 v[120:123], v[136:139], v[144:147], v[120:123]
	v_mfma_f32_16x16x32_bf16 v[108:111], v[128:131], v[152:155], v[108:111]
	v_mfma_f32_16x16x32_bf16 v[104:107], v[136:139], v[152:155], v[104:107]
	v_mfma_f32_16x16x32_bf16 v[92:95], v[128:131], v[160:163], v[92:95]
	v_mfma_f32_16x16x32_bf16 v[88:91], v[136:139], v[160:163], v[88:91]
	v_mfma_f32_16x16x32_bf16 v[76:79], v[128:131], v[168:171], v[76:79]
	v_mfma_f32_16x16x32_bf16 v[72:75], v[136:139], v[168:171], v[72:75]
	v_mfma_f32_16x16x32_bf16 v[124:127], v[132:135], v[148:151], v[124:127]
	v_mfma_f32_16x16x32_bf16 v[120:123], v[140:143], v[148:151], v[120:123]
	v_mfma_f32_16x16x32_bf16 v[108:111], v[132:135], v[156:159], v[108:111]
	v_mfma_f32_16x16x32_bf16 v[104:107], v[140:143], v[156:159], v[104:107]
	v_mfma_f32_16x16x32_bf16 v[92:95], v[132:135], v[164:167], v[92:95]
	v_mfma_f32_16x16x32_bf16 v[88:91], v[140:143], v[164:167], v[88:91]
	v_mfma_f32_16x16x32_bf16 v[76:79], v[132:135], v[172:175], v[76:79]
	v_mfma_f32_16x16x32_bf16 v[72:75], v[140:143], v[172:175], v[72:75]
	s_barrier
	s_setprio 0
	s_add_i32 m0, s37, 0xe000
	s_nop 0
	global_load_lds_dwordx4 v186, s[22:23]
	s_add_i32 s54, s50, s35
	s_add_u32 s98, s24, 0x80
	s_addc_u32 s99, s25, 0
	s_add_u32 s100, s26, 0x80
	s_addc_u32 s101, s27, 0
	s_mov_b32 m0, s54
	ds_read_b128 v[192:195], v209
	ds_read_b128 v[196:199], v209 offset:1024
	ds_read_b128 v[200:203], v209 offset:2048
	ds_read_b128 v[212:215], v209 offset:3072
	global_load_lds_dwordx4 v180, s[24:25]
	s_add_i32 m0, s54, 0x2000
	s_nop 0
	global_load_lds_dwordx4 v176, s[24:25]
	s_waitcnt lgkmcnt(0)
	s_setprio 1
	s_barrier
	v_mfma_f32_16x16x32_bf16 v[116:119], v[192:195], v[144:147], v[116:119]
	v_mfma_f32_16x16x32_bf16 v[112:115], v[200:203], v[144:147], v[112:115]
	v_mfma_f32_16x16x32_bf16 v[100:103], v[192:195], v[152:155], v[100:103]
	v_mfma_f32_16x16x32_bf16 v[96:99], v[200:203], v[152:155], v[96:99]
	v_mfma_f32_16x16x32_bf16 v[84:87], v[192:195], v[160:163], v[84:87]
	v_mfma_f32_16x16x32_bf16 v[80:83], v[200:203], v[160:163], v[80:83]
	v_mfma_f32_16x16x32_bf16 v[68:71], v[192:195], v[168:171], v[68:71]
	v_mfma_f32_16x16x32_bf16 v[64:67], v[200:203], v[168:171], v[64:67]
	v_mfma_f32_16x16x32_bf16 v[116:119], v[196:199], v[148:151], v[116:119]
	v_mfma_f32_16x16x32_bf16 v[112:115], v[212:215], v[148:151], v[112:115]
	v_mfma_f32_16x16x32_bf16 v[100:103], v[196:199], v[156:159], v[100:103]
	v_mfma_f32_16x16x32_bf16 v[96:99], v[212:215], v[156:159], v[96:99]
	v_mfma_f32_16x16x32_bf16 v[84:87], v[196:199], v[164:167], v[84:87]
	v_mfma_f32_16x16x32_bf16 v[80:83], v[212:215], v[164:167], v[80:83]
	v_mfma_f32_16x16x32_bf16 v[68:71], v[196:199], v[172:175], v[68:71]
	v_mfma_f32_16x16x32_bf16 v[64:67], v[212:215], v[172:175], v[64:67]
	s_barrier
	s_setprio 0
	s_mov_b32 m0, s37
	ds_read_b128 v[144:147], v208 offset:16384
	ds_read_b128 v[148:151], v208 offset:17408
	ds_read_b128 v[152:155], v208 offset:18432
	ds_read_b128 v[156:159], v208 offset:19456
	ds_read_b128 v[160:163], v208 offset:20480
	ds_read_b128 v[164:167], v208 offset:21504
	ds_read_b128 v[168:171], v208 offset:22528
	ds_read_b128 v[172:175], v208 offset:23552
	global_load_lds_dwordx4 v182, s[26:27]
	s_waitcnt vmcnt(9)
	s_waitcnt lgkmcnt(0)
	s_setprio 1
	s_barrier
	v_mfma_f32_16x16x32_bf16 v[60:63], v[128:131], v[144:147], v[60:63]
	v_mfma_f32_16x16x32_bf16 v[56:59], v[136:139], v[144:147], v[56:59]
	v_mfma_f32_16x16x32_bf16 v[44:47], v[128:131], v[152:155], v[44:47]
	v_mfma_f32_16x16x32_bf16 v[40:43], v[136:139], v[152:155], v[40:43]
	v_mfma_f32_16x16x32_bf16 v[28:31], v[128:131], v[160:163], v[28:31]
	v_mfma_f32_16x16x32_bf16 v[24:27], v[136:139], v[160:163], v[24:27]
	v_mfma_f32_16x16x32_bf16 v[12:15], v[128:131], v[168:171], v[12:15]
	v_mfma_f32_16x16x32_bf16 v[8:11], v[136:139], v[168:171], v[8:11]
	v_mfma_f32_16x16x32_bf16 v[60:63], v[132:135], v[148:151], v[60:63]
	v_mfma_f32_16x16x32_bf16 v[56:59], v[140:143], v[148:151], v[56:59]
	v_mfma_f32_16x16x32_bf16 v[44:47], v[132:135], v[156:159], v[44:47]
	v_mfma_f32_16x16x32_bf16 v[40:43], v[140:143], v[156:159], v[40:43]
	v_mfma_f32_16x16x32_bf16 v[28:31], v[132:135], v[164:167], v[28:31]
	v_mfma_f32_16x16x32_bf16 v[24:27], v[140:143], v[164:167], v[24:27]
	v_mfma_f32_16x16x32_bf16 v[12:15], v[132:135], v[172:175], v[12:15]
	v_mfma_f32_16x16x32_bf16 v[8:11], v[140:143], v[172:175], v[8:11]
	s_barrier
	s_setprio 0
	s_mov_b32 m0, s38
	s_nop 0
	global_load_lds_dwordx4 v178, s[26:27]
	s_add_u32 s54, s24, 0x80000
	s_addc_u32 s55, s25, 0
	s_add_i32 s57, s51, s35
	s_mov_b32 m0, s57
	s_nop 0
	global_load_lds_dwordx4 v180, s[54:55]
	s_add_i32 m0, s57, 0x2000
	s_nop 0
	global_load_lds_dwordx4 v176, s[54:55]
	s_add_i32 s54, 0, 0x18000
	v_add_u32_e32 v140, s54, v205
	ds_read_b128 v[128:131], v140
	ds_read_b128 v[132:135], v140 offset:1024
	ds_read_b128 v[136:139], v140 offset:2048
	ds_read_b128 v[140:143], v140 offset:3072
	s_waitcnt vmcnt(6)
	s_setprio 1
	s_barrier
; #define PG8_STAGE(bufoff, gbase, voff) do { _Pragma("unroll") for (int _i = 0; _i < 2; ++_i) \
;     __builtin_amdgcn_global_load_lds((const unsigned*)((const char*)(gbase) + (voff)[_i]), (LAS unsigned*)(lds + (bufoff) + ldsw + _i * 8192), 16, 0, 0); } while (0)
; #define PG8_LDA(dst, b, h) do { _Pragma("unroll") for (int m = 0; m < 4; ++m) _Pragma("unroll") for (int k = 0; k < 2; ++k) dst[m][k] = *(const LAS bf16x8*)(lds + PG8_SA(b, h) + aoff + m * 2048 + k * 1024); } while (0)
; #define PG8_LDB(dst, b, h) do { _Pragma("unroll") for (int n = 0; n < 2; ++n) _Pragma("unroll") for (int k = 0; k < 2; ++k) dst[n][k] = *(const LAS bf16x8*)(lds + PG8_SB(b, h) + boff + n * 2048 + k * 1024); } while (0)
; #define PG8_MMA(ai, bj, At, Bt) do { __builtin_amdgcn_s_setprio(1); _Pragma("unroll") for (int m = 0; m < 4; ++m) _Pragma("unroll") for (int n = 0; n < 2; ++n) _Pragma("unroll") for (int k = 0; k < 2; ++k) \
;     acc[ai][bj][m][n] = __builtin_amdgcn_mfma_f32_16x16x32_bf16(Bt[n][k], At[m][k], acc[ai][bj][m][n], 0, 0, 0); __builtin_amdgcn_s_setprio(0); } while (0)
; #define PG8_WAIT_V(n) asm volatile("s_waitcnt vmcnt(" #n ")" ::: "memory")
; #define PG8_WAIT_L(n) asm volatile("s_waitcnt lgkmcnt(" #n ")" ::: "memory")
; #define PG8_BAR __builtin_amdgcn_s_barrier()
; #define PG8_SCHED __builtin_amdgcn_sched_barrier(0)
; template <class Epi, class Sched = StaticOrder>
; DI void gemm_phase(LAS unsigned char* lds, const Gemm g, const Sched& S, const Epi& E) {
;     ...
;       PG8_WAIT_V(6); PG8_BAR; PG8_MMA(1, 1, At, B1); PG8_BAR;
;       PG8_LDB(B0, 1, 0); PG8_SCHED; PG8_LDA(At, 1, 0); PG8_STAGE(PG8_SA(0, 1), a2 + hstep, voffA);
;       PG8_WAIT_L(8); PG8_BAR; PG8_WAIT_L(0); PG8_MMA(0, 0, At, B0); PG8_BAR; PG8_SCHED;
;       PG8_LDB(B1, 1, 1); PG8_STAGE(PG8_SB(1, 0), b3, voffB);
;       PG8_BAR; PG8_WAIT_L(0); PG8_MMA(0, 1, At, B1); PG8_BAR;
;       PG8_LDA(At, 1, 1); PG8_STAGE(PG8_SA(1, 0), a3, voffA);
;       PG8_BAR; PG8_WAIT_L(0); PG8_MMA(1, 0, At, B0); PG8_BAR; PG8_SCHED;
;       PG8_STAGE(PG8_SB(1, 1), b3 + hstep, voffB);
;       PG8_WAIT_V(6); PG8_BAR; PG8_MMA(1, 1, At, B1); PG8_BAR;
	v_mfma_f32_16x16x32_bf16 v[52:55], v[192:195], v[144:147], v[52:55]
	v_mfma_f32_16x16x32_bf16 v[48:51], v[200:203], v[144:147], v[48:51]
	v_mfma_f32_16x16x32_bf16 v[36:39], v[192:195], v[152:155], v[36:39]
	v_mfma_f32_16x16x32_bf16 v[32:35], v[200:203], v[152:155], v[32:35]
	v_mfma_f32_16x16x32_bf16 v[20:23], v[192:195], v[160:163], v[20:23]
	v_mfma_f32_16x16x32_bf16 v[16:19], v[200:203], v[160:163], v[16:19]
	v_mfma_f32_16x16x32_bf16 v[4:7], v[192:195], v[168:171], v[4:7]
	v_mfma_f32_16x16x32_bf16 v[0:3], v[200:203], v[168:171], v[0:3]
	v_mfma_f32_16x16x32_bf16 v[52:55], v[196:199], v[148:151], v[52:55]
	v_mfma_f32_16x16x32_bf16 v[48:51], v[212:215], v[148:151], v[48:51]
	v_mfma_f32_16x16x32_bf16 v[36:39], v[196:199], v[156:159], v[36:39]
	v_mfma_f32_16x16x32_bf16 v[32:35], v[212:215], v[156:159], v[32:35]
	v_mfma_f32_16x16x32_bf16 v[20:23], v[196:199], v[164:167], v[20:23]
	v_mfma_f32_16x16x32_bf16 v[16:19], v[212:215], v[164:167], v[16:19]
	v_mfma_f32_16x16x32_bf16 v[4:7], v[196:199], v[172:175], v[4:7]
	v_mfma_f32_16x16x32_bf16 v[0:3], v[212:215], v[172:175], v[0:3]
	s_barrier
	s_setprio 0
	s_add_u32 s26, s26, 0x80000
	s_addc_u32 s27, s27, 0
	s_mov_b32 m0, s39
	ds_read_b128 v[144:147], v208 offset:32768
	ds_read_b128 v[148:151], v208 offset:33792
	ds_read_b128 v[152:155], v208 offset:34816
	ds_read_b128 v[156:159], v208 offset:35840
	ds_read_b128 v[160:163], v208 offset:36864
	ds_read_b128 v[164:167], v208 offset:37888
	ds_read_b128 v[168:171], v208 offset:38912
	ds_read_b128 v[172:175], v208 offset:39936
	global_load_lds_dwordx4 v182, s[26:27]
	s_waitcnt lgkmcnt(0)
	s_setprio 1
	s_barrier
	v_mfma_f32_16x16x32_bf16 v[124:127], v[128:131], v[144:147], v[124:127]
	v_mfma_f32_16x16x32_bf16 v[120:123], v[136:139], v[144:147], v[120:123]
	v_mfma_f32_16x16x32_bf16 v[108:111], v[128:131], v[152:155], v[108:111]
	v_mfma_f32_16x16x32_bf16 v[104:107], v[136:139], v[152:155], v[104:107]
	v_mfma_f32_16x16x32_bf16 v[92:95], v[128:131], v[160:163], v[92:95]
	v_mfma_f32_16x16x32_bf16 v[88:91], v[136:139], v[160:163], v[88:91]
	v_mfma_f32_16x16x32_bf16 v[76:79], v[128:131], v[168:171], v[76:79]
	v_mfma_f32_16x16x32_bf16 v[72:75], v[136:139], v[168:171], v[72:75]
	v_mfma_f32_16x16x32_bf16 v[124:127], v[132:135], v[148:151], v[124:127]
	v_mfma_f32_16x16x32_bf16 v[120:123], v[140:143], v[148:151], v[120:123]
	v_mfma_f32_16x16x32_bf16 v[108:111], v[132:135], v[156:159], v[108:111]
	v_mfma_f32_16x16x32_bf16 v[104:107], v[140:143], v[156:159], v[104:107]
	v_mfma_f32_16x16x32_bf16 v[92:95], v[132:135], v[164:167], v[92:95]
	v_mfma_f32_16x16x32_bf16 v[88:91], v[140:143], v[164:167], v[88:91]
	v_mfma_f32_16x16x32_bf16 v[76:79], v[132:135], v[172:175], v[76:79]
	v_mfma_f32_16x16x32_bf16 v[72:75], v[140:143], v[172:175], v[72:75]
	s_barrier
	s_setprio 0
	s_mov_b32 m0, s40
	s_nop 0
	global_load_lds_dwordx4 v178, s[26:27]
	s_add_i32 s26, 0, 0x1c000
	s_add_i32 s27, s54, s35
	v_add_u32_e32 v212, s26, v205
	s_mov_b32 m0, s27
	ds_read_b128 v[192:195], v212
	ds_read_b128 v[196:199], v212 offset:1024
	ds_read_b128 v[200:203], v212 offset:2048
	ds_read_b128 v[212:215], v212 offset:3072
	global_load_lds_dwordx4 v180, s[98:99]
	s_add_i32 m0, s27, 0x2000
	s_nop 0
	global_load_lds_dwordx4 v176, s[98:99]
	s_waitcnt lgkmcnt(0)
	s_setprio 1
	s_barrier
	v_mfma_f32_16x16x32_bf16 v[116:119], v[192:195], v[144:147], v[116:119]
	v_mfma_f32_16x16x32_bf16 v[112:115], v[200:203], v[144:147], v[112:115]
	v_mfma_f32_16x16x32_bf16 v[100:103], v[192:195], v[152:155], v[100:103]
	v_mfma_f32_16x16x32_bf16 v[96:99], v[200:203], v[152:155], v[96:99]
	v_mfma_f32_16x16x32_bf16 v[84:87], v[192:195], v[160:163], v[84:87]
	v_mfma_f32_16x16x32_bf16 v[80:83], v[200:203], v[160:163], v[80:83]
	v_mfma_f32_16x16x32_bf16 v[68:71], v[192:195], v[168:171], v[68:71]
	v_mfma_f32_16x16x32_bf16 v[64:67], v[200:203], v[168:171], v[64:67]
	v_mfma_f32_16x16x32_bf16 v[116:119], v[196:199], v[148:151], v[116:119]
	v_mfma_f32_16x16x32_bf16 v[112:115], v[212:215], v[148:151], v[112:115]
	v_mfma_f32_16x16x32_bf16 v[100:103], v[196:199], v[156:159], v[100:103]
	v_mfma_f32_16x16x32_bf16 v[96:99], v[212:215], v[156:159], v[96:99]
	v_mfma_f32_16x16x32_bf16 v[84:87], v[196:199], v[164:167], v[84:87]
	v_mfma_f32_16x16x32_bf16 v[80:83], v[212:215], v[164:167], v[80:83]
	v_mfma_f32_16x16x32_bf16 v[68:71], v[196:199], v[172:175], v[68:71]
	v_mfma_f32_16x16x32_bf16 v[64:67], v[212:215], v[172:175], v[64:67]
	s_barrier
	s_setprio 0
	s_mov_b32 m0, s46
	ds_read_b128 v[144:147], v208 offset:49152
	ds_read_b128 v[148:151], v208 offset:50176
	ds_read_b128 v[152:155], v208 offset:51200
	ds_read_b128 v[156:159], v208 offset:52224
	ds_read_b128 v[160:163], v208 offset:53248
	ds_read_b128 v[164:167], v208 offset:54272
	ds_read_b128 v[168:171], v208 offset:55296
	ds_read_b128 v[172:175], v208 offset:56320
	global_load_lds_dwordx4 v182, s[100:101]
	s_waitcnt vmcnt(9)
	s_waitcnt lgkmcnt(0)
	s_setprio 1
	s_barrier
	v_mfma_f32_16x16x32_bf16 v[60:63], v[128:131], v[144:147], v[60:63]
	v_mfma_f32_16x16x32_bf16 v[56:59], v[136:139], v[144:147], v[56:59]
	v_mfma_f32_16x16x32_bf16 v[44:47], v[128:131], v[152:155], v[44:47]
	v_mfma_f32_16x16x32_bf16 v[40:43], v[136:139], v[152:155], v[40:43]
	v_mfma_f32_16x16x32_bf16 v[28:31], v[128:131], v[160:163], v[28:31]
	v_mfma_f32_16x16x32_bf16 v[24:27], v[136:139], v[160:163], v[24:27]
	v_mfma_f32_16x16x32_bf16 v[12:15], v[128:131], v[168:171], v[12:15]
	v_mfma_f32_16x16x32_bf16 v[8:11], v[136:139], v[168:171], v[8:11]
	v_mfma_f32_16x16x32_bf16 v[60:63], v[132:135], v[148:151], v[60:63]
	v_mfma_f32_16x16x32_bf16 v[56:59], v[140:143], v[148:151], v[56:59]
	v_mfma_f32_16x16x32_bf16 v[44:47], v[132:135], v[156:159], v[44:47]
	v_mfma_f32_16x16x32_bf16 v[40:43], v[140:143], v[156:159], v[40:43]
	v_mfma_f32_16x16x32_bf16 v[28:31], v[132:135], v[164:167], v[28:31]
	v_mfma_f32_16x16x32_bf16 v[24:27], v[140:143], v[164:167], v[24:27]
	v_mfma_f32_16x16x32_bf16 v[12:15], v[132:135], v[172:175], v[12:15]
	v_mfma_f32_16x16x32_bf16 v[8:11], v[140:143], v[172:175], v[8:11]
	s_barrier
; DI unsigned pack2(float lo, float hi) { f32x2 v = {lo, hi}; bf16v2 r = __builtin_convertvector(v, bf16v2); return __builtin_bit_cast(unsigned, r); }
; #define PG8_STAGE(bufoff, gbase, voff) do { _Pragma("unroll") for (int _i = 0; _i < 2; ++_i) \
;     __builtin_amdgcn_global_load_lds((const unsigned*)((const char*)(gbase) + (voff)[_i]), (LAS unsigned*)(lds + (bufoff) + ldsw + _i * 8192), 16, 0, 0); } while (0)
; #define PG8_WAIT_V(n) asm volatile("s_waitcnt vmcnt(" #n ")" ::: "memory")
;   DI void operator()(const f32x4 (&acc)[2][2][4][2], const Unit& u, int wr, int wc, int fr, int fq) const {
;     const int row0 = u.pm * BM + wr * 64 + fr, col0 = u.pn * BM + wc * 32 + 8 * fq;
; #pragma unroll
;     for (int ai = 0; ai < 2; ++ai) {
;       f32x4 bv[4][2][2];
; #pragma unroll
;       for (int m = 0; m < 4; ++m)
; #pragma unroll
;         for (int bj = 0; bj < 2; ++bj) {
;           const float* bp = base + (size_t)(row0 + ai * HALF + m * 16) * 2048 + col0 + bj * HALF;
;           bv[m][bj][0] = *(const f32x4*)bp; bv[m][bj][1] = *(const f32x4*)(bp + 4);
;         }
; #pragma unroll
;       for (int m = 0; m < 4; ++m) {
;         const int row = row0 + ai * HALF + m * 16;
;         const size_t off = (size_t)row * 2048 + col0;
;         float ss = 0.f;
; #pragma unroll
;         for (int bj = 0; bj < 2; ++bj) {
;           const f32x4 v0 = acc[ai][bj][m][0] + bv[m][bj][0], v1 = acc[ai][bj][m][1] + bv[m][bj][1];
;           *(f32x4*)(C + off + bj * HALF) = v0; *(f32x4*)(C + off + bj * HALF + 4) = v1;
;           if (xb) {
;             u32x4 w; w.x = pack2(v0[0], v0[1]); w.y = pack2(v0[2], v0[3]); w.z = pack2(v1[0], v1[1]); w.w = pack2(v1[2], v1[3]);
;             *(u32x4*)(xb + off + bj * HALF) = w;
;             ss += v0[0] * v0[0] + v0[1] * v0[1] + v0[2] * v0[2] + v0[3] * v0[3] + v1[0] * v1[0] + v1[1] * v1[1] + v1[2] * v1[2] + v1[3] * v1[3];
;           }
;         }
;         if (xb) {
;           ss += __shfl_xor(ss, 16); ss += __shfl_xor(ss, 32);
;           if (fq == 0) ssq[(size_t)row * 32 + u.pn * 4 + wc] = ss;
; template <class Epi, class Sched = StaticOrder>
; DI void gemm_phase(LAS unsigned char* lds, const Gemm g, const Sched& S, const Epi& E) {
;     ...
;       PG8_STAGE(PG8_SB(1, 1), b3 + hstep, voffB);
;       PG8_WAIT_V(6); PG8_BAR; PG8_MMA(1, 1, At, B1); PG8_BAR;
;     }
;     E(acc, cur, wr, wc, fr, fq);
	s_setprio 0
	s_mov_b32 m0, s47
	s_nop 0
	global_load_lds_dwordx4 v178, s[100:101]
	s_add_u32 s24, s24, 0x80080
	s_addc_u32 s25, s25, 0
	s_add_i32 s26, s26, s35
	s_mov_b32 m0, s26
	s_nop 0
	global_load_lds_dwordx4 v180, s[24:25]
	s_add_i32 m0, s26, 0x2000
	s_nop 0
	global_load_lds_dwordx4 v176, s[24:25]
	ds_read_b128 v[128:131], v207
	ds_read_b128 v[132:135], v207 offset:1024
	ds_read_b128 v[136:139], v207 offset:2048
	ds_read_b128 v[140:143], v207 offset:3072
	s_waitcnt vmcnt(6)
	s_setprio 1
	s_barrier
	v_mfma_f32_16x16x32_bf16 v[52:55], v[192:195], v[144:147], v[52:55]
	v_mfma_f32_16x16x32_bf16 v[48:51], v[200:203], v[144:147], v[48:51]
	v_mfma_f32_16x16x32_bf16 v[36:39], v[192:195], v[152:155], v[36:39]
	v_mfma_f32_16x16x32_bf16 v[32:35], v[200:203], v[152:155], v[32:35]
	v_mfma_f32_16x16x32_bf16 v[20:23], v[192:195], v[160:163], v[20:23]
	v_mfma_f32_16x16x32_bf16 v[16:19], v[200:203], v[160:163], v[16:19]
	v_mfma_f32_16x16x32_bf16 v[4:7], v[192:195], v[168:171], v[4:7]
	v_mfma_f32_16x16x32_bf16 v[0:3], v[200:203], v[168:171], v[0:3]
	v_mfma_f32_16x16x32_bf16 v[52:55], v[196:199], v[148:151], v[52:55]
	v_mfma_f32_16x16x32_bf16 v[48:51], v[212:215], v[148:151], v[48:51]
	v_mfma_f32_16x16x32_bf16 v[36:39], v[196:199], v[156:159], v[36:39]
	v_mfma_f32_16x16x32_bf16 v[32:35], v[212:215], v[156:159], v[32:35]
	v_mfma_f32_16x16x32_bf16 v[20:23], v[196:199], v[164:167], v[20:23]
	v_mfma_f32_16x16x32_bf16 v[16:19], v[212:215], v[164:167], v[16:19]
	v_mfma_f32_16x16x32_bf16 v[4:7], v[196:199], v[172:175], v[4:7]
	v_mfma_f32_16x16x32_bf16 v[0:3], v[212:215], v[172:175], v[0:3]
	s_add_i32 s53, s53, 2
	s_add_u32 s22, s22, 0x100
	s_addc_u32 s23, s23, 0
	s_add_u32 s45, s45, 0x100
	s_addc_u32 s52, s52, 0
	s_cmp_gt_u32 s53, 29
	s_barrier
	s_setprio 0
	s_cbranch_scc0 .LBB0_728
	s_waitcnt lgkmcnt(0)
	v_lshl_add_u32 v196, s12, 8, v204
	v_lshl_or_b32 v192, s42, 8, v206
	v_ashrrev_i32_e32 v193, 31, v192
	v_ashrrev_i32_e32 v197, 31, v196
	v_lshl_add_u64 v[194:195], v[192:193], 2, s[60:61]
	v_lshlrev_b64 v[128:129], 13, v[196:197]
	v_lshl_add_u64 v[128:129], v[194:195], 0, v[128:129]
	global_load_dwordx4 v[214:217], v[128:129], off
	global_load_dwordx4 v[218:221], v[128:129], off offset:16
	global_load_dwordx4 v[222:225], v[128:129], off offset:512
	global_load_dwordx4 v[226:229], v[128:129], off offset:528
	v_or_b32_e32 v202, 16, v196
	v_or_b32_e32 v200, 32, v196
	v_or_b32_e32 v198, 48, v196
	v_ashrrev_i32_e32 v203, 31, v202
	v_ashrrev_i32_e32 v201, 31, v200
	v_ashrrev_i32_e32 v199, 31, v198
	v_lshlrev_b64 v[128:129], 13, v[202:203]
	v_lshlrev_b64 v[130:131], 13, v[200:201]
	v_lshlrev_b64 v[132:133], 13, v[198:199]
	v_lshl_add_u64 v[128:129], v[194:195], 0, v[128:129]
	v_lshl_add_u64 v[130:131], v[194:195], 0, v[130:131]
	v_lshl_add_u64 v[132:133], v[194:195], 0, v[132:133]
	global_load_dwordx4 v[168:171], v[128:129], off offset:16
	global_load_dwordx4 v[172:175], v[128:129], off
	global_load_dwordx4 v[160:163], v[128:129], off offset:528
	global_load_dwordx4 v[164:167], v[128:129], off offset:512
	global_load_dwordx4 v[152:155], v[130:131], off offset:16
	global_load_dwordx4 v[156:159], v[130:131], off
	global_load_dwordx4 v[144:147], v[130:131], off offset:528
	global_load_dwordx4 v[148:151], v[130:131], off offset:512
	global_load_dwordx4 v[136:139], v[132:133], off offset:16
	global_load_dwordx4 v[140:143], v[132:133], off
	s_nop 0
	global_load_dwordx4 v[128:131], v[132:133], off offset:528
	s_nop 0
	global_load_dwordx4 v[132:135], v[132:133], off offset:512
	v_and_b32_e32 v212, 64, v211
	v_xor_b32_e32 v230, 16, v211
	v_add_u32_e32 v232, 64, v212
	v_xor_b32_e32 v231, 32, v211
	v_cmp_lt_i32_e32 vcc, v230, v232
	v_lshlrev_b64 v[212:213], 11, v[196:197]
	v_readlane_b32 s64, v243, 3
	v_cndmask_b32_e32 v233, v211, v230, vcc
	v_cmp_lt_i32_e32 vcc, v231, v232
	v_readlane_b32 s78, v243, 17
	v_readlane_b32 s79, v243, 18
	v_cndmask_b32_e32 v234, v211, v231, vcc
	v_lshl_add_u64 v[230:231], v[212:213], 0, v[192:193]
	v_lshlrev_b32_e32 v212, 2, v233
	v_lshl_add_u64 v[232:233], v[230:231], 2, s[78:79]
	v_lshl_add_u64 v[230:231], v[230:231], 1, s[2:3]
	s_lshl_b32 s22, s42, 2
	s_ashr_i32 s23, s22, 31
	v_readlane_b32 s65, v243, 4
	v_readlane_b32 s66, v243, 5
	v_readlane_b32 s67, v243, 6
	v_readlane_b32 s68, v243, 7
	v_readlane_b32 s69, v243, 8
	v_readlane_b32 s70, v243, 9
	v_readlane_b32 s71, v243, 10
	v_readlane_b32 s72, v243, 11
	v_readlane_b32 s73, v243, 12
	v_readlane_b32 s74, v243, 13
	v_readlane_b32 s75, v243, 14
	v_readlane_b32 s76, v243, 15
	v_readlane_b32 s77, v243, 16
	s_waitcnt vmcnt(0)
	v_pk_add_f32 v[126:127], v[126:127], v[216:217]
	v_pk_add_f32 v[124:125], v[124:125], v[214:215]
	v_pk_add_f32 v[116:117], v[116:117], v[222:223]
	v_pk_add_f32 v[122:123], v[122:123], v[220:221]
	v_pk_add_f32 v[120:121], v[120:121], v[218:219]
	v_pk_add_f32 v[214:215], v[112:113], v[226:227]
	global_store_dwordx4 v[232:233], v[124:127], off
	global_store_dwordx4 v[232:233], v[120:123], off offset:16
	v_cvt_pk_bf16_f32 v112, v124, v125
	v_mul_f32_e32 v125, v125, v125
	v_mul_f32_e32 v213, v117, v117
	v_pk_add_f32 v[118:119], v[118:119], v[224:225]
	v_fmac_f32_e32 v125, v124, v124
	v_fmac_f32_e32 v213, v116, v116
	v_fmac_f32_e32 v125, v126, v126
	v_fmac_f32_e32 v213, v118, v118
	v_fmac_f32_e32 v125, v127, v127
	v_fmac_f32_e32 v213, v119, v119
	v_fmac_f32_e32 v125, v120, v120
	v_fmac_f32_e32 v213, v214, v214
	v_pk_add_f32 v[216:217], v[114:115], v[228:229]
	v_fmac_f32_e32 v125, v121, v121
	v_fmac_f32_e32 v213, v215, v215
	v_fmac_f32_e32 v125, v122, v122
	v_fmac_f32_e32 v213, v216, v216
	v_fmac_f32_e32 v125, v123, v123
	v_fmac_f32_e32 v213, v217, v217
	v_cvt_pk_bf16_f32 v114, v120, v121
	v_add_f32_e32 v120, v125, v213
	ds_bpermute_b32 v121, v212, v120
	v_cvt_pk_bf16_f32 v113, v126, v127
	v_cvt_pk_bf16_f32 v115, v122, v123
	global_store_dwordx4 v[230:231], v[112:115], off
	global_store_dwordx4 v[232:233], v[116:119], off offset:512
	global_store_dwordx4 v[232:233], v[214:217], off offset:528
	v_cvt_pk_bf16_f32 v122, v116, v117
	s_waitcnt lgkmcnt(0)
	v_add_f32_e32 v112, v120, v121
	v_lshlrev_b32_e32 v120, 2, v234
	ds_bpermute_b32 v113, v120, v112
	v_cvt_pk_bf16_f32 v123, v118, v119
	v_cvt_pk_bf16_f32 v124, v214, v215
	v_cvt_pk_bf16_f32 v125, v216, v217
	global_store_dwordx4 v[230:231], v[122:125], off offset:256
	s_and_saveexec_b64 s[24:25], s[0:1]
	s_cbranch_execz .LBB0_731
	s_waitcnt lgkmcnt(0)
	v_add_f32_e32 v114, v112, v113
	v_lshlrev_b64 v[112:113], 7, v[196:197]
	v_lshl_add_u64 v[112:113], s[8:9], 0, v[112:113]
	v_lshl_add_u64 v[112:113], s[22:23], 2, v[112:113]
	s_lshl_b32 s12, s41, 2
	v_lshl_add_u64 v[112:113], v[112:113], 0, s[12:13]
	global_store_dword v[112:113], v114, off

; #define PG8_STAGE(bufoff, gbase, voff) do { _Pragma("unroll") for (int _i = 0; _i < 2; ++_i) \
;     __builtin_amdgcn_global_load_lds((const unsigned*)((const char*)(gbase) + (voff)[_i]), (LAS unsigned*)(lds + (bufoff) + ldsw + _i * 8192), 16, 0, 0); } while (0)
; #define PG8_LDA(dst, b, h) do { _Pragma("unroll") for (int m = 0; m < 4; ++m) _Pragma("unroll") for (int k = 0; k < 2; ++k) dst[m][k] = *(const LAS bf16x8*)(lds + PG8_SA(b, h) + aoff + m * 2048 + k * 1024); } while (0)
; #define PG8_LDB(dst, b, h) do { _Pragma("unroll") for (int n = 0; n < 2; ++n) _Pragma("unroll") for (int k = 0; k < 2; ++k) dst[n][k] = *(const LAS bf16x8*)(lds + PG8_SB(b, h) + boff + n * 2048 + k * 1024); } while (0)
; #define PG8_MMA(ai, bj, At, Bt) do { __builtin_amdgcn_s_setprio(1); _Pragma("unroll") for (int m = 0; m < 4; ++m) _Pragma("unroll") for (int n = 0; n < 2; ++n) _Pragma("unroll") for (int k = 0; k < 2; ++k) \
;     acc[ai][bj][m][n] = __builtin_amdgcn_mfma_f32_16x16x32_bf16(Bt[n][k], At[m][k], acc[ai][bj][m][n], 0, 0, 0); __builtin_amdgcn_s_setprio(0); } while (0)
; #define PG8_WAIT_V(n) asm volatile("s_waitcnt vmcnt(" #n ")" ::: "memory")
; #define PG8_WAIT_L(n) asm volatile("s_waitcnt lgkmcnt(" #n ")" ::: "memory")
; #define PG8_BAR __builtin_amdgcn_s_barrier()
; #define PG8_SCHED __builtin_amdgcn_sched_barrier(0)
; template <class Epi, class Sched = StaticOrder>
; DI void gemm_phase(LAS unsigned char* lds, const Gemm g, const Sched& S, const Epi& E) {
;     ...
;     for (int t = 0; t < nt; t += 2) {
;       const bool last = (t == nt - 2);
;       const char* a1 = cA + (size_t)(t + 1) * kstep;
;       const char* a2 = last ? nA : cA + (size_t)(t + 2) * kstep; const char* b2 = last ? nB : cB + (size_t)(t + 2) * kstep;
;       const char* a3 = a2 + kstep; const char* b3 = b2 + kstep;
;       PG8_LDB(B0, 0, 0); PG8_SCHED; PG8_LDA(At, 0, 0); PG8_STAGE(PG8_SA(1, 1), a1 + hstep, voffA);
;       PG8_WAIT_L(8); PG8_BAR; PG8_WAIT_L(0); PG8_MMA(0, 0, At, B0); PG8_BAR; PG8_SCHED;
;       PG8_LDB(B1, 0, 1); PG8_STAGE(PG8_SB(0, 0), b2, voffB);
;       PG8_BAR; PG8_WAIT_L(0); PG8_MMA(0, 1, At, B1); PG8_BAR;
;       PG8_LDA(At, 0, 1); PG8_STAGE(PG8_SA(0, 0), a2, voffA);
;       PG8_BAR; PG8_WAIT_L(0); PG8_MMA(1, 0, At, B0); PG8_BAR; PG8_SCHED;
;       PG8_STAGE(PG8_SB(0, 1), b2 + hstep, voffB);
;       PG8_WAIT_V(6); PG8_BAR; PG8_MMA(1, 1, At, B1); PG8_BAR;
.LBB0_811:
	s_add_u32 s46, s14, 0xfff80080
	s_addc_u32 s47, s15, -1
	s_cmp_eq_u32 s52, 28
	s_cselect_b32 s49, s37, s47
	s_cselect_b32 s48, s42, s46
	s_cselect_b32 s47, s35, s45
	s_cselect_b32 s46, s43, s44
	s_add_i32 m0, s62, 0xc000
	ds_read_b128 v[80:83], v202
	ds_read_b128 v[84:87], v202 offset:1024
	ds_read_b128 v[92:95], v202 offset:2048
	ds_read_b128 v[96:99], v202 offset:3072
	ds_read_b128 v[180:183], v202 offset:4096
	ds_read_b128 v[184:187], v202 offset:5120
	ds_read_b128 v[188:191], v202 offset:6144
	ds_read_b128 v[192:195], v202 offset:7168
	global_load_lds_dwordx4 v170, s[14:15]
	s_waitcnt lgkmcnt(0)
	s_setprio 1
	s_barrier
	v_mfma_f32_16x16x32_bf16 v[156:159], v[64:67], v[80:83], v[156:159]
	v_mfma_f32_16x16x32_bf16 v[144:147], v[72:75], v[80:83], v[144:147]
	v_mfma_f32_16x16x32_bf16 v[140:143], v[64:67], v[92:95], v[140:143]
	v_mfma_f32_16x16x32_bf16 v[132:135], v[72:75], v[92:95], v[132:135]
	v_mfma_f32_16x16x32_bf16 v[124:127], v[64:67], v[180:183], v[124:127]
	v_mfma_f32_16x16x32_bf16 v[116:119], v[72:75], v[180:183], v[116:119]
	v_mfma_f32_16x16x32_bf16 v[112:115], v[64:67], v[188:191], v[112:115]
	v_mfma_f32_16x16x32_bf16 v[108:111], v[72:75], v[188:191], v[108:111]
	v_mfma_f32_16x16x32_bf16 v[156:159], v[68:71], v[84:87], v[156:159]
	v_mfma_f32_16x16x32_bf16 v[144:147], v[76:79], v[84:87], v[144:147]
	v_mfma_f32_16x16x32_bf16 v[140:143], v[68:71], v[96:99], v[140:143]
	v_mfma_f32_16x16x32_bf16 v[132:135], v[76:79], v[96:99], v[132:135]
	v_mfma_f32_16x16x32_bf16 v[124:127], v[68:71], v[184:187], v[124:127]
	v_mfma_f32_16x16x32_bf16 v[116:119], v[76:79], v[184:187], v[116:119]
	v_mfma_f32_16x16x32_bf16 v[112:115], v[68:71], v[192:195], v[112:115]
	v_mfma_f32_16x16x32_bf16 v[108:111], v[76:79], v[192:195], v[108:111]
	s_barrier
	s_setprio 0
	s_add_i32 m0, s62, 0xe000
	s_nop 0
	global_load_lds_dwordx4 v172, s[14:15]
	s_add_i32 s53, s72, s60
	s_add_u32 s98, s46, 0x80
	s_addc_u32 s99, s47, 0
	s_add_u32 s100, s48, 0x80
	s_addc_u32 s101, s49, 0
	s_mov_b32 m0, s53
	ds_read_b128 v[206:209], v203
	ds_read_b128 v[212:215], v203 offset:1024
	ds_read_b128 v[216:219], v203 offset:2048
	ds_read_b128 v[220:223], v203 offset:3072
	global_load_lds_dwordx4 v164, s[46:47]
	s_add_i32 m0, s53, 0x2000
	s_nop 0
	global_load_lds_dwordx4 v160, s[46:47]
	s_waitcnt lgkmcnt(0)
	s_setprio 1
	s_barrier
	v_mfma_f32_16x16x32_bf16 v[152:155], v[206:209], v[80:83], v[152:155]
	v_mfma_f32_16x16x32_bf16 v[80:83], v[216:219], v[80:83], v[148:151]
	v_mfma_f32_16x16x32_bf16 v[152:155], v[212:215], v[84:87], v[152:155]
	v_mfma_f32_16x16x32_bf16 v[80:83], v[220:223], v[84:87], v[80:83]
	v_mfma_f32_16x16x32_bf16 v[84:87], v[206:209], v[92:95], v[136:139]
	v_mfma_f32_16x16x32_bf16 v[92:95], v[216:219], v[92:95], v[128:131]
	v_mfma_f32_16x16x32_bf16 v[104:107], v[216:219], v[180:183], v[104:107]
	v_mfma_f32_16x16x32_bf16 v[100:103], v[206:209], v[188:191], v[100:103]
	v_mfma_f32_16x16x32_bf16 v[88:91], v[216:219], v[188:191], v[88:91]
	v_mfma_f32_16x16x32_bf16 v[84:87], v[212:215], v[96:99], v[84:87]
	v_mfma_f32_16x16x32_bf16 v[92:95], v[220:223], v[96:99], v[92:95]
	v_mfma_f32_16x16x32_bf16 v[96:99], v[206:209], v[180:183], v[120:123]
	v_mfma_f32_16x16x32_bf16 v[104:107], v[220:223], v[184:187], v[104:107]
	v_mfma_f32_16x16x32_bf16 v[100:103], v[212:215], v[192:195], v[100:103]
	v_mfma_f32_16x16x32_bf16 v[88:91], v[220:223], v[192:195], v[88:91]
	v_mfma_f32_16x16x32_bf16 v[96:99], v[212:215], v[184:187], v[96:99]
	s_barrier
	s_setprio 0
	s_mov_b32 m0, s62
	ds_read_b128 v[120:123], v202 offset:16384
	ds_read_b128 v[128:131], v202 offset:17408
	ds_read_b128 v[136:139], v202 offset:18432
	ds_read_b128 v[148:151], v202 offset:19456
	ds_read_b128 v[180:183], v202 offset:20480
	ds_read_b128 v[184:187], v202 offset:21504
	ds_read_b128 v[188:191], v202 offset:22528
	ds_read_b128 v[192:195], v202 offset:23552
	global_load_lds_dwordx4 v166, s[48:49]
	s_waitcnt vmcnt(9)
	s_waitcnt lgkmcnt(0)
	s_setprio 1
	s_barrier
	v_mfma_f32_16x16x32_bf16 v[60:63], v[64:67], v[120:123], v[60:63]
	v_mfma_f32_16x16x32_bf16 v[48:51], v[72:75], v[120:123], v[48:51]
	v_mfma_f32_16x16x32_bf16 v[44:47], v[64:67], v[136:139], v[44:47]
	v_mfma_f32_16x16x32_bf16 v[36:39], v[72:75], v[136:139], v[36:39]
	v_mfma_f32_16x16x32_bf16 v[28:31], v[64:67], v[180:183], v[28:31]
	v_mfma_f32_16x16x32_bf16 v[20:23], v[72:75], v[180:183], v[20:23]
	v_mfma_f32_16x16x32_bf16 v[16:19], v[64:67], v[188:191], v[16:19]
	v_mfma_f32_16x16x32_bf16 v[12:15], v[72:75], v[188:191], v[12:15]
	v_mfma_f32_16x16x32_bf16 v[60:63], v[68:71], v[128:131], v[60:63]
	v_mfma_f32_16x16x32_bf16 v[48:51], v[76:79], v[128:131], v[48:51]
	v_mfma_f32_16x16x32_bf16 v[44:47], v[68:71], v[148:151], v[44:47]
	v_mfma_f32_16x16x32_bf16 v[36:39], v[76:79], v[148:151], v[36:39]
	v_mfma_f32_16x16x32_bf16 v[28:31], v[68:71], v[184:187], v[28:31]
	v_mfma_f32_16x16x32_bf16 v[20:23], v[76:79], v[184:187], v[20:23]
	v_mfma_f32_16x16x32_bf16 v[16:19], v[68:71], v[192:195], v[16:19]
	v_mfma_f32_16x16x32_bf16 v[12:15], v[76:79], v[192:195], v[12:15]
	s_barrier
	s_setprio 0
	s_mov_b32 m0, s63
	s_nop 0
	global_load_lds_dwordx4 v162, s[48:49]
	s_add_u32 s54, s46, 0x80000
	s_addc_u32 s55, s47, 0
	s_add_i32 s53, s73, s60
	s_mov_b32 m0, s53
	s_nop 0
	global_load_lds_dwordx4 v164, s[54:55]
	s_add_i32 m0, s53, 0x2000
	s_nop 0
	global_load_lds_dwordx4 v160, s[54:55]
	s_add_i32 s53, 0, 0x18000
	v_add_u32_e32 v76, s53, v198
	ds_read_b128 v[64:67], v76
	ds_read_b128 v[68:71], v76 offset:1024
	ds_read_b128 v[72:75], v76 offset:2048
	ds_read_b128 v[76:79], v76 offset:3072
	s_waitcnt vmcnt(6)
	s_setprio 1
	s_barrier
; #define PG8_STAGE(bufoff, gbase, voff) do { _Pragma("unroll") for (int _i = 0; _i < 2; ++_i) \
;     __builtin_amdgcn_global_load_lds((const unsigned*)((const char*)(gbase) + (voff)[_i]), (LAS unsigned*)(lds + (bufoff) + ldsw + _i * 8192), 16, 0, 0); } while (0)
; #define PG8_LDA(dst, b, h) do { _Pragma("unroll") for (int m = 0; m < 4; ++m) _Pragma("unroll") for (int k = 0; k < 2; ++k) dst[m][k] = *(const LAS bf16x8*)(lds + PG8_SA(b, h) + aoff + m * 2048 + k * 1024); } while (0)
; #define PG8_LDB(dst, b, h) do { _Pragma("unroll") for (int n = 0; n < 2; ++n) _Pragma("unroll") for (int k = 0; k < 2; ++k) dst[n][k] = *(const LAS bf16x8*)(lds + PG8_SB(b, h) + boff + n * 2048 + k * 1024); } while (0)
; #define PG8_MMA(ai, bj, At, Bt) do { __builtin_amdgcn_s_setprio(1); _Pragma("unroll") for (int m = 0; m < 4; ++m) _Pragma("unroll") for (int n = 0; n < 2; ++n) _Pragma("unroll") for (int k = 0; k < 2; ++k) \
;     acc[ai][bj][m][n] = __builtin_amdgcn_mfma_f32_16x16x32_bf16(Bt[n][k], At[m][k], acc[ai][bj][m][n], 0, 0, 0); __builtin_amdgcn_s_setprio(0); } while (0)
; #define PG8_WAIT_V(n) asm volatile("s_waitcnt vmcnt(" #n ")" ::: "memory")
; #define PG8_WAIT_L(n) asm volatile("s_waitcnt lgkmcnt(" #n ")" ::: "memory")
; #define PG8_BAR __builtin_amdgcn_s_barrier()
; #define PG8_SCHED __builtin_amdgcn_sched_barrier(0)
; template <class Epi, class Sched = StaticOrder>
; DI void gemm_phase(LAS unsigned char* lds, const Gemm g, const Sched& S, const Epi& E) {
;     ...
;       PG8_WAIT_V(6); PG8_BAR; PG8_MMA(1, 1, At, B1); PG8_BAR;
;       PG8_LDB(B0, 1, 0); PG8_SCHED; PG8_LDA(At, 1, 0); PG8_STAGE(PG8_SA(0, 1), a2 + hstep, voffA);
;       PG8_WAIT_L(8); PG8_BAR; PG8_WAIT_L(0); PG8_MMA(0, 0, At, B0); PG8_BAR; PG8_SCHED;
;       PG8_LDB(B1, 1, 1); PG8_STAGE(PG8_SB(1, 0), b3, voffB);
;       PG8_BAR; PG8_WAIT_L(0); PG8_MMA(0, 1, At, B1); PG8_BAR;
;       PG8_LDA(At, 1, 1); PG8_STAGE(PG8_SA(1, 0), a3, voffA);
;       PG8_BAR; PG8_WAIT_L(0); PG8_MMA(1, 0, At, B0); PG8_BAR; PG8_SCHED;
;       PG8_STAGE(PG8_SB(1, 1), b3 + hstep, voffB);
;       PG8_WAIT_V(6); PG8_BAR; PG8_MMA(1, 1, At, B1); PG8_BAR;
	v_mfma_f32_16x16x32_bf16 v[56:59], v[206:209], v[120:123], v[56:59]
	v_mfma_f32_16x16x32_bf16 v[52:55], v[216:219], v[120:123], v[52:55]
	v_mfma_f32_16x16x32_bf16 v[40:43], v[206:209], v[136:139], v[40:43]
	v_mfma_f32_16x16x32_bf16 v[32:35], v[216:219], v[136:139], v[32:35]
	v_mfma_f32_16x16x32_bf16 v[24:27], v[206:209], v[180:183], v[24:27]
	v_mfma_f32_16x16x32_bf16 v[8:11], v[216:219], v[180:183], v[8:11]
	v_mfma_f32_16x16x32_bf16 v[4:7], v[206:209], v[188:191], v[4:7]
	v_mfma_f32_16x16x32_bf16 v[0:3], v[216:219], v[188:191], v[0:3]
	v_mfma_f32_16x16x32_bf16 v[56:59], v[212:215], v[128:131], v[56:59]
	v_mfma_f32_16x16x32_bf16 v[52:55], v[220:223], v[128:131], v[52:55]
	v_mfma_f32_16x16x32_bf16 v[40:43], v[212:215], v[148:151], v[40:43]
	v_mfma_f32_16x16x32_bf16 v[32:35], v[220:223], v[148:151], v[32:35]
	v_mfma_f32_16x16x32_bf16 v[24:27], v[212:215], v[184:187], v[24:27]
	v_mfma_f32_16x16x32_bf16 v[8:11], v[220:223], v[184:187], v[8:11]
	v_mfma_f32_16x16x32_bf16 v[4:7], v[212:215], v[192:195], v[4:7]
	v_mfma_f32_16x16x32_bf16 v[0:3], v[220:223], v[192:195], v[0:3]
	s_barrier
	s_setprio 0
	s_add_u32 s48, s48, 0x80000
	s_addc_u32 s49, s49, 0
	s_mov_b32 m0, s64
	ds_read_b128 v[120:123], v202 offset:32768
	ds_read_b128 v[128:131], v202 offset:33792
	ds_read_b128 v[180:183], v202 offset:34816
	ds_read_b128 v[184:187], v202 offset:35840
	ds_read_b128 v[188:191], v202 offset:36864
	ds_read_b128 v[192:195], v202 offset:37888
	ds_read_b128 v[206:209], v202 offset:38912
	ds_read_b128 v[212:215], v202 offset:39936
	global_load_lds_dwordx4 v166, s[48:49]
	s_waitcnt lgkmcnt(0)
	s_setprio 1
	s_barrier
	v_mfma_f32_16x16x32_bf16 v[136:139], v[64:67], v[120:123], v[156:159]
	v_mfma_f32_16x16x32_bf16 v[156:159], v[68:71], v[128:131], v[136:139]
	v_mfma_f32_16x16x32_bf16 v[136:139], v[72:75], v[120:123], v[144:147]
	v_mfma_f32_16x16x32_bf16 v[144:147], v[76:79], v[128:131], v[136:139]
	v_mfma_f32_16x16x32_bf16 v[136:139], v[64:67], v[180:183], v[140:143]
	v_mfma_f32_16x16x32_bf16 v[132:135], v[72:75], v[180:183], v[132:135]
	v_mfma_f32_16x16x32_bf16 v[124:127], v[64:67], v[188:191], v[124:127]
	v_mfma_f32_16x16x32_bf16 v[116:119], v[72:75], v[188:191], v[116:119]
	v_mfma_f32_16x16x32_bf16 v[112:115], v[64:67], v[206:209], v[112:115]
	v_mfma_f32_16x16x32_bf16 v[108:111], v[72:75], v[206:209], v[108:111]
	v_mfma_f32_16x16x32_bf16 v[140:143], v[68:71], v[184:187], v[136:139]
	v_mfma_f32_16x16x32_bf16 v[132:135], v[76:79], v[184:187], v[132:135]
	v_mfma_f32_16x16x32_bf16 v[124:127], v[68:71], v[192:195], v[124:127]
	v_mfma_f32_16x16x32_bf16 v[116:119], v[76:79], v[192:195], v[116:119]
	v_mfma_f32_16x16x32_bf16 v[112:115], v[68:71], v[212:215], v[112:115]
	v_mfma_f32_16x16x32_bf16 v[108:111], v[76:79], v[212:215], v[108:111]
	s_barrier
	s_setprio 0
	s_mov_b32 m0, s65
	s_nop 0
	global_load_lds_dwordx4 v162, s[48:49]
	s_add_i32 s48, 0, 0x1c000
	v_add_u32_e32 v136, s48, v198
	s_add_i32 s49, s53, s60
	ds_read_b128 v[216:219], v136
	ds_read_b128 v[220:223], v136 offset:1024
	ds_read_b128 v[224:227], v136 offset:2048
	ds_read_b128 v[228:231], v136 offset:3072
	s_mov_b32 m0, s49
	s_nop 0
	global_load_lds_dwordx4 v164, s[98:99]
	s_add_i32 m0, s49, 0x2000
	s_nop 0
	global_load_lds_dwordx4 v160, s[98:99]
	s_waitcnt lgkmcnt(0)
	s_setprio 1
	s_barrier
	v_mfma_f32_16x16x32_bf16 v[80:83], v[224:227], v[120:123], v[80:83]
	v_mfma_f32_16x16x32_bf16 v[136:139], v[216:219], v[120:123], v[152:155]
	v_mfma_f32_16x16x32_bf16 v[148:151], v[228:231], v[128:131], v[80:83]
	v_mfma_f32_16x16x32_bf16 v[80:83], v[216:219], v[180:183], v[84:87]
	v_mfma_f32_16x16x32_bf16 v[152:155], v[220:223], v[128:131], v[136:139]
	v_mfma_f32_16x16x32_bf16 v[136:139], v[220:223], v[184:187], v[80:83]
	v_mfma_f32_16x16x32_bf16 v[80:83], v[224:227], v[180:183], v[92:95]
	v_mfma_f32_16x16x32_bf16 v[128:131], v[228:231], v[184:187], v[80:83]
	v_mfma_f32_16x16x32_bf16 v[80:83], v[216:219], v[188:191], v[96:99]
	v_mfma_f32_16x16x32_bf16 v[120:123], v[220:223], v[192:195], v[80:83]
	v_mfma_f32_16x16x32_bf16 v[80:83], v[224:227], v[188:191], v[104:107]
	v_mfma_f32_16x16x32_bf16 v[104:107], v[228:231], v[192:195], v[80:83]
	v_mfma_f32_16x16x32_bf16 v[80:83], v[216:219], v[206:209], v[100:103]
	v_mfma_f32_16x16x32_bf16 v[100:103], v[220:223], v[212:215], v[80:83]
	v_mfma_f32_16x16x32_bf16 v[80:83], v[224:227], v[206:209], v[88:91]
	v_mfma_f32_16x16x32_bf16 v[88:91], v[228:231], v[212:215], v[80:83]
	s_barrier
	s_setprio 0
	s_mov_b32 m0, s67
	s_nop 2
	ds_read_b128 v[80:83], v202 offset:49152
	ds_read_b128 v[84:87], v202 offset:50176
	ds_read_b128 v[92:95], v202 offset:51200
	ds_read_b128 v[96:99], v202 offset:52224
	ds_read_b128 v[180:183], v202 offset:53248
	ds_read_b128 v[184:187], v202 offset:54272
	ds_read_b128 v[188:191], v202 offset:55296
	ds_read_b128 v[192:195], v202 offset:56320
	global_load_lds_dwordx4 v166, s[100:101]
	s_waitcnt vmcnt(9)
	s_waitcnt lgkmcnt(0)
	s_setprio 1
	s_barrier
	v_mfma_f32_16x16x32_bf16 v[60:63], v[64:67], v[80:83], v[60:63]
	v_mfma_f32_16x16x32_bf16 v[48:51], v[72:75], v[80:83], v[48:51]
	v_mfma_f32_16x16x32_bf16 v[44:47], v[64:67], v[92:95], v[44:47]
	v_mfma_f32_16x16x32_bf16 v[36:39], v[72:75], v[92:95], v[36:39]
	v_mfma_f32_16x16x32_bf16 v[28:31], v[64:67], v[180:183], v[28:31]
	v_mfma_f32_16x16x32_bf16 v[20:23], v[72:75], v[180:183], v[20:23]
	v_mfma_f32_16x16x32_bf16 v[16:19], v[64:67], v[188:191], v[16:19]
	v_mfma_f32_16x16x32_bf16 v[12:15], v[72:75], v[188:191], v[12:15]
	v_mfma_f32_16x16x32_bf16 v[60:63], v[68:71], v[84:87], v[60:63]
	v_mfma_f32_16x16x32_bf16 v[48:51], v[76:79], v[84:87], v[48:51]
	v_mfma_f32_16x16x32_bf16 v[44:47], v[68:71], v[96:99], v[44:47]
	v_mfma_f32_16x16x32_bf16 v[36:39], v[76:79], v[96:99], v[36:39]
	v_mfma_f32_16x16x32_bf16 v[28:31], v[68:71], v[184:187], v[28:31]
	v_mfma_f32_16x16x32_bf16 v[20:23], v[76:79], v[184:187], v[20:23]
	v_mfma_f32_16x16x32_bf16 v[16:19], v[68:71], v[192:195], v[16:19]
	v_mfma_f32_16x16x32_bf16 v[12:15], v[76:79], v[192:195], v[12:15]
	s_barrier
; #define PG8_STAGE(bufoff, gbase, voff) do { _Pragma("unroll") for (int _i = 0; _i < 2; ++_i) \
;     __builtin_amdgcn_global_load_lds((const unsigned*)((const char*)(gbase) + (voff)[_i]), (LAS unsigned*)(lds + (bufoff) + ldsw + _i * 8192), 16, 0, 0); } while (0)
; #define PG8_MMA(ai, bj, At, Bt) do { __builtin_amdgcn_s_setprio(1); _Pragma("unroll") for (int m = 0; m < 4; ++m) _Pragma("unroll") for (int n = 0; n < 2; ++n) _Pragma("unroll") for (int k = 0; k < 2; ++k) \
;     acc[ai][bj][m][n] = __builtin_amdgcn_mfma_f32_16x16x32_bf16(Bt[n][k], At[m][k], acc[ai][bj][m][n], 0, 0, 0); __builtin_amdgcn_s_setprio(0); } while (0)
; #define PG8_WAIT_V(n) asm volatile("s_waitcnt vmcnt(" #n ")" ::: "memory")
; #define PG8_BAR __builtin_amdgcn_s_barrier()
; DI float row_rstd(const float* ssq, int row, int fq) {
;   const f32x4 a = *(const f32x4*)(ssq + (size_t)row * 32 + fq * 8), b = *(const f32x4*)(ssq + (size_t)row * 32 + fq * 8 + 4);
;   float sm = ((a[0] + a[1]) + (a[2] + a[3])) + ((b[0] + b[1]) + (b[2] + b[3]));
;   sm += __shfl_xor(sm, 16); sm += __shfl_xor(sm, 32);
;   return rsqrtf(sm * (1.0f / 2048.f) + 1e-6f);
; }
;   DI void operator()(const f32x4 (&acc)[2][2][4][2], const Unit& u, int wr, int wc, int fr, int fq) const {
;     const int col = u.pn * 128 + wc * 32 + 8 * fq;
;     float w0[8], w1[8], w2[8], bb[8];
; #pragma unroll
;     for (int e = 0; e < 8; ++e) { w0[e] = cw[col + e]; w1[e] = cw[5632 + col + e]; w2[e] = cw[2 * 5632 + col + e]; bb[e] = cb[col + e]; }
; #pragma unroll
;     for (int ai = 0; ai < 2; ++ai) {
;       const int row0 = u.pm * BM + ai * HALF + wr * 64, span = row0 >> 6;
;       float rsv[4];
; #pragma unroll
;       for (int m = 0; m < 4; ++m) rsv[m] = row_rstd(ssq, row0 + 16 * m + fr, fq);
; template <class Epi, class Sched = StaticOrder>
; DI void gemm_phase(LAS unsigned char* lds, const Gemm g, const Sched& S, const Epi& E) {
;     ...
;       PG8_STAGE(PG8_SB(1, 1), b3 + hstep, voffB);
;       PG8_WAIT_V(6); PG8_BAR; PG8_MMA(1, 1, At, B1); PG8_BAR;
;     }
;     E(acc, cur, wr, wc, fr, fq);
	s_setprio 0
	s_mov_b32 m0, s68
	s_nop 0
	global_load_lds_dwordx4 v162, s[100:101]
	s_add_u32 s46, s46, 0x80080
	s_addc_u32 s47, s47, 0
	s_add_i32 s48, s48, s60
	s_mov_b32 m0, s48
	s_nop 0
	global_load_lds_dwordx4 v164, s[46:47]
	s_add_i32 m0, s48, 0x2000
	s_nop 0
	global_load_lds_dwordx4 v160, s[46:47]
	ds_read_b128 v[64:67], v201
	ds_read_b128 v[68:71], v201 offset:1024
	ds_read_b128 v[72:75], v201 offset:2048
	ds_read_b128 v[76:79], v201 offset:3072
	s_waitcnt vmcnt(6)
	s_setprio 1
	s_barrier
	v_mfma_f32_16x16x32_bf16 v[56:59], v[216:219], v[80:83], v[56:59]
	v_mfma_f32_16x16x32_bf16 v[52:55], v[224:227], v[80:83], v[52:55]
	v_mfma_f32_16x16x32_bf16 v[40:43], v[216:219], v[92:95], v[40:43]
	v_mfma_f32_16x16x32_bf16 v[32:35], v[224:227], v[92:95], v[32:35]
	v_mfma_f32_16x16x32_bf16 v[24:27], v[216:219], v[180:183], v[24:27]
	v_mfma_f32_16x16x32_bf16 v[8:11], v[224:227], v[180:183], v[8:11]
	v_mfma_f32_16x16x32_bf16 v[4:7], v[216:219], v[188:191], v[4:7]
	v_mfma_f32_16x16x32_bf16 v[0:3], v[224:227], v[188:191], v[0:3]
	v_mfma_f32_16x16x32_bf16 v[56:59], v[220:223], v[84:87], v[56:59]
	v_mfma_f32_16x16x32_bf16 v[52:55], v[228:231], v[84:87], v[52:55]
	v_mfma_f32_16x16x32_bf16 v[40:43], v[220:223], v[96:99], v[40:43]
	v_mfma_f32_16x16x32_bf16 v[32:35], v[228:231], v[96:99], v[32:35]
	v_mfma_f32_16x16x32_bf16 v[24:27], v[220:223], v[184:187], v[24:27]
	v_mfma_f32_16x16x32_bf16 v[8:11], v[228:231], v[184:187], v[8:11]
	v_mfma_f32_16x16x32_bf16 v[4:7], v[220:223], v[192:195], v[4:7]
	v_mfma_f32_16x16x32_bf16 v[0:3], v[228:231], v[192:195], v[0:3]
	s_add_i32 s52, s52, 2
	s_add_u32 s14, s14, 0x100
	s_addc_u32 s15, s15, 0
	s_add_u32 s44, s44, 0x100
	s_addc_u32 s45, s45, 0
	s_cmp_gt_u32 s52, 29
	s_barrier
	s_setprio 0
	s_cbranch_scc0 .LBB0_811
	s_waitcnt lgkmcnt(0)
	s_lshl_b32 s35, s12, 8
	s_add_i32 s35, s35, s66
	v_or_b32_e32 v190, s35, v179
	v_ashrrev_i32_e32 v191, 31, v190
	v_lshlrev_b64 v[64:65], 7, v[190:191]
	v_or_b32_e32 v188, 16, v190
	v_lshl_add_u64 v[64:65], v[168:169], 0, v[64:65]
	v_ashrrev_i32_e32 v189, 31, v188
	global_load_dwordx4 v[192:195], v[64:65], off
	global_load_dwordx4 v[206:209], v[64:65], off offset:16
	v_lshlrev_b64 v[64:65], 7, v[188:189]
	v_lshl_add_u64 v[64:65], v[168:169], 0, v[64:65]
	global_load_dwordx4 v[212:215], v[64:65], off
	global_load_dwordx4 v[216:219], v[64:65], off offset:16
	v_or_b32_e32 v186, 32, v190
	v_ashrrev_i32_e32 v187, 31, v186
	v_lshlrev_b64 v[64:65], 7, v[186:187]
	v_or_b32_e32 v184, 48, v190
	v_lshl_add_u64 v[64:65], v[168:169], 0, v[64:65]
	v_ashrrev_i32_e32 v185, 31, v184
	global_load_dwordx4 v[220:223], v[64:65], off
	global_load_dwordx4 v[224:227], v[64:65], off offset:16
	v_lshlrev_b64 v[64:65], 7, v[184:185]
	v_lshl_add_u64 v[64:65], v[168:169], 0, v[64:65]
	global_load_dwordx4 v[228:231], v[64:65], off
	global_load_dwordx4 v[232:235], v[64:65], off offset:16
	v_lshl_or_b32 v180, s13, 7, v200
	v_and_b32_e32 v65, 64, v204
	v_xor_b32_e32 v64, 16, v204
	v_ashrrev_i32_e32 v181, 31, v180
	v_add_u32_e32 v65, 64, v65
	v_readlane_b32 s44, v243, 3
	v_xor_b32_e32 v66, 32, v204
	v_lshlrev_b64 v[182:183], 2, v[180:181]
	v_cmp_lt_i32_e32 vcc, v64, v65
	v_readlane_b32 s52, v243, 11
	v_readlane_b32 s53, v243, 12
	v_cndmask_b32_e32 v64, v204, v64, vcc
	v_cmp_lt_i32_e32 vcc, v66, v65
	v_lshl_add_u64 v[92:93], s[52:53], 0, v[182:183]
	v_readlane_b32 s54, v243, 13
	v_cndmask_b32_e32 v65, v204, v66, vcc
	v_add_co_u32_e32 v94, vcc, 0x5000, v92
	v_readlane_b32 s55, v243, 14
	s_nop 0
	v_addc_co_u32_e32 v95, vcc, 0, v93, vcc
	v_add_co_u32_e32 v96, vcc, 0xb000, v92
	v_lshl_add_u64 v[72:73], s[54:55], 0, v[182:183]
	v_lshl_add_u64 v[74:75], v[92:93], 0, s[26:27]
	v_lshl_add_u64 v[76:77], v[92:93], 0, s[28:29]
	v_addc_co_u32_e32 v97, vcc, 0, v93, vcc
	v_lshlrev_b32_e32 v187, 2, v64
	v_lshlrev_b32_e32 v185, 2, v65
	global_load_dwordx4 v[64:67], v[92:93], off offset:16
	global_load_dwordx4 v[80:83], v[92:93], off
	global_load_dwordx4 v[68:71], v[72:73], off offset:16
	global_load_dwordx4 v[84:87], v[72:73], off
	s_nop 0
	global_load_dwordx4 v[72:75], v[74:75], off offset:16
	s_nop 0
	global_load_dwordx4 v[76:79], v[76:77], off offset:16
	s_nop 0
	global_load_dwordx4 v[92:95], v[94:95], off offset:2048
	s_nop 0
	global_load_dwordx4 v[96:99], v[96:97], off
	v_mov_b32_e32 v211, 0
	v_mov_b32_e32 v205, 0
	v_readlane_b32 s45, v243, 4
	v_readlane_b32 s46, v243, 5
	v_readlane_b32 s47, v243, 6
	v_readlane_b32 s48, v243, 7
	v_readlane_b32 s49, v243, 8
	v_readlane_b32 s50, v243, 9
	v_readlane_b32 s51, v243, 10
	v_readlane_b32 s56, v243, 15
	v_readlane_b32 s57, v243, 16
	v_readlane_b32 s58, v243, 17
	v_readlane_b32 s59, v243, 18
	s_waitcnt vmcnt(0)
	v_mov_b32_e32 v196, v192
	v_mov_b32_e32 v197, v206
	v_mov_b32_e32 v206, v193
	v_mov_b32_e32 v192, v194
	v_mov_b32_e32 v193, v208
	v_mov_b32_e32 v208, v195
	v_pk_add_f32 v[194:195], v[196:197], v[206:207]
	v_pk_add_f32 v[192:193], v[192:193], v[208:209]
	v_mov_b32_e32 v196, v212
	v_mov_b32_e32 v197, v216
	v_mov_b32_e32 v216, v213
	v_mov_b32_e32 v206, v214
	v_mov_b32_e32 v207, v218
	v_mov_b32_e32 v218, v215
	v_pk_add_f32 v[192:193], v[194:195], v[192:193]
	v_pk_add_f32 v[194:195], v[196:197], v[216:217]
	v_pk_add_f32 v[196:197], v[206:207], v[218:219]
	v_mov_b32_e32 v208, v220
	v_pk_add_f32 v[194:195], v[194:195], v[196:197]
	v_mov_b32_e32 v197, v192
	v_mov_b32_e32 v196, v194
	v_mov_b32_e32 v192, v195
	v_pk_add_f32 v[192:193], v[196:197], v[192:193]
	ds_bpermute_b32 v195, v187, v193
	ds_bpermute_b32 v194, v187, v192
	v_mov_b32_e32 v209, v224
	v_mov_b32_e32 v224, v221
	v_mov_b32_e32 v212, v222
	v_mov_b32_e32 v213, v226
	s_waitcnt lgkmcnt(0)
; DI unsigned pack2(float lo, float hi) { f32x2 v = {lo, hi}; bf16v2 r = __builtin_convertvector(v, bf16v2); return __builtin_bit_cast(unsigned, r); }
; DI float silu_f(float x) { return x * sigmoid_f(x); }
; DI float dpp_ror1(float v) { return __int_as_float(__builtin_amdgcn_update_dpp(0, __float_as_int(v), 0x121, 0xf, 0xf, false)); }
; DI float dpp_ror2(float v) { return __int_as_float(__builtin_amdgcn_update_dpp(0, __float_as_int(v), 0x122, 0xf, 0xf, false)); }
;   DI void operator()(const f32x4 (&acc)[2][2][4][2], const Unit& u, int wr, int wc, int fr, int fq) const {
;     ...
;       const int row0 = u.pm * BM + ai * HALF + wr * 64, span = row0 >> 6;
;       float rsv[4];
; #pragma unroll
;       for (int m = 0; m < 4; ++m) rsv[m] = row_rstd(ssq, row0 + 16 * m + fr, fq);
;       float p1[8], p2[8];
; #pragma unroll
;       for (int e = 0; e < 8; ++e) { p1[e] = 0.f; p2[e] = 0.f; }
; #pragma unroll
;       for (int m = 0; m < 4; ++m) {
;         float g[8], uu[8], a[8];
;         const float rs = rsv[m];
; #pragma unroll
;         for (int e = 0; e < 4; ++e) { g[e] = acc[ai][0][m][0][e] * rs; g[4 + e] = acc[ai][0][m][1][e] * rs; uu[e] = acc[ai][1][m][0][e] * rs; uu[4 + e] = acc[ai][1][m][1][e] * rs; }
; #pragma unroll
;         for (int e = 0; e < 8; ++e) {
;           const float x1 = dpp_ror1(g[e]), x2 = dpp_ror2(g[e]);
;           const float pr1 = (fr == 0) ? p1[e] : x1, pr2 = (fr < 2) ? p2[e] : x2;
;           a[e] = w2[e] * g[e] + w1[e] * pr1 + w0[e] * pr2 + bb[e];
;           p1[e] = x1; p2[e] = x2;
;         }
;         if (m == 0 && fr < 2) {
;           float* ha = headA + (size_t)(span * 2 + fr) * 5632 + col; float* hu = headU + (size_t)(span * 2 + fr) * 5632 + col;
;           *(f32x4*)ha = (f32x4){a[0], a[1], a[2], a[3]}; *(f32x4*)(ha + 4) = (f32x4){a[4], a[5], a[6], a[7]};
;           *(f32x4*)hu = (f32x4){uu[0], uu[1], uu[2], uu[3]}; *(f32x4*)(hu + 4) = (f32x4){uu[4], uu[5], uu[6], uu[7]};
;         } else {
;           u32x4 w;
;           w.x = pack2(silu_f(a[0]) * uu[0], silu_f(a[1]) * uu[1]);
;           w.y = pack2(silu_f(a[2]) * uu[2], silu_f(a[3]) * uu[3]);
;           w.z = pack2(silu_f(a[4]) * uu[4], silu_f(a[5]) * uu[5]);
;           w.w = pack2(silu_f(a[6]) * uu[6], silu_f(a[7]) * uu[7]);
;           *(u32x4*)(H + (size_t)(row0 + 16 * m + fr) * 5632 + col) = w;
	v_pk_add_f32 v[192:193], v[192:193], v[194:195]
	ds_bpermute_b32 v195, v185, v193
	ds_bpermute_b32 v194, v185, v192
	v_mov_b32_e32 v226, v223
	v_mov_b32_e32 v196, v228
	v_mov_b32_e32 v197, v232
	v_mov_b32_e32 v232, v229
	s_waitcnt lgkmcnt(0)
	v_pk_add_f32 v[192:193], v[192:193], v[194:195]
	v_mov_b32_e32 v206, v230
	v_pk_fma_f32 v[192:193], v[192:193], s[30:31], v[178:179] op_sel_hi:[1,0,0]
	v_mov_b32_e32 v207, v234
	v_mul_f32_e32 v189, 0x4b800000, v193
	v_cmp_gt_f32_e64 s[12:13], s74, v193
	v_mov_b32_e32 v234, v231
	v_pk_add_f32 v[208:209], v[208:209], v[224:225]
	v_cndmask_b32_e64 v189, v193, v189, s[12:13]
	v_rsq_f32_e32 v189, v189
	v_pk_add_f32 v[212:213], v[212:213], v[226:227]
	v_pk_add_f32 v[196:197], v[196:197], v[232:233]
	v_pk_add_f32 v[194:195], v[206:207], v[234:235]
	v_mul_f32_e32 v191, 0x45800000, v189
	v_cndmask_b32_e64 v220, v189, v191, s[12:13]
	v_pk_add_f32 v[208:209], v[208:209], v[212:213]
	v_pk_add_f32 v[194:195], v[196:197], v[194:195]
	v_pk_mul_f32 v[156:157], v[156:157], v[220:221] op_sel_hi:[1,0]
	v_mov_b32_e32 v216, 0
	v_mov_b32_e32 v218, 0
	v_mov_b32_e32 v196, v194
	v_mov_b32_e32 v197, v208
	v_mov_b32_e32 v208, v195
	v_mov_b32_dpp v216, v156 row_ror:1 row_mask:0xf bank_mask:0xf
	v_mov_b32_dpp v218, v157 row_ror:1 row_mask:0xf bank_mask:0xf
	v_pk_add_f32 v[194:195], v[196:197], v[208:209]
	v_cndmask_b32_e64 v207, v218, 0, s[0:1]
	v_cndmask_b32_e64 v206, v216, 0, s[0:1]
	v_pk_mul_f32 v[158:159], v[158:159], v[220:221] op_sel_hi:[1,0]
	v_mov_b32_e32 v212, 0
	v_mov_b32_e32 v214, 0
	ds_bpermute_b32 v197, v187, v195
	ds_bpermute_b32 v196, v187, v194
	v_mov_b32_e32 v215, 0
	v_mov_b32_e32 v217, 0
	v_pk_mul_f32 v[206:207], v[92:93], v[206:207]
	v_mov_b32_dpp v212, v158 row_ror:1 row_mask:0xf bank_mask:0xf
	v_mov_b32_dpp v214, v159 row_ror:1 row_mask:0xf bank_mask:0xf
	v_mov_b32_dpp v215, v156 row_ror:2 row_mask:0xf bank_mask:0xf
	v_mov_b32_dpp v217, v157 row_ror:2 row_mask:0xf bank_mask:0xf
	v_pk_fma_f32 v[156:157], v[96:97], v[156:157], v[206:207]
	v_mov_b32_e32 v213, 0
	v_cndmask_b32_e64 v207, v214, 0, s[0:1]
	v_cndmask_b32_e64 v206, v212, 0, s[0:1]
	v_cndmask_b32_e64 v209, v217, 0, s[4:5]
	v_cndmask_b32_e64 v208, v215, 0, s[4:5]
	v_mov_b32_dpp v211, v158 row_ror:2 row_mask:0xf bank_mask:0xf
	v_mov_b32_dpp v213, v159 row_ror:2 row_mask:0xf bank_mask:0xf
	v_pk_mul_f32 v[206:207], v[94:95], v[206:207]
	v_pk_fma_f32 v[156:157], v[80:81], v[208:209], v[156:157]
	v_cndmask_b32_e64 v209, v213, 0, s[4:5]
	v_cndmask_b32_e64 v208, v211, 0, s[4:5]
	v_pk_fma_f32 v[158:159], v[98:99], v[158:159], v[206:207]
	v_pk_mul_f32 v[144:145], v[144:145], v[220:221] op_sel_hi:[1,0]
	v_pk_fma_f32 v[158:159], v[82:83], v[208:209], v[158:159]
	v_mov_b32_e32 v207, 0
	v_mov_b32_e32 v209, 0
	v_pk_mul_f32 v[146:147], v[146:147], v[220:221] op_sel_hi:[1,0]
	v_mov_b32_e32 v191, 0
	s_waitcnt lgkmcnt(0)
	v_pk_add_f32 v[194:195], v[194:195], v[196:197]
	v_mov_b32_dpp v207, v144 row_ror:1 row_mask:0xf bank_mask:0xf
	v_mov_b32_dpp v209, v145 row_ror:1 row_mask:0xf bank_mask:0xf
	v_mov_b32_dpp v191, v146 row_ror:1 row_mask:0xf bank_mask:0xf
	v_mov_b32_dpp v205, v147 row_ror:1 row_mask:0xf bank_mask:0xf
	ds_bpermute_b32 v197, v185, v195
	ds_bpermute_b32 v196, v185, v194
	v_pk_mul_f32 v[152:153], v[152:153], v[220:221] op_sel_hi:[1,0]
	v_pk_mul_f32 v[148:149], v[148:149], v[220:221] op_sel_hi:[1,0]
	v_pk_mul_f32 v[154:155], v[154:155], v[220:221] op_sel_hi:[1,0]
	v_pk_mul_f32 v[150:151], v[150:151], v[220:221] op_sel_hi:[1,0]
	v_mov_b32_e32 v206, 0
	v_mov_b32_e32 v208, 0
	v_cndmask_b32_e64 v223, v209, 0, s[0:1]
	v_cndmask_b32_e64 v222, v207, 0, s[0:1]
	v_mov_b32_e32 v189, 0
	v_mov_b32_e32 v193, 0
	v_cndmask_b32_e64 v221, v205, 0, s[0:1]
	v_cndmask_b32_e64 v220, v191, 0, s[0:1]
	v_mov_b32_dpp v206, v144 row_ror:2 row_mask:0xf bank_mask:0xf
	v_mov_b32_dpp v208, v145 row_ror:2 row_mask:0xf bank_mask:0xf
	v_pk_mul_f32 v[222:223], v[72:73], v[222:223]
	v_mov_b32_dpp v189, v146 row_ror:2 row_mask:0xf bank_mask:0xf
	v_mov_b32_dpp v193, v147 row_ror:2 row_mask:0xf bank_mask:0xf
	v_pk_mul_f32 v[220:221], v[74:75], v[220:221]
	v_cndmask_b32_e64 v225, v208, 0, s[4:5]
	v_cndmask_b32_e64 v224, v206, 0, s[4:5]
	v_pk_fma_f32 v[144:145], v[76:77], v[144:145], v[222:223]
	v_cndmask_b32_e64 v223, v193, 0, s[4:5]
	v_cndmask_b32_e64 v222, v189, 0, s[4:5]
	v_pk_fma_f32 v[146:147], v[78:79], v[146:147], v[220:221]
	v_pk_fma_f32 v[144:145], v[64:65], v[224:225], v[144:145]
	v_pk_fma_f32 v[146:147], v[66:67], v[222:223], v[146:147]
	v_cmp_gt_f32_e32 vcc, s74, v192
	v_pk_add_f32 v[156:157], v[84:85], v[156:157]
	v_pk_add_f32 v[158:159], v[86:87], v[158:159]
	v_pk_add_f32 v[144:145], v[68:69], v[144:145]
	v_pk_add_f32 v[146:147], v[70:71], v[146:147]
	s_and_saveexec_b64 s[12:13], s[10:11]
	s_xor_b64 s[12:13], exec, s[12:13]
	s_cbranch_execz .LBB0_814
	v_mul_f32_e32 v219, 0xbfb8aa3b, v156
	v_exp_f32_e32 v219, v219
	v_mul_f32_e32 v220, 0xbfb8aa3b, v157
	v_exp_f32_e32 v220, v220
	v_mul_f32_e32 v222, 0xbfb8aa3b, v159
	v_add_f32_e32 v219, 1.0, v219
	v_exp_f32_e32 v223, v222
	v_add_f32_e32 v221, 1.0, v220
	v_rcp_f32_e32 v220, v219
	v_mul_f32_e32 v219, 0xbfb8aa3b, v158
	v_exp_f32_e32 v219, v219
	v_rcp_f32_e32 v221, v221
	v_add_f32_e32 v219, 1.0, v219
	v_rcp_f32_e32 v222, v219
	v_add_f32_e32 v219, 1.0, v223
	v_rcp_f32_e32 v223, v219
	v_pk_mul_f32 v[156:157], v[156:157], v[220:221]
	s_nop 0
	v_pk_mul_f32 v[152:153], v[152:153], v[156:157]
	v_pk_mul_f32 v[156:157], v[158:159], v[222:223]
	v_cvt_pk_bf16_f32 v152, v152, v153
	v_mul_f32_e32 v153, 0xbfb8aa3b, v144
	v_pk_mul_f32 v[154:155], v[154:155], v[156:157]
	v_exp_f32_e32 v156, v153
	v_mul_f32_e32 v153, 0xbfb8aa3b, v145
	v_exp_f32_e32 v157, v153
	v_cvt_pk_bf16_f32 v153, v154, v155
	v_add_f32_e32 v154, 1.0, v156
	v_mul_f32_e32 v156, 0xbfb8aa3b, v146
	v_add_f32_e32 v155, 1.0, v157
	v_mul_f32_e32 v157, 0xbfb8aa3b, v147
	v_exp_f32_e32 v156, v156
	v_exp_f32_e32 v157, v157
	v_rcp_f32_e32 v154, v154
	v_rcp_f32_e32 v155, v155
	v_add_f32_e32 v156, 1.0, v156
	v_add_f32_e32 v157, 1.0, v157
	v_rcp_f32_e32 v156, v156
	v_rcp_f32_e32 v157, v157
	v_pk_mul_f32 v[144:145], v[144:145], v[154:155]
	s_nop 0
	v_pk_mul_f32 v[144:145], v[148:149], v[144:145]
	s_nop 0
	v_cvt_pk_bf16_f32 v154, v144, v145
	v_pk_mul_f32 v[144:145], v[146:147], v[156:157]
	s_nop 0
	v_pk_mul_f32 v[144:145], v[150:151], v[144:145]
	s_nop 0
	v_cvt_pk_bf16_f32 v155, v144, v145
	v_mov_b64_e32 v[144:145], s[16:17]
	v_mad_i64_i32 v[144:145], s[14:15], v190, s75, v[144:145]
	v_lshl_add_u64 v[144:145], v[180:181], 1, v[144:145]
	global_store_dwordx4 v[144:145], v[152:155], off

; #define PG8_STAGE(bufoff, gbase, voff) do { _Pragma("unroll") for (int _i = 0; _i < 2; ++_i) \
;     __builtin_amdgcn_global_load_lds((const unsigned*)((const char*)(gbase) + (voff)[_i]), (LAS unsigned*)(lds + (bufoff) + ldsw + _i * 8192), 16, 0, 0); } while (0)
; #define PG8_LDA(dst, b, h) do { _Pragma("unroll") for (int m = 0; m < 4; ++m) _Pragma("unroll") for (int k = 0; k < 2; ++k) dst[m][k] = *(const LAS bf16x8*)(lds + PG8_SA(b, h) + aoff + m * 2048 + k * 1024); } while (0)
; #define PG8_LDB(dst, b, h) do { _Pragma("unroll") for (int n = 0; n < 2; ++n) _Pragma("unroll") for (int k = 0; k < 2; ++k) dst[n][k] = *(const LAS bf16x8*)(lds + PG8_SB(b, h) + boff + n * 2048 + k * 1024); } while (0)
; #define PG8_MMA(ai, bj, At, Bt) do { __builtin_amdgcn_s_setprio(1); _Pragma("unroll") for (int m = 0; m < 4; ++m) _Pragma("unroll") for (int n = 0; n < 2; ++n) _Pragma("unroll") for (int k = 0; k < 2; ++k) \
;     acc[ai][bj][m][n] = __builtin_amdgcn_mfma_f32_16x16x32_bf16(Bt[n][k], At[m][k], acc[ai][bj][m][n], 0, 0, 0); __builtin_amdgcn_s_setprio(0); } while (0)
; #define PG8_WAIT_V(n) asm volatile("s_waitcnt vmcnt(" #n ")" ::: "memory")
; #define PG8_WAIT_L(n) asm volatile("s_waitcnt lgkmcnt(" #n ")" ::: "memory")
; #define PG8_BAR __builtin_amdgcn_s_barrier()
; #define PG8_SCHED __builtin_amdgcn_sched_barrier(0)
; template <class Epi, class Sched = StaticOrder>
; DI void gemm_phase(LAS unsigned char* lds, const Gemm g, const Sched& S, const Epi& E) {
;     ...
;     for (int t = 0; t < nt; t += 2) {
;       const bool last = (t == nt - 2);
;       const char* a1 = cA + (size_t)(t + 1) * kstep;
;       const char* a2 = last ? nA : cA + (size_t)(t + 2) * kstep; const char* b2 = last ? nB : cB + (size_t)(t + 2) * kstep;
;       const char* a3 = a2 + kstep; const char* b3 = b2 + kstep;
;       PG8_LDB(B0, 0, 0); PG8_SCHED; PG8_LDA(At, 0, 0); PG8_STAGE(PG8_SA(1, 1), a1 + hstep, voffA);
;       PG8_WAIT_L(8); PG8_BAR; PG8_WAIT_L(0); PG8_MMA(0, 0, At, B0); PG8_BAR; PG8_SCHED;
;       PG8_LDB(B1, 0, 1); PG8_STAGE(PG8_SB(0, 0), b2, voffB);
;       PG8_BAR; PG8_WAIT_L(0); PG8_MMA(0, 1, At, B1); PG8_BAR;
;       PG8_LDA(At, 0, 1); PG8_STAGE(PG8_SA(0, 0), a2, voffA);
;       PG8_BAR; PG8_WAIT_L(0); PG8_MMA(1, 0, At, B0); PG8_BAR; PG8_SCHED;
;       PG8_STAGE(PG8_SB(0, 1), b2 + hstep, voffB);
;       PG8_WAIT_V(6); PG8_BAR; PG8_MMA(1, 1, At, B1); PG8_BAR;
.LBB0_961:
	s_add_u32 s20, s18, 0xffea0080
	s_addc_u32 s21, s19, -1
	s_cmpk_eq_i32 s44, 0x54
	s_cselect_b32 s23, s5, s21
	s_cselect_b32 s22, s4, s20
	s_cselect_b32 s21, s7, s43
	s_cselect_b32 s20, s6, s42
	s_add_i32 m0, s31, 0xc000
	ds_read_b128 v[144:147], v215
	ds_read_b128 v[148:151], v215 offset:1024
	ds_read_b128 v[152:155], v215 offset:2048
	ds_read_b128 v[156:159], v215 offset:3072
	ds_read_b128 v[160:163], v215 offset:4096
	ds_read_b128 v[164:167], v215 offset:5120
	ds_read_b128 v[168:171], v215 offset:6144
	ds_read_b128 v[172:175], v215 offset:7168
	global_load_lds_dwordx4 v184, s[18:19]
	s_waitcnt lgkmcnt(0)
	s_setprio 1
	s_barrier
	v_mfma_f32_16x16x32_bf16 v[124:127], v[128:131], v[144:147], v[124:127]
	v_mfma_f32_16x16x32_bf16 v[120:123], v[136:139], v[144:147], v[120:123]
	v_mfma_f32_16x16x32_bf16 v[108:111], v[128:131], v[152:155], v[108:111]
	v_mfma_f32_16x16x32_bf16 v[104:107], v[136:139], v[152:155], v[104:107]
	v_mfma_f32_16x16x32_bf16 v[92:95], v[128:131], v[160:163], v[92:95]
	v_mfma_f32_16x16x32_bf16 v[88:91], v[136:139], v[160:163], v[88:91]
	v_mfma_f32_16x16x32_bf16 v[76:79], v[128:131], v[168:171], v[76:79]
	v_mfma_f32_16x16x32_bf16 v[72:75], v[136:139], v[168:171], v[72:75]
	v_mfma_f32_16x16x32_bf16 v[124:127], v[132:135], v[148:151], v[124:127]
	v_mfma_f32_16x16x32_bf16 v[120:123], v[140:143], v[148:151], v[120:123]
	v_mfma_f32_16x16x32_bf16 v[108:111], v[132:135], v[156:159], v[108:111]
	v_mfma_f32_16x16x32_bf16 v[104:107], v[140:143], v[156:159], v[104:107]
	v_mfma_f32_16x16x32_bf16 v[92:95], v[132:135], v[164:167], v[92:95]
	v_mfma_f32_16x16x32_bf16 v[88:91], v[140:143], v[164:167], v[88:91]
	v_mfma_f32_16x16x32_bf16 v[76:79], v[132:135], v[172:175], v[76:79]
	v_mfma_f32_16x16x32_bf16 v[72:75], v[140:143], v[172:175], v[72:75]
	s_barrier
	s_setprio 0
	s_add_i32 m0, s31, 0xe000
	s_nop 0
	global_load_lds_dwordx4 v186, s[18:19]
	s_add_i32 s45, s46, s30
	s_add_u32 s98, s20, 0x80
	s_addc_u32 s99, s21, 0
	s_add_u32 s100, s22, 0x80
	s_addc_u32 s101, s23, 0
	s_mov_b32 m0, s45
	ds_read_b128 v[192:195], v216
	ds_read_b128 v[196:199], v216 offset:1024
	ds_read_b128 v[200:203], v216 offset:2048
	ds_read_b128 v[204:207], v216 offset:3072
	global_load_lds_dwordx4 v178, s[20:21]
	s_add_i32 m0, s45, 0x2000
	s_nop 0
	global_load_lds_dwordx4 v182, s[20:21]
	s_waitcnt lgkmcnt(0)
	s_setprio 1
	s_barrier
	v_mfma_f32_16x16x32_bf16 v[116:119], v[192:195], v[144:147], v[116:119]
	v_mfma_f32_16x16x32_bf16 v[112:115], v[200:203], v[144:147], v[112:115]
	v_mfma_f32_16x16x32_bf16 v[100:103], v[192:195], v[152:155], v[100:103]
	v_mfma_f32_16x16x32_bf16 v[96:99], v[200:203], v[152:155], v[96:99]
	v_mfma_f32_16x16x32_bf16 v[84:87], v[192:195], v[160:163], v[84:87]
	v_mfma_f32_16x16x32_bf16 v[80:83], v[200:203], v[160:163], v[80:83]
	v_mfma_f32_16x16x32_bf16 v[68:71], v[192:195], v[168:171], v[68:71]
	v_mfma_f32_16x16x32_bf16 v[64:67], v[200:203], v[168:171], v[64:67]
	v_mfma_f32_16x16x32_bf16 v[116:119], v[196:199], v[148:151], v[116:119]
	v_mfma_f32_16x16x32_bf16 v[112:115], v[204:207], v[148:151], v[112:115]
	v_mfma_f32_16x16x32_bf16 v[100:103], v[196:199], v[156:159], v[100:103]
	v_mfma_f32_16x16x32_bf16 v[96:99], v[204:207], v[156:159], v[96:99]
	v_mfma_f32_16x16x32_bf16 v[84:87], v[196:199], v[164:167], v[84:87]
	v_mfma_f32_16x16x32_bf16 v[80:83], v[204:207], v[164:167], v[80:83]
	v_mfma_f32_16x16x32_bf16 v[68:71], v[196:199], v[172:175], v[68:71]
	v_mfma_f32_16x16x32_bf16 v[64:67], v[204:207], v[172:175], v[64:67]
	s_barrier
	s_setprio 0
	s_mov_b32 m0, s31
	ds_read_b128 v[144:147], v215 offset:16384
	ds_read_b128 v[148:151], v215 offset:17408
	ds_read_b128 v[152:155], v215 offset:18432
	ds_read_b128 v[156:159], v215 offset:19456
	ds_read_b128 v[160:163], v215 offset:20480
	ds_read_b128 v[164:167], v215 offset:21504
	ds_read_b128 v[168:171], v215 offset:22528
	ds_read_b128 v[172:175], v215 offset:23552
	global_load_lds_dwordx4 v176, s[22:23]
	s_waitcnt vmcnt(9)
	s_waitcnt lgkmcnt(0)
	s_setprio 1
	s_barrier
	v_mfma_f32_16x16x32_bf16 v[60:63], v[128:131], v[144:147], v[60:63]
	v_mfma_f32_16x16x32_bf16 v[56:59], v[136:139], v[144:147], v[56:59]
	v_mfma_f32_16x16x32_bf16 v[44:47], v[128:131], v[152:155], v[44:47]
	v_mfma_f32_16x16x32_bf16 v[40:43], v[136:139], v[152:155], v[40:43]
	v_mfma_f32_16x16x32_bf16 v[28:31], v[128:131], v[160:163], v[28:31]
	v_mfma_f32_16x16x32_bf16 v[24:27], v[136:139], v[160:163], v[24:27]
	v_mfma_f32_16x16x32_bf16 v[12:15], v[128:131], v[168:171], v[12:15]
	v_mfma_f32_16x16x32_bf16 v[8:11], v[136:139], v[168:171], v[8:11]
	v_mfma_f32_16x16x32_bf16 v[60:63], v[132:135], v[148:151], v[60:63]
	v_mfma_f32_16x16x32_bf16 v[56:59], v[140:143], v[148:151], v[56:59]
	v_mfma_f32_16x16x32_bf16 v[44:47], v[132:135], v[156:159], v[44:47]
	v_mfma_f32_16x16x32_bf16 v[40:43], v[140:143], v[156:159], v[40:43]
	v_mfma_f32_16x16x32_bf16 v[28:31], v[132:135], v[164:167], v[28:31]
	v_mfma_f32_16x16x32_bf16 v[24:27], v[140:143], v[164:167], v[24:27]
	v_mfma_f32_16x16x32_bf16 v[12:15], v[132:135], v[172:175], v[12:15]
	v_mfma_f32_16x16x32_bf16 v[8:11], v[140:143], v[172:175], v[8:11]
	s_barrier
	s_setprio 0
	s_mov_b32 m0, s33
	s_nop 0
	global_load_lds_dwordx4 v180, s[22:23]
	s_add_u32 s52, s20, 0x160000
	s_addc_u32 s53, s21, 0
	s_add_i32 s45, s47, s30
	s_mov_b32 m0, s45
	s_nop 0
	global_load_lds_dwordx4 v178, s[52:53]
	s_add_i32 m0, s45, 0x2000
	s_nop 0
	global_load_lds_dwordx4 v182, s[52:53]
	s_add_i32 s45, 0, 0x18000
	v_add_u32_e32 v140, s45, v212
	ds_read_b128 v[128:131], v140
	ds_read_b128 v[132:135], v140 offset:1024
	ds_read_b128 v[136:139], v140 offset:2048
	ds_read_b128 v[140:143], v140 offset:3072
	s_waitcnt vmcnt(6)
	s_setprio 1
	s_barrier
; #define PG8_STAGE(bufoff, gbase, voff) do { _Pragma("unroll") for (int _i = 0; _i < 2; ++_i) \
;     __builtin_amdgcn_global_load_lds((const unsigned*)((const char*)(gbase) + (voff)[_i]), (LAS unsigned*)(lds + (bufoff) + ldsw + _i * 8192), 16, 0, 0); } while (0)
; #define PG8_LDA(dst, b, h) do { _Pragma("unroll") for (int m = 0; m < 4; ++m) _Pragma("unroll") for (int k = 0; k < 2; ++k) dst[m][k] = *(const LAS bf16x8*)(lds + PG8_SA(b, h) + aoff + m * 2048 + k * 1024); } while (0)
; #define PG8_LDB(dst, b, h) do { _Pragma("unroll") for (int n = 0; n < 2; ++n) _Pragma("unroll") for (int k = 0; k < 2; ++k) dst[n][k] = *(const LAS bf16x8*)(lds + PG8_SB(b, h) + boff + n * 2048 + k * 1024); } while (0)
; #define PG8_MMA(ai, bj, At, Bt) do { __builtin_amdgcn_s_setprio(1); _Pragma("unroll") for (int m = 0; m < 4; ++m) _Pragma("unroll") for (int n = 0; n < 2; ++n) _Pragma("unroll") for (int k = 0; k < 2; ++k) \
;     acc[ai][bj][m][n] = __builtin_amdgcn_mfma_f32_16x16x32_bf16(Bt[n][k], At[m][k], acc[ai][bj][m][n], 0, 0, 0); __builtin_amdgcn_s_setprio(0); } while (0)
; #define PG8_WAIT_V(n) asm volatile("s_waitcnt vmcnt(" #n ")" ::: "memory")
; #define PG8_WAIT_L(n) asm volatile("s_waitcnt lgkmcnt(" #n ")" ::: "memory")
; #define PG8_BAR __builtin_amdgcn_s_barrier()
; #define PG8_SCHED __builtin_amdgcn_sched_barrier(0)
; template <class Epi, class Sched = StaticOrder>
; DI void gemm_phase(LAS unsigned char* lds, const Gemm g, const Sched& S, const Epi& E) {
;     ...
;       PG8_WAIT_V(6); PG8_BAR; PG8_MMA(1, 1, At, B1); PG8_BAR;
;       PG8_LDB(B0, 1, 0); PG8_SCHED; PG8_LDA(At, 1, 0); PG8_STAGE(PG8_SA(0, 1), a2 + hstep, voffA);
;       PG8_WAIT_L(8); PG8_BAR; PG8_WAIT_L(0); PG8_MMA(0, 0, At, B0); PG8_BAR; PG8_SCHED;
;       PG8_LDB(B1, 1, 1); PG8_STAGE(PG8_SB(1, 0), b3, voffB);
;       PG8_BAR; PG8_WAIT_L(0); PG8_MMA(0, 1, At, B1); PG8_BAR;
;       PG8_LDA(At, 1, 1); PG8_STAGE(PG8_SA(1, 0), a3, voffA);
;       PG8_BAR; PG8_WAIT_L(0); PG8_MMA(1, 0, At, B0); PG8_BAR; PG8_SCHED;
;       PG8_STAGE(PG8_SB(1, 1), b3 + hstep, voffB);
;       PG8_WAIT_V(6); PG8_BAR; PG8_MMA(1, 1, At, B1); PG8_BAR;
	v_mfma_f32_16x16x32_bf16 v[52:55], v[192:195], v[144:147], v[52:55]
	v_mfma_f32_16x16x32_bf16 v[48:51], v[200:203], v[144:147], v[48:51]
	v_mfma_f32_16x16x32_bf16 v[36:39], v[192:195], v[152:155], v[36:39]
	v_mfma_f32_16x16x32_bf16 v[32:35], v[200:203], v[152:155], v[32:35]
	v_mfma_f32_16x16x32_bf16 v[20:23], v[192:195], v[160:163], v[20:23]
	v_mfma_f32_16x16x32_bf16 v[16:19], v[200:203], v[160:163], v[16:19]
	v_mfma_f32_16x16x32_bf16 v[4:7], v[192:195], v[168:171], v[4:7]
	v_mfma_f32_16x16x32_bf16 v[0:3], v[200:203], v[168:171], v[0:3]
	v_mfma_f32_16x16x32_bf16 v[52:55], v[196:199], v[148:151], v[52:55]
	v_mfma_f32_16x16x32_bf16 v[48:51], v[204:207], v[148:151], v[48:51]
	v_mfma_f32_16x16x32_bf16 v[36:39], v[196:199], v[156:159], v[36:39]
	v_mfma_f32_16x16x32_bf16 v[32:35], v[204:207], v[156:159], v[32:35]
	v_mfma_f32_16x16x32_bf16 v[20:23], v[196:199], v[164:167], v[20:23]
	v_mfma_f32_16x16x32_bf16 v[16:19], v[204:207], v[164:167], v[16:19]
	v_mfma_f32_16x16x32_bf16 v[4:7], v[196:199], v[172:175], v[4:7]
	v_mfma_f32_16x16x32_bf16 v[0:3], v[204:207], v[172:175], v[0:3]
	s_barrier
	s_setprio 0
	s_add_u32 s22, s22, 0x160000
	s_addc_u32 s23, s23, 0
	s_mov_b32 m0, s34
	ds_read_b128 v[144:147], v215 offset:32768
	ds_read_b128 v[148:151], v215 offset:33792
	ds_read_b128 v[152:155], v215 offset:34816
	ds_read_b128 v[156:159], v215 offset:35840
	ds_read_b128 v[160:163], v215 offset:36864
	ds_read_b128 v[164:167], v215 offset:37888
	ds_read_b128 v[168:171], v215 offset:38912
	ds_read_b128 v[172:175], v215 offset:39936
	global_load_lds_dwordx4 v176, s[22:23]
	s_waitcnt lgkmcnt(0)
	s_setprio 1
	s_barrier
	v_mfma_f32_16x16x32_bf16 v[124:127], v[128:131], v[144:147], v[124:127]
	v_mfma_f32_16x16x32_bf16 v[120:123], v[136:139], v[144:147], v[120:123]
	v_mfma_f32_16x16x32_bf16 v[108:111], v[128:131], v[152:155], v[108:111]
	v_mfma_f32_16x16x32_bf16 v[104:107], v[136:139], v[152:155], v[104:107]
	v_mfma_f32_16x16x32_bf16 v[92:95], v[128:131], v[160:163], v[92:95]
	v_mfma_f32_16x16x32_bf16 v[88:91], v[136:139], v[160:163], v[88:91]
	v_mfma_f32_16x16x32_bf16 v[76:79], v[128:131], v[168:171], v[76:79]
	v_mfma_f32_16x16x32_bf16 v[72:75], v[136:139], v[168:171], v[72:75]
	v_mfma_f32_16x16x32_bf16 v[124:127], v[132:135], v[148:151], v[124:127]
	v_mfma_f32_16x16x32_bf16 v[120:123], v[140:143], v[148:151], v[120:123]
	v_mfma_f32_16x16x32_bf16 v[108:111], v[132:135], v[156:159], v[108:111]
	v_mfma_f32_16x16x32_bf16 v[104:107], v[140:143], v[156:159], v[104:107]
	v_mfma_f32_16x16x32_bf16 v[92:95], v[132:135], v[164:167], v[92:95]
	v_mfma_f32_16x16x32_bf16 v[88:91], v[140:143], v[164:167], v[88:91]
	v_mfma_f32_16x16x32_bf16 v[76:79], v[132:135], v[172:175], v[76:79]
	v_mfma_f32_16x16x32_bf16 v[72:75], v[140:143], v[172:175], v[72:75]
	s_barrier
	s_setprio 0
	s_mov_b32 m0, s35
	s_nop 0
	global_load_lds_dwordx4 v180, s[22:23]
	s_add_i32 s22, 0, 0x1c000
	s_add_i32 s23, s45, s30
	v_add_u32_e32 v204, s22, v212
	s_mov_b32 m0, s23
	ds_read_b128 v[192:195], v204
	ds_read_b128 v[196:199], v204 offset:1024
	ds_read_b128 v[200:203], v204 offset:2048
	ds_read_b128 v[204:207], v204 offset:3072
	global_load_lds_dwordx4 v178, s[98:99]
	s_add_i32 m0, s23, 0x2000
	s_nop 0
	global_load_lds_dwordx4 v182, s[98:99]
	s_waitcnt lgkmcnt(0)
	s_setprio 1
	s_barrier
	v_mfma_f32_16x16x32_bf16 v[116:119], v[192:195], v[144:147], v[116:119]
	v_mfma_f32_16x16x32_bf16 v[112:115], v[200:203], v[144:147], v[112:115]
	v_mfma_f32_16x16x32_bf16 v[100:103], v[192:195], v[152:155], v[100:103]
	v_mfma_f32_16x16x32_bf16 v[96:99], v[200:203], v[152:155], v[96:99]
	v_mfma_f32_16x16x32_bf16 v[84:87], v[192:195], v[160:163], v[84:87]
	v_mfma_f32_16x16x32_bf16 v[80:83], v[200:203], v[160:163], v[80:83]
	v_mfma_f32_16x16x32_bf16 v[68:71], v[192:195], v[168:171], v[68:71]
	v_mfma_f32_16x16x32_bf16 v[64:67], v[200:203], v[168:171], v[64:67]
	v_mfma_f32_16x16x32_bf16 v[116:119], v[196:199], v[148:151], v[116:119]
	v_mfma_f32_16x16x32_bf16 v[112:115], v[204:207], v[148:151], v[112:115]
	v_mfma_f32_16x16x32_bf16 v[100:103], v[196:199], v[156:159], v[100:103]
	v_mfma_f32_16x16x32_bf16 v[96:99], v[204:207], v[156:159], v[96:99]
	v_mfma_f32_16x16x32_bf16 v[84:87], v[196:199], v[164:167], v[84:87]
	v_mfma_f32_16x16x32_bf16 v[80:83], v[204:207], v[164:167], v[80:83]
	v_mfma_f32_16x16x32_bf16 v[68:71], v[196:199], v[172:175], v[68:71]
	v_mfma_f32_16x16x32_bf16 v[64:67], v[204:207], v[172:175], v[64:67]
	s_barrier
	s_setprio 0
	s_mov_b32 m0, s37
	ds_read_b128 v[144:147], v215 offset:49152
	ds_read_b128 v[148:151], v215 offset:50176
	ds_read_b128 v[152:155], v215 offset:51200
	ds_read_b128 v[156:159], v215 offset:52224
	ds_read_b128 v[160:163], v215 offset:53248
	ds_read_b128 v[164:167], v215 offset:54272
	ds_read_b128 v[168:171], v215 offset:55296
	ds_read_b128 v[172:175], v215 offset:56320
	global_load_lds_dwordx4 v176, s[100:101]
	s_waitcnt vmcnt(9)
	s_waitcnt lgkmcnt(0)
	s_setprio 1
	s_barrier
	v_mfma_f32_16x16x32_bf16 v[60:63], v[128:131], v[144:147], v[60:63]
	v_mfma_f32_16x16x32_bf16 v[56:59], v[136:139], v[144:147], v[56:59]
	v_mfma_f32_16x16x32_bf16 v[44:47], v[128:131], v[152:155], v[44:47]
	v_mfma_f32_16x16x32_bf16 v[40:43], v[136:139], v[152:155], v[40:43]
	v_mfma_f32_16x16x32_bf16 v[28:31], v[128:131], v[160:163], v[28:31]
	v_mfma_f32_16x16x32_bf16 v[24:27], v[136:139], v[160:163], v[24:27]
	v_mfma_f32_16x16x32_bf16 v[12:15], v[128:131], v[168:171], v[12:15]
	v_mfma_f32_16x16x32_bf16 v[8:11], v[136:139], v[168:171], v[8:11]
	v_mfma_f32_16x16x32_bf16 v[60:63], v[132:135], v[148:151], v[60:63]
	v_mfma_f32_16x16x32_bf16 v[56:59], v[140:143], v[148:151], v[56:59]
	v_mfma_f32_16x16x32_bf16 v[44:47], v[132:135], v[156:159], v[44:47]
	v_mfma_f32_16x16x32_bf16 v[40:43], v[140:143], v[156:159], v[40:43]
	v_mfma_f32_16x16x32_bf16 v[28:31], v[132:135], v[164:167], v[28:31]
	v_mfma_f32_16x16x32_bf16 v[24:27], v[140:143], v[164:167], v[24:27]
	v_mfma_f32_16x16x32_bf16 v[12:15], v[132:135], v[172:175], v[12:15]
	v_mfma_f32_16x16x32_bf16 v[8:11], v[140:143], v[172:175], v[8:11]
	s_barrier
; DI unsigned pack2(float lo, float hi) { f32x2 v = {lo, hi}; bf16v2 r = __builtin_convertvector(v, bf16v2); return __builtin_bit_cast(unsigned, r); }
; #define PG8_STAGE(bufoff, gbase, voff) do { _Pragma("unroll") for (int _i = 0; _i < 2; ++_i) \
;     __builtin_amdgcn_global_load_lds((const unsigned*)((const char*)(gbase) + (voff)[_i]), (LAS unsigned*)(lds + (bufoff) + ldsw + _i * 8192), 16, 0, 0); } while (0)
; #define PG8_WAIT_V(n) asm volatile("s_waitcnt vmcnt(" #n ")" ::: "memory")
;   DI void operator()(const f32x4 (&acc)[2][2][4][2], const Unit& u, int wr, int wc, int fr, int fq) const {
;     const int row0 = u.pm * BM + wr * 64 + fr, col0 = u.pn * BM + wc * 32 + 8 * fq;
; #pragma unroll
;     for (int ai = 0; ai < 2; ++ai) {
;       f32x4 bv[4][2][2];
; #pragma unroll
;       for (int m = 0; m < 4; ++m)
; #pragma unroll
;         for (int bj = 0; bj < 2; ++bj) {
;           const float* bp = base + (size_t)(row0 + ai * HALF + m * 16) * 2048 + col0 + bj * HALF;
;           bv[m][bj][0] = *(const f32x4*)bp; bv[m][bj][1] = *(const f32x4*)(bp + 4);
;         }
; #pragma unroll
;       for (int m = 0; m < 4; ++m) {
;         const int row = row0 + ai * HALF + m * 16;
;         const size_t off = (size_t)row * 2048 + col0;
;         float ss = 0.f;
; #pragma unroll
;         for (int bj = 0; bj < 2; ++bj) {
;           const f32x4 v0 = acc[ai][bj][m][0] + bv[m][bj][0], v1 = acc[ai][bj][m][1] + bv[m][bj][1];
;           *(f32x4*)(C + off + bj * HALF) = v0; *(f32x4*)(C + off + bj * HALF + 4) = v1;
;           if (xb) {
;             u32x4 w; w.x = pack2(v0[0], v0[1]); w.y = pack2(v0[2], v0[3]); w.z = pack2(v1[0], v1[1]); w.w = pack2(v1[2], v1[3]);
;             *(u32x4*)(xb + off + bj * HALF) = w;
;             ss += v0[0] * v0[0] + v0[1] * v0[1] + v0[2] * v0[2] + v0[3] * v0[3] + v1[0] * v1[0] + v1[1] * v1[1] + v1[2] * v1[2] + v1[3] * v1[3];
;           }
;         }
;         if (xb) {
;           ss += __shfl_xor(ss, 16); ss += __shfl_xor(ss, 32);
;           if (fq == 0) ssq[(size_t)row * 32 + u.pn * 4 + wc] = ss;
; template <class Epi, class Sched = StaticOrder>
; DI void gemm_phase(LAS unsigned char* lds, const Gemm g, const Sched& S, const Epi& E) {
;     ...
;       PG8_STAGE(PG8_SB(1, 1), b3 + hstep, voffB);
;       PG8_WAIT_V(6); PG8_BAR; PG8_MMA(1, 1, At, B1); PG8_BAR;
;     }
;     E(acc, cur, wr, wc, fr, fq);
	s_setprio 0
	s_mov_b32 m0, s38
	s_nop 0
	global_load_lds_dwordx4 v180, s[100:101]
	s_add_u32 s20, s20, 0x160080
	s_addc_u32 s21, s21, 0
	s_add_i32 s22, s22, s30
	s_mov_b32 m0, s22
	s_nop 0
	global_load_lds_dwordx4 v178, s[20:21]
	s_add_i32 m0, s22, 0x2000
	s_nop 0
	global_load_lds_dwordx4 v182, s[20:21]
	ds_read_b128 v[128:131], v214
	ds_read_b128 v[132:135], v214 offset:1024
	ds_read_b128 v[136:139], v214 offset:2048
	ds_read_b128 v[140:143], v214 offset:3072
	s_waitcnt vmcnt(6)
	s_setprio 1
	s_barrier
	v_mfma_f32_16x16x32_bf16 v[52:55], v[192:195], v[144:147], v[52:55]
	v_mfma_f32_16x16x32_bf16 v[48:51], v[200:203], v[144:147], v[48:51]
	v_mfma_f32_16x16x32_bf16 v[36:39], v[192:195], v[152:155], v[36:39]
	v_mfma_f32_16x16x32_bf16 v[32:35], v[200:203], v[152:155], v[32:35]
	v_mfma_f32_16x16x32_bf16 v[20:23], v[192:195], v[160:163], v[20:23]
	v_mfma_f32_16x16x32_bf16 v[16:19], v[200:203], v[160:163], v[16:19]
	v_mfma_f32_16x16x32_bf16 v[4:7], v[192:195], v[168:171], v[4:7]
	v_mfma_f32_16x16x32_bf16 v[0:3], v[200:203], v[168:171], v[0:3]
	v_mfma_f32_16x16x32_bf16 v[52:55], v[196:199], v[148:151], v[52:55]
	v_mfma_f32_16x16x32_bf16 v[48:51], v[204:207], v[148:151], v[48:51]
	v_mfma_f32_16x16x32_bf16 v[36:39], v[196:199], v[156:159], v[36:39]
	v_mfma_f32_16x16x32_bf16 v[32:35], v[204:207], v[156:159], v[32:35]
	v_mfma_f32_16x16x32_bf16 v[20:23], v[196:199], v[164:167], v[20:23]
	v_mfma_f32_16x16x32_bf16 v[16:19], v[204:207], v[164:167], v[16:19]
	v_mfma_f32_16x16x32_bf16 v[4:7], v[196:199], v[172:175], v[4:7]
	v_mfma_f32_16x16x32_bf16 v[0:3], v[204:207], v[172:175], v[0:3]
	s_add_i32 s44, s44, 2
	s_add_u32 s18, s18, 0x100
	s_addc_u32 s19, s19, 0
	s_add_u32 s42, s42, 0x100
	s_addc_u32 s43, s43, 0
	s_cmpk_gt_u32 s44, 0x55
	s_barrier
	s_setprio 0
	s_cbranch_scc0 .LBB0_961
	s_waitcnt lgkmcnt(0)
	v_lshl_add_u32 v194, s51, 8, v211
	v_lshl_or_b32 v192, s2, 8, v213
	v_readlane_b32 s52, v243, 3
	v_ashrrev_i32_e32 v193, 31, v192
	v_readlane_b32 s66, v243, 17
	v_readlane_b32 s67, v243, 18
	v_ashrrev_i32_e32 v195, 31, v194
	v_lshlrev_b64 v[128:129], 13, v[194:195]
	v_lshl_add_u64 v[196:197], v[192:193], 2, s[66:67]
	v_lshl_add_u64 v[236:237], v[196:197], 0, v[128:129]
	global_load_dwordx4 v[220:223], v[236:237], off
	global_load_dwordx4 v[224:227], v[236:237], off offset:16
	global_load_dwordx4 v[228:231], v[236:237], off offset:512
	global_load_dwordx4 v[232:235], v[236:237], off offset:528
	v_or_b32_e32 v206, 16, v194
	v_or_b32_e32 v202, 32, v194
	v_or_b32_e32 v198, 48, v194
	v_ashrrev_i32_e32 v207, 31, v206
	v_ashrrev_i32_e32 v203, 31, v202
	v_ashrrev_i32_e32 v199, 31, v198
	v_lshlrev_b64 v[128:129], 13, v[206:207]
	v_lshlrev_b64 v[130:131], 13, v[202:203]
	v_lshlrev_b64 v[132:133], 13, v[198:199]
	v_lshl_add_u64 v[208:209], v[196:197], 0, v[128:129]
	v_lshl_add_u64 v[204:205], v[196:197], 0, v[130:131]
	v_lshl_add_u64 v[200:201], v[196:197], 0, v[132:133]
	global_load_dwordx4 v[168:171], v[208:209], off offset:16
	global_load_dwordx4 v[172:175], v[208:209], off
	global_load_dwordx4 v[160:163], v[208:209], off offset:528
	global_load_dwordx4 v[164:167], v[208:209], off offset:512
	global_load_dwordx4 v[152:155], v[204:205], off offset:16
	global_load_dwordx4 v[156:159], v[204:205], off
	global_load_dwordx4 v[144:147], v[204:205], off offset:528
	global_load_dwordx4 v[148:151], v[204:205], off offset:512
	global_load_dwordx4 v[136:139], v[200:201], off offset:16
	global_load_dwordx4 v[140:143], v[200:201], off
	global_load_dwordx4 v[128:131], v[200:201], off offset:528
	global_load_dwordx4 v[132:135], v[200:201], off offset:512
	v_and_b32_e32 v218, 64, v217
	v_xor_b32_e32 v238, 16, v217
	v_add_u32_e32 v240, 64, v218
	v_xor_b32_e32 v239, 32, v217
	v_cmp_lt_i32_e32 vcc, v238, v240
	v_lshlrev_b64 v[218:219], 11, v[194:195]
	s_lshl_b32 s18, s2, 2
	v_cndmask_b32_e32 v241, v217, v238, vcc
	v_cmp_lt_i32_e32 vcc, v239, v240
	s_ashr_i32 s19, s18, 31
	v_readlane_b32 s53, v243, 4
	v_cndmask_b32_e32 v240, v217, v239, vcc
	v_lshl_add_u64 v[238:239], v[218:219], 0, v[192:193]
	v_lshlrev_b32_e32 v218, 2, v241
	v_lshl_add_u64 v[238:239], v[238:239], 1, s[12:13]
	v_readlane_b32 s54, v243, 5
	v_readlane_b32 s55, v243, 6
	v_readlane_b32 s56, v243, 7
	v_readlane_b32 s57, v243, 8
	v_readlane_b32 s58, v243, 9
	v_readlane_b32 s59, v243, 10
	v_readlane_b32 s60, v243, 11
	v_readlane_b32 s61, v243, 12
	v_readlane_b32 s62, v243, 13
	v_readlane_b32 s63, v243, 14
	v_readlane_b32 s64, v243, 15
	v_readlane_b32 s65, v243, 16
	s_waitcnt vmcnt(0)
	v_pk_add_f32 v[126:127], v[126:127], v[222:223]
	v_pk_add_f32 v[124:125], v[124:125], v[220:221]
	v_pk_add_f32 v[116:117], v[116:117], v[228:229]
	v_pk_add_f32 v[122:123], v[122:123], v[226:227]
	v_pk_add_f32 v[120:121], v[120:121], v[224:225]
	v_pk_add_f32 v[220:221], v[112:113], v[232:233]
	global_store_dwordx4 v[236:237], v[124:127], off
	global_store_dwordx4 v[236:237], v[120:123], off offset:16
	v_cvt_pk_bf16_f32 v112, v124, v125
	v_mul_f32_e32 v125, v125, v125
	v_mul_f32_e32 v219, v117, v117
	v_pk_add_f32 v[118:119], v[118:119], v[230:231]
	v_fmac_f32_e32 v125, v124, v124
	v_fmac_f32_e32 v219, v116, v116
	v_fmac_f32_e32 v125, v126, v126
	v_fmac_f32_e32 v219, v118, v118
	v_fmac_f32_e32 v125, v127, v127
	v_fmac_f32_e32 v219, v119, v119
	v_fmac_f32_e32 v125, v120, v120
	v_fmac_f32_e32 v219, v220, v220
	v_pk_add_f32 v[222:223], v[114:115], v[234:235]
	v_fmac_f32_e32 v125, v121, v121
	v_fmac_f32_e32 v219, v221, v221
	v_fmac_f32_e32 v125, v122, v122
	v_fmac_f32_e32 v219, v222, v222
	v_fmac_f32_e32 v125, v123, v123
	v_fmac_f32_e32 v219, v223, v223
	v_cvt_pk_bf16_f32 v114, v120, v121
	v_add_f32_e32 v121, v125, v219
	v_cvt_pk_bf16_f32 v115, v122, v123
	ds_bpermute_b32 v122, v218, v121
	v_cvt_pk_bf16_f32 v113, v126, v127
	global_store_dwordx4 v[238:239], v[112:115], off
	global_store_dwordx4 v[236:237], v[116:119], off offset:512
	global_store_dwordx4 v[236:237], v[220:223], off offset:528
	v_lshlrev_b32_e32 v126, 2, v240
	v_cvt_pk_bf16_f32 v120, v116, v117
	s_waitcnt lgkmcnt(0)
	v_add_f32_e32 v112, v121, v122
	ds_bpermute_b32 v113, v126, v112
	v_cvt_pk_bf16_f32 v121, v118, v119
	v_cvt_pk_bf16_f32 v122, v220, v221
	v_cvt_pk_bf16_f32 v123, v222, v223
	global_store_dwordx4 v[238:239], v[120:123], off offset:256
	s_and_saveexec_b64 s[20:21], s[0:1]
	s_cbranch_execz .LBB0_964
	s_waitcnt lgkmcnt(0)
	v_add_f32_e32 v114, v112, v113
	v_lshlrev_b64 v[112:113], 7, v[194:195]
	v_lshl_add_u64 v[112:113], s[14:15], 0, v[112:113]
	v_lshl_add_u64 v[112:113], s[18:19], 2, v[112:113]
	s_lshl_b32 s2, s36, 2
	v_lshl_add_u64 v[112:113], v[112:113], 0, s[2:3]
	global_store_dword v[112:113], v114, off

; #define PG8_STAGE(bufoff, gbase, voff) do { _Pragma("unroll") for (int _i = 0; _i < 2; ++_i) \
;     __builtin_amdgcn_global_load_lds((const unsigned*)((const char*)(gbase) + (voff)[_i]), (LAS unsigned*)(lds + (bufoff) + ldsw + _i * 8192), 16, 0, 0); } while (0)
; #define PG8_LDA(dst, b, h) do { _Pragma("unroll") for (int m = 0; m < 4; ++m) _Pragma("unroll") for (int k = 0; k < 2; ++k) dst[m][k] = *(const LAS bf16x8*)(lds + PG8_SA(b, h) + aoff + m * 2048 + k * 1024); } while (0)
; #define PG8_LDB(dst, b, h) do { _Pragma("unroll") for (int n = 0; n < 2; ++n) _Pragma("unroll") for (int k = 0; k < 2; ++k) dst[n][k] = *(const LAS bf16x8*)(lds + PG8_SB(b, h) + boff + n * 2048 + k * 1024); } while (0)
; #define PG8_WAIT_V(n) asm volatile("s_waitcnt vmcnt(" #n ")" ::: "memory")
; template <class Epi, class Sched = StaticOrder>
; DI void gemm_phase(LAS unsigned char* lds, const Gemm g, const Sched& S, const Epi& E) {
;     ...
;     for (int t = 0; t < nt; t += 2) {
;       const bool last = (t == nt - 2);
;       const char* a1 = cA + (size_t)(t + 1) * kstep;
;       const char* a2 = last ? nA : cA + (size_t)(t + 2) * kstep; const char* b2 = last ? nB : cB + (size_t)(t + 2) * kstep;
;       const char* a3 = a2 + kstep; const char* b3 = b2 + kstep;
;       PG8_LDB(B0, 0, 0); PG8_SCHED; PG8_LDA(At, 0, 0); PG8_STAGE(PG8_SA(1, 1), a1 + hstep, voffA);
;       PG8_WAIT_L(8); PG8_BAR; PG8_WAIT_L(0); PG8_MMA(0, 0, At, B0); PG8_BAR; PG8_SCHED;
;       PG8_LDB(B1, 0, 1); PG8_STAGE(PG8_SB(0, 0), b2, voffB);
;       PG8_BAR; PG8_WAIT_L(0); PG8_MMA(0, 1, At, B1); PG8_BAR;
;       PG8_LDA(At, 0, 1); PG8_STAGE(PG8_SA(0, 0), a2, voffA);
;       PG8_BAR; PG8_WAIT_L(0); PG8_MMA(1, 0, At, B0); PG8_BAR; PG8_SCHED;
;       PG8_STAGE(PG8_SB(0, 1), b2 + hstep, voffB);
;       PG8_WAIT_V(6); PG8_BAR; PG8_MMA(1, 1, At, B1); PG8_BAR;
;       PG8_LDB(B0, 1, 0); PG8_SCHED; PG8_LDA(At, 1, 0); PG8_STAGE(PG8_SA(0, 1), a2 + hstep, voffA);
;       PG8_WAIT_L(8); PG8_BAR; PG8_WAIT_L(0); PG8_MMA(0, 0, At, B0); PG8_BAR; PG8_SCHED;
;       PG8_LDB(B1, 1, 1); PG8_STAGE(PG8_SB(1, 0), b3, voffB);
;       PG8_BAR; PG8_WAIT_L(0); PG8_MMA(0, 1, At, B1); PG8_BAR;
;       PG8_LDA(At, 1, 1); PG8_STAGE(PG8_SA(1, 0), a3, voffA);
;       PG8_BAR; PG8_WAIT_L(0); PG8_MMA(1, 0, At, B0); PG8_BAR; PG8_SCHED;
;       PG8_STAGE(PG8_SB(1, 1), b3 + hstep, voffB);
;       PG8_WAIT_V(6); PG8_BAR; PG8_MMA(1, 1, At, B1); PG8_BAR;
.LBB0_1052:
	s_add_u32 s12, s10, 0xfff80080
	s_addc_u32 s13, s11, -1
	s_cmp_eq_u32 s52, 28
	s_cselect_b32 s65, s41, s13
	s_cselect_b32 s64, s42, s12
	s_cselect_b32 s13, s43, s49
	s_cselect_b32 s12, s44, s45
	s_add_i32 m0, s61, 0xc000
	ds_read_b128 v[144:147], v204
	ds_read_b128 v[148:151], v204 offset:1024
	ds_read_b128 v[152:155], v204 offset:2048
	ds_read_b128 v[156:159], v204 offset:3072
	ds_read_b128 v[178:181], v204 offset:4096
	ds_read_b128 v[182:185], v204 offset:5120
	ds_read_b128 v[186:189], v204 offset:6144
	ds_read_b128 v[190:193], v204 offset:7168
	global_load_lds_dwordx4 v172, s[10:11]
	s_waitcnt lgkmcnt(0)
	s_setprio 1
	s_barrier
	v_mfma_f32_16x16x32_bf16 v[124:127], v[128:131], v[144:147], v[124:127]
	v_mfma_f32_16x16x32_bf16 v[120:123], v[136:139], v[144:147], v[120:123]
	v_mfma_f32_16x16x32_bf16 v[116:119], v[128:131], v[152:155], v[116:119]
	v_mfma_f32_16x16x32_bf16 v[104:107], v[136:139], v[152:155], v[104:107]
	v_mfma_f32_16x16x32_bf16 v[92:95], v[128:131], v[178:181], v[92:95]
	v_mfma_f32_16x16x32_bf16 v[88:91], v[136:139], v[178:181], v[88:91]
	v_mfma_f32_16x16x32_bf16 v[84:87], v[128:131], v[186:189], v[84:87]
	v_mfma_f32_16x16x32_bf16 v[72:75], v[136:139], v[186:189], v[72:75]
	v_mfma_f32_16x16x32_bf16 v[124:127], v[132:135], v[148:151], v[124:127]
	v_mfma_f32_16x16x32_bf16 v[120:123], v[140:143], v[148:151], v[120:123]
	v_mfma_f32_16x16x32_bf16 v[116:119], v[132:135], v[156:159], v[116:119]
	v_mfma_f32_16x16x32_bf16 v[104:107], v[140:143], v[156:159], v[104:107]
	v_mfma_f32_16x16x32_bf16 v[92:95], v[132:135], v[182:185], v[92:95]
	v_mfma_f32_16x16x32_bf16 v[88:91], v[140:143], v[182:185], v[88:91]
	v_mfma_f32_16x16x32_bf16 v[84:87], v[132:135], v[190:193], v[84:87]
	v_mfma_f32_16x16x32_bf16 v[72:75], v[140:143], v[190:193], v[72:75]
	s_barrier
	s_setprio 0
	s_add_i32 m0, s61, 0xe000
	s_nop 0
	global_load_lds_dwordx4 v174, s[10:11]
	s_add_i32 s53, s80, s70
	s_add_u32 s98, s12, 0x80
	s_addc_u32 s99, s13, 0
	s_add_u32 s100, s64, 0x80
	s_addc_u32 s101, s65, 0
	s_mov_b32 m0, s53
	ds_read_b128 v[194:197], v205
	ds_read_b128 v[212:215], v205 offset:1024
	ds_read_b128 v[216:219], v205 offset:2048
	ds_read_b128 v[220:223], v205 offset:3072
	global_load_lds_dwordx4 v162, s[12:13]
	s_add_i32 m0, s53, 0x2000
	s_nop 0
	global_load_lds_dwordx4 v166, s[12:13]
	s_waitcnt lgkmcnt(0)
	s_setprio 1
	s_barrier
	v_mfma_f32_16x16x32_bf16 v[112:115], v[194:197], v[144:147], v[112:115]
	v_mfma_f32_16x16x32_bf16 v[108:111], v[216:219], v[144:147], v[108:111]
	v_mfma_f32_16x16x32_bf16 v[100:103], v[194:197], v[152:155], v[100:103]
	v_mfma_f32_16x16x32_bf16 v[96:99], v[216:219], v[152:155], v[96:99]
	v_mfma_f32_16x16x32_bf16 v[80:83], v[194:197], v[178:181], v[80:83]
	v_mfma_f32_16x16x32_bf16 v[76:79], v[216:219], v[178:181], v[76:79]
	v_mfma_f32_16x16x32_bf16 v[68:71], v[194:197], v[186:189], v[68:71]
	v_mfma_f32_16x16x32_bf16 v[64:67], v[216:219], v[186:189], v[64:67]
	v_mfma_f32_16x16x32_bf16 v[112:115], v[212:215], v[148:151], v[112:115]
	v_mfma_f32_16x16x32_bf16 v[108:111], v[220:223], v[148:151], v[108:111]
	v_mfma_f32_16x16x32_bf16 v[100:103], v[212:215], v[156:159], v[100:103]
	v_mfma_f32_16x16x32_bf16 v[96:99], v[220:223], v[156:159], v[96:99]
	v_mfma_f32_16x16x32_bf16 v[80:83], v[212:215], v[182:185], v[80:83]
	v_mfma_f32_16x16x32_bf16 v[76:79], v[220:223], v[182:185], v[76:79]
	v_mfma_f32_16x16x32_bf16 v[68:71], v[212:215], v[190:193], v[68:71]
	v_mfma_f32_16x16x32_bf16 v[64:67], v[220:223], v[190:193], v[64:67]
	s_barrier
	s_setprio 0
	s_mov_b32 m0, s61
	ds_read_b128 v[144:147], v204 offset:16384
	ds_read_b128 v[148:151], v204 offset:17408
	ds_read_b128 v[152:155], v204 offset:18432
	ds_read_b128 v[156:159], v204 offset:19456
	ds_read_b128 v[178:181], v204 offset:20480
	ds_read_b128 v[182:185], v204 offset:21504
	ds_read_b128 v[186:189], v204 offset:22528
	ds_read_b128 v[190:193], v204 offset:23552
	global_load_lds_dwordx4 v160, s[64:65]
	s_waitcnt vmcnt(9)
	s_waitcnt lgkmcnt(0)
	s_setprio 1
	s_barrier
	v_mfma_f32_16x16x32_bf16 v[60:63], v[128:131], v[144:147], v[60:63]
	v_mfma_f32_16x16x32_bf16 v[56:59], v[136:139], v[144:147], v[56:59]
	v_mfma_f32_16x16x32_bf16 v[48:51], v[128:131], v[152:155], v[48:51]
	v_mfma_f32_16x16x32_bf16 v[40:43], v[136:139], v[152:155], v[40:43]
	v_mfma_f32_16x16x32_bf16 v[28:31], v[128:131], v[178:181], v[28:31]
	v_mfma_f32_16x16x32_bf16 v[24:27], v[136:139], v[178:181], v[24:27]
	v_mfma_f32_16x16x32_bf16 v[12:15], v[128:131], v[186:189], v[12:15]
	v_mfma_f32_16x16x32_bf16 v[8:11], v[136:139], v[186:189], v[8:11]
	v_mfma_f32_16x16x32_bf16 v[60:63], v[132:135], v[148:151], v[60:63]
	v_mfma_f32_16x16x32_bf16 v[56:59], v[140:143], v[148:151], v[56:59]
	v_mfma_f32_16x16x32_bf16 v[48:51], v[132:135], v[156:159], v[48:51]
	v_mfma_f32_16x16x32_bf16 v[40:43], v[140:143], v[156:159], v[40:43]
	v_mfma_f32_16x16x32_bf16 v[28:31], v[132:135], v[182:185], v[28:31]
	v_mfma_f32_16x16x32_bf16 v[24:27], v[140:143], v[182:185], v[24:27]
	v_mfma_f32_16x16x32_bf16 v[12:15], v[132:135], v[190:193], v[12:15]
	v_mfma_f32_16x16x32_bf16 v[8:11], v[140:143], v[190:193], v[8:11]
	s_barrier
	s_setprio 0
	s_mov_b32 m0, s63
	s_nop 0
	global_load_lds_dwordx4 v164, s[64:65]
	s_add_u32 s54, s12, 0x80000
	s_addc_u32 s55, s13, 0
	s_add_i32 s53, s81, s70
	s_mov_b32 m0, s53
	s_nop 0
	global_load_lds_dwordx4 v162, s[54:55]
	s_add_i32 m0, s53, 0x2000
	s_nop 0
	global_load_lds_dwordx4 v166, s[54:55]
	s_add_i32 s53, 0, 0x18000
	v_add_u32_e32 v140, s53, v199
	ds_read_b128 v[128:131], v140
	ds_read_b128 v[132:135], v140 offset:1024
	ds_read_b128 v[136:139], v140 offset:2048
	ds_read_b128 v[140:143], v140 offset:3072
	s_waitcnt vmcnt(6)
	s_setprio 1
	s_barrier
; #define PG8_STAGE(bufoff, gbase, voff) do { _Pragma("unroll") for (int _i = 0; _i < 2; ++_i) \
;     __builtin_amdgcn_global_load_lds((const unsigned*)((const char*)(gbase) + (voff)[_i]), (LAS unsigned*)(lds + (bufoff) + ldsw + _i * 8192), 16, 0, 0); } while (0)
; #define PG8_LDA(dst, b, h) do { _Pragma("unroll") for (int m = 0; m < 4; ++m) _Pragma("unroll") for (int k = 0; k < 2; ++k) dst[m][k] = *(const LAS bf16x8*)(lds + PG8_SA(b, h) + aoff + m * 2048 + k * 1024); } while (0)
; #define PG8_LDB(dst, b, h) do { _Pragma("unroll") for (int n = 0; n < 2; ++n) _Pragma("unroll") for (int k = 0; k < 2; ++k) dst[n][k] = *(const LAS bf16x8*)(lds + PG8_SB(b, h) + boff + n * 2048 + k * 1024); } while (0)
; #define PG8_WAIT_V(n) asm volatile("s_waitcnt vmcnt(" #n ")" ::: "memory")
; template <class Epi, class Sched = StaticOrder>
; DI void gemm_phase(LAS unsigned char* lds, const Gemm g, const Sched& S, const Epi& E) {
;     ...
;     for (int t = 0; t < nt; t += 2) {
;       const bool last = (t == nt - 2);
;       const char* a1 = cA + (size_t)(t + 1) * kstep;
;       const char* a2 = last ? nA : cA + (size_t)(t + 2) * kstep; const char* b2 = last ? nB : cB + (size_t)(t + 2) * kstep;
;       const char* a3 = a2 + kstep; const char* b3 = b2 + kstep;
;       PG8_LDB(B0, 0, 0); PG8_SCHED; PG8_LDA(At, 0, 0); PG8_STAGE(PG8_SA(1, 1), a1 + hstep, voffA);
;       PG8_WAIT_L(8); PG8_BAR; PG8_WAIT_L(0); PG8_MMA(0, 0, At, B0); PG8_BAR; PG8_SCHED;
;       PG8_LDB(B1, 0, 1); PG8_STAGE(PG8_SB(0, 0), b2, voffB);
;       PG8_BAR; PG8_WAIT_L(0); PG8_MMA(0, 1, At, B1); PG8_BAR;
;       PG8_LDA(At, 0, 1); PG8_STAGE(PG8_SA(0, 0), a2, voffA);
;       PG8_BAR; PG8_WAIT_L(0); PG8_MMA(1, 0, At, B0); PG8_BAR; PG8_SCHED;
;       PG8_STAGE(PG8_SB(0, 1), b2 + hstep, voffB);
;       PG8_WAIT_V(6); PG8_BAR; PG8_MMA(1, 1, At, B1); PG8_BAR;
;       PG8_LDB(B0, 1, 0); PG8_SCHED; PG8_LDA(At, 1, 0); PG8_STAGE(PG8_SA(0, 1), a2 + hstep, voffA);
;       PG8_WAIT_L(8); PG8_BAR; PG8_WAIT_L(0); PG8_MMA(0, 0, At, B0); PG8_BAR; PG8_SCHED;
;       PG8_LDB(B1, 1, 1); PG8_STAGE(PG8_SB(1, 0), b3, voffB);
;       PG8_BAR; PG8_WAIT_L(0); PG8_MMA(0, 1, At, B1); PG8_BAR;
;       PG8_LDA(At, 1, 1); PG8_STAGE(PG8_SA(1, 0), a3, voffA);
;       PG8_BAR; PG8_WAIT_L(0); PG8_MMA(1, 0, At, B0); PG8_BAR; PG8_SCHED;
;       PG8_STAGE(PG8_SB(1, 1), b3 + hstep, voffB);
;       PG8_WAIT_V(6); PG8_BAR; PG8_MMA(1, 1, At, B1); PG8_BAR;
	v_mfma_f32_16x16x32_bf16 v[52:55], v[194:197], v[144:147], v[52:55]
	v_mfma_f32_16x16x32_bf16 v[44:47], v[216:219], v[144:147], v[44:47]
	v_mfma_f32_16x16x32_bf16 v[36:39], v[194:197], v[152:155], v[36:39]
	v_mfma_f32_16x16x32_bf16 v[32:35], v[216:219], v[152:155], v[32:35]
	v_mfma_f32_16x16x32_bf16 v[20:23], v[194:197], v[178:181], v[20:23]
	v_mfma_f32_16x16x32_bf16 v[16:19], v[216:219], v[178:181], v[16:19]
	v_mfma_f32_16x16x32_bf16 v[4:7], v[194:197], v[186:189], v[4:7]
	v_mfma_f32_16x16x32_bf16 v[0:3], v[216:219], v[186:189], v[0:3]
	v_mfma_f32_16x16x32_bf16 v[52:55], v[212:215], v[148:151], v[52:55]
	v_mfma_f32_16x16x32_bf16 v[44:47], v[220:223], v[148:151], v[44:47]
	v_mfma_f32_16x16x32_bf16 v[36:39], v[212:215], v[156:159], v[36:39]
	v_mfma_f32_16x16x32_bf16 v[32:35], v[220:223], v[156:159], v[32:35]
	v_mfma_f32_16x16x32_bf16 v[20:23], v[212:215], v[182:185], v[20:23]
	v_mfma_f32_16x16x32_bf16 v[16:19], v[220:223], v[182:185], v[16:19]
	v_mfma_f32_16x16x32_bf16 v[4:7], v[212:215], v[190:193], v[4:7]
	v_mfma_f32_16x16x32_bf16 v[0:3], v[220:223], v[190:193], v[0:3]
	s_barrier
	s_setprio 0
	s_add_u32 s54, s64, 0x80000
	s_addc_u32 s55, s65, 0
	s_mov_b32 m0, s71
	ds_read_b128 v[144:147], v204 offset:32768
	ds_read_b128 v[148:151], v204 offset:33792
	ds_read_b128 v[152:155], v204 offset:34816
	ds_read_b128 v[156:159], v204 offset:35840
	ds_read_b128 v[178:181], v204 offset:36864
	ds_read_b128 v[182:185], v204 offset:37888
	ds_read_b128 v[186:189], v204 offset:38912
	ds_read_b128 v[190:193], v204 offset:39936
	global_load_lds_dwordx4 v160, s[54:55]
	s_waitcnt lgkmcnt(0)
	s_setprio 1
	s_barrier
	v_mfma_f32_16x16x32_bf16 v[124:127], v[128:131], v[144:147], v[124:127]
	v_mfma_f32_16x16x32_bf16 v[120:123], v[136:139], v[144:147], v[120:123]
	v_mfma_f32_16x16x32_bf16 v[116:119], v[128:131], v[152:155], v[116:119]
	v_mfma_f32_16x16x32_bf16 v[104:107], v[136:139], v[152:155], v[104:107]
	v_mfma_f32_16x16x32_bf16 v[92:95], v[128:131], v[178:181], v[92:95]
	v_mfma_f32_16x16x32_bf16 v[88:91], v[136:139], v[178:181], v[88:91]
	v_mfma_f32_16x16x32_bf16 v[84:87], v[128:131], v[186:189], v[84:87]
	v_mfma_f32_16x16x32_bf16 v[72:75], v[136:139], v[186:189], v[72:75]
	v_mfma_f32_16x16x32_bf16 v[124:127], v[132:135], v[148:151], v[124:127]
	v_mfma_f32_16x16x32_bf16 v[120:123], v[140:143], v[148:151], v[120:123]
	v_mfma_f32_16x16x32_bf16 v[116:119], v[132:135], v[156:159], v[116:119]
	v_mfma_f32_16x16x32_bf16 v[104:107], v[140:143], v[156:159], v[104:107]
	v_mfma_f32_16x16x32_bf16 v[92:95], v[132:135], v[182:185], v[92:95]
	v_mfma_f32_16x16x32_bf16 v[88:91], v[140:143], v[182:185], v[88:91]
	v_mfma_f32_16x16x32_bf16 v[84:87], v[132:135], v[190:193], v[84:87]
	v_mfma_f32_16x16x32_bf16 v[72:75], v[140:143], v[190:193], v[72:75]
	s_barrier
	s_setprio 0
	s_mov_b32 m0, s72
	s_nop 0
	global_load_lds_dwordx4 v164, s[54:55]
	s_add_i32 s54, 0, 0x1c000
	s_add_i32 s53, s53, s70
	v_add_u32_e32 v168, s54, v199
	s_mov_b32 m0, s53
	ds_read_b128 v[194:197], v168
	ds_read_b128 v[212:215], v168 offset:1024
	ds_read_b128 v[216:219], v168 offset:2048
	ds_read_b128 v[220:223], v168 offset:3072
	global_load_lds_dwordx4 v162, s[98:99]
	s_add_i32 m0, s53, 0x2000
	s_nop 0
	global_load_lds_dwordx4 v166, s[98:99]
	s_waitcnt lgkmcnt(0)
	s_setprio 1
	s_barrier
	v_mfma_f32_16x16x32_bf16 v[112:115], v[194:197], v[144:147], v[112:115]
	v_mfma_f32_16x16x32_bf16 v[108:111], v[216:219], v[144:147], v[108:111]
	v_mfma_f32_16x16x32_bf16 v[100:103], v[194:197], v[152:155], v[100:103]
	v_mfma_f32_16x16x32_bf16 v[96:99], v[216:219], v[152:155], v[96:99]
	v_mfma_f32_16x16x32_bf16 v[80:83], v[194:197], v[178:181], v[80:83]
	v_mfma_f32_16x16x32_bf16 v[76:79], v[216:219], v[178:181], v[76:79]
	v_mfma_f32_16x16x32_bf16 v[68:71], v[194:197], v[186:189], v[68:71]
	v_mfma_f32_16x16x32_bf16 v[64:67], v[216:219], v[186:189], v[64:67]
	v_mfma_f32_16x16x32_bf16 v[112:115], v[212:215], v[148:151], v[112:115]
	v_mfma_f32_16x16x32_bf16 v[108:111], v[220:223], v[148:151], v[108:111]
	v_mfma_f32_16x16x32_bf16 v[100:103], v[212:215], v[156:159], v[100:103]
	v_mfma_f32_16x16x32_bf16 v[96:99], v[220:223], v[156:159], v[96:99]
	v_mfma_f32_16x16x32_bf16 v[80:83], v[212:215], v[182:185], v[80:83]
	v_mfma_f32_16x16x32_bf16 v[76:79], v[220:223], v[182:185], v[76:79]
	v_mfma_f32_16x16x32_bf16 v[68:71], v[212:215], v[190:193], v[68:71]
	v_mfma_f32_16x16x32_bf16 v[64:67], v[220:223], v[190:193], v[64:67]
	s_barrier
	s_setprio 0
	s_mov_b32 m0, s76
	ds_read_b128 v[144:147], v204 offset:49152
	ds_read_b128 v[148:151], v204 offset:50176
	ds_read_b128 v[152:155], v204 offset:51200
	ds_read_b128 v[156:159], v204 offset:52224
	ds_read_b128 v[178:181], v204 offset:53248
	ds_read_b128 v[182:185], v204 offset:54272
	ds_read_b128 v[186:189], v204 offset:55296
	ds_read_b128 v[190:193], v204 offset:56320
	global_load_lds_dwordx4 v160, s[100:101]
	s_waitcnt vmcnt(9)
	s_waitcnt lgkmcnt(0)
	s_setprio 1
	s_barrier
	v_mfma_f32_16x16x32_bf16 v[60:63], v[128:131], v[144:147], v[60:63]
	v_mfma_f32_16x16x32_bf16 v[56:59], v[136:139], v[144:147], v[56:59]
	v_mfma_f32_16x16x32_bf16 v[48:51], v[128:131], v[152:155], v[48:51]
	v_mfma_f32_16x16x32_bf16 v[40:43], v[136:139], v[152:155], v[40:43]
	v_mfma_f32_16x16x32_bf16 v[28:31], v[128:131], v[178:181], v[28:31]
	v_mfma_f32_16x16x32_bf16 v[24:27], v[136:139], v[178:181], v[24:27]
	v_mfma_f32_16x16x32_bf16 v[12:15], v[128:131], v[186:189], v[12:15]
	v_mfma_f32_16x16x32_bf16 v[8:11], v[136:139], v[186:189], v[8:11]
	v_mfma_f32_16x16x32_bf16 v[60:63], v[132:135], v[148:151], v[60:63]
	v_mfma_f32_16x16x32_bf16 v[56:59], v[140:143], v[148:151], v[56:59]
	v_mfma_f32_16x16x32_bf16 v[48:51], v[132:135], v[156:159], v[48:51]
	v_mfma_f32_16x16x32_bf16 v[40:43], v[140:143], v[156:159], v[40:43]
	v_mfma_f32_16x16x32_bf16 v[28:31], v[132:135], v[182:185], v[28:31]
	v_mfma_f32_16x16x32_bf16 v[24:27], v[140:143], v[182:185], v[24:27]
	v_mfma_f32_16x16x32_bf16 v[12:15], v[132:135], v[190:193], v[12:15]
	v_mfma_f32_16x16x32_bf16 v[8:11], v[140:143], v[190:193], v[8:11]
	s_barrier
; #define PG8_STAGE(bufoff, gbase, voff) do { _Pragma("unroll") for (int _i = 0; _i < 2; ++_i) \
;     __builtin_amdgcn_global_load_lds((const unsigned*)((const char*)(gbase) + (voff)[_i]), (LAS unsigned*)(lds + (bufoff) + ldsw + _i * 8192), 16, 0, 0); } while (0)
; #define PG8_MMA(ai, bj, At, Bt) do { __builtin_amdgcn_s_setprio(1); _Pragma("unroll") for (int m = 0; m < 4; ++m) _Pragma("unroll") for (int n = 0; n < 2; ++n) _Pragma("unroll") for (int k = 0; k < 2; ++k) \
;     acc[ai][bj][m][n] = __builtin_amdgcn_mfma_f32_16x16x32_bf16(Bt[n][k], At[m][k], acc[ai][bj][m][n], 0, 0, 0); __builtin_amdgcn_s_setprio(0); } while (0)
; #define PG8_WAIT_V(n) asm volatile("s_waitcnt vmcnt(" #n ")" ::: "memory")
; #define PG8_WAIT_L(n) asm volatile("s_waitcnt lgkmcnt(" #n ")" ::: "memory")
; #define PG8_BAR __builtin_amdgcn_s_barrier()
; #define PG8_SCHED __builtin_amdgcn_sched_barrier(0)
;   DI void operator()(const f32x4 (&acc)[2][2][4][2], const Unit& u, int wr, int wc, int fr, int fq) const {
;     ...
;     const int col = u.pn * 128 + wc * 32 + 8 * fq;
;     float w0[8], w1[8], w2[8];
; #pragma unroll
;     for (int e = 0; e < 8; ++e) { w0[e] = cw[col + e]; w1[e] = cw[2048 + col + e]; w2[e] = cw[4096 + col + e]; }
; #pragma unroll
;     for (int ai = 0; ai < 2; ++ai) {
;       const int row0 = u.pm * BM + ai * HALF + wr * 64, span = row0 >> 6;
;       float rsv[4];
; #pragma unroll
;       for (int m = 0; m < 4; ++m) rsv[m] = row_rstd(ssq, row0 + 16 * m + fr, fq);
; template <class Epi, class Sched = StaticOrder>
; DI void gemm_phase(LAS unsigned char* lds, const Gemm g, const Sched& S, const Epi& E) {
;     ...
;       PG8_BAR; PG8_WAIT_L(0); PG8_MMA(1, 0, At, B0); PG8_BAR; PG8_SCHED;
;       PG8_STAGE(PG8_SB(1, 1), b3 + hstep, voffB);
;       PG8_WAIT_V(6); PG8_BAR; PG8_MMA(1, 1, At, B1); PG8_BAR;
;     }
;     E(acc, cur, wr, wc, fr, fq);
	s_setprio 0
	s_mov_b32 m0, s77
	s_nop 0
	global_load_lds_dwordx4 v164, s[100:101]
	s_add_u32 s12, s12, 0x80080
	s_addc_u32 s13, s13, 0
	s_add_i32 s53, s54, s70
	s_mov_b32 m0, s53
	s_nop 0
	global_load_lds_dwordx4 v162, s[12:13]
	s_add_i32 m0, s53, 0x2000
	s_nop 0
	global_load_lds_dwordx4 v166, s[12:13]
	ds_read_b128 v[128:131], v203
	ds_read_b128 v[132:135], v203 offset:1024
	ds_read_b128 v[136:139], v203 offset:2048
	ds_read_b128 v[140:143], v203 offset:3072
	s_waitcnt vmcnt(6)
	s_setprio 1
	s_barrier
	v_mfma_f32_16x16x32_bf16 v[52:55], v[194:197], v[144:147], v[52:55]
	v_mfma_f32_16x16x32_bf16 v[44:47], v[216:219], v[144:147], v[44:47]
	v_mfma_f32_16x16x32_bf16 v[36:39], v[194:197], v[152:155], v[36:39]
	v_mfma_f32_16x16x32_bf16 v[32:35], v[216:219], v[152:155], v[32:35]
	v_mfma_f32_16x16x32_bf16 v[20:23], v[194:197], v[178:181], v[20:23]
	v_mfma_f32_16x16x32_bf16 v[16:19], v[216:219], v[178:181], v[16:19]
	v_mfma_f32_16x16x32_bf16 v[4:7], v[194:197], v[186:189], v[4:7]
	v_mfma_f32_16x16x32_bf16 v[0:3], v[216:219], v[186:189], v[0:3]
	v_mfma_f32_16x16x32_bf16 v[52:55], v[212:215], v[148:151], v[52:55]
	v_mfma_f32_16x16x32_bf16 v[44:47], v[220:223], v[148:151], v[44:47]
	v_mfma_f32_16x16x32_bf16 v[36:39], v[212:215], v[156:159], v[36:39]
	v_mfma_f32_16x16x32_bf16 v[32:35], v[220:223], v[156:159], v[32:35]
	v_mfma_f32_16x16x32_bf16 v[20:23], v[212:215], v[182:185], v[20:23]
	v_mfma_f32_16x16x32_bf16 v[16:19], v[220:223], v[182:185], v[16:19]
	v_mfma_f32_16x16x32_bf16 v[4:7], v[212:215], v[190:193], v[4:7]
	v_mfma_f32_16x16x32_bf16 v[0:3], v[220:223], v[190:193], v[0:3]
	s_add_i32 s52, s52, 2
	s_add_u32 s10, s10, 0x100
	s_addc_u32 s11, s11, 0
	s_add_u32 s45, s45, 0x100
	s_addc_u32 s49, s49, 0
	s_cmp_gt_u32 s52, 29
	s_barrier
	s_setprio 0
	s_cbranch_scc0 .LBB0_1052
	s_waitcnt lgkmcnt(0)
	s_cmp_lt_i32 s62, 16
	s_mov_b64 s[10:11], -1
	s_cbranch_scc0 .LBB0_1067
	s_lshl_b32 s41, s60, 8
	s_add_i32 s41, s41, s75
	v_or_b32_e32 v186, s41, v177
	v_ashrrev_i32_e32 v187, 31, v186
	v_lshlrev_b64 v[128:129], 7, v[186:187]
	v_or_b32_e32 v180, 16, v186
	v_lshl_add_u64 v[128:129], v[170:171], 0, v[128:129]
	v_ashrrev_i32_e32 v181, 31, v180
	global_load_dwordx4 v[152:155], v[128:129], off
	global_load_dwordx4 v[156:159], v[128:129], off offset:16
	v_lshlrev_b64 v[128:129], 7, v[180:181]
	v_lshl_add_u64 v[128:129], v[170:171], 0, v[128:129]
	global_load_dwordx4 v[188:191], v[128:129], off
	global_load_dwordx4 v[192:195], v[128:129], off offset:16
	v_or_b32_e32 v184, 32, v186
	v_ashrrev_i32_e32 v185, 31, v184
	v_lshlrev_b64 v[128:129], 7, v[184:185]
	v_or_b32_e32 v182, 48, v186
	v_lshl_add_u64 v[128:129], v[170:171], 0, v[128:129]
	v_ashrrev_i32_e32 v183, 31, v182
	global_load_dwordx4 v[212:215], v[128:129], off
	global_load_dwordx4 v[216:219], v[128:129], off offset:16
	v_lshlrev_b64 v[128:129], 7, v[182:183]
	v_lshl_add_u64 v[128:129], v[170:171], 0, v[128:129]
	global_load_dwordx4 v[220:223], v[128:129], off
	global_load_dwordx4 v[224:227], v[128:129], off offset:16
	v_and_b32_e32 v129, 64, v206
	v_lshl_or_b32 v178, s62, 7, v200
	v_xor_b32_e32 v128, 16, v206
	v_add_u32_e32 v129, 64, v129
	v_readlane_b32 s44, v243, 3
	v_xor_b32_e32 v130, 32, v206
	v_ashrrev_i32_e32 v179, 31, v178
	v_readlane_b32 s45, v243, 4
	v_cmp_lt_i32_e32 vcc, v128, v129
	s_movk_i32 s10, 0x2000
	v_lshl_add_u64 v[144:145], v[178:179], 2, s[44:45]
	v_cndmask_b32_e32 v134, v206, v128, vcc
	v_cmp_lt_i32_e32 vcc, v130, v129
	v_lshl_add_u64 v[132:133], v[144:145], 0, s[26:27]
	v_lshl_add_u64 v[136:137], v[144:145], 0, s[28:29]
	v_cndmask_b32_e32 v135, v206, v130, vcc
	v_add_co_u32_e32 v146, vcc, s10, v144
	global_load_dwordx4 v[128:131], v[144:145], off offset:16
	global_load_dwordx4 v[140:143], v[144:145], off
	v_addc_co_u32_e32 v147, vcc, 0, v145, vcc
	v_add_co_u32_e32 v148, vcc, s74, v144
	v_lshlrev_b32_e32 v196, 2, v134
	s_nop 0
	v_addc_co_u32_e32 v149, vcc, 0, v145, vcc
	v_lshlrev_b32_e32 v207, 2, v135
	global_load_dwordx4 v[132:135], v[132:133], off offset:16
	s_nop 0
	global_load_dwordx4 v[136:139], v[136:137], off offset:16
	s_nop 0
	global_load_dwordx4 v[144:147], v[146:147], off
	s_nop 0
	global_load_dwordx4 v[148:151], v[148:149], off
	v_mov_b32_e32 v197, 0
	v_mov_b32_e32 v211, 0
	v_readlane_b32 s46, v243, 5
	v_readlane_b32 s47, v243, 6
	v_readlane_b32 s48, v243, 7
	v_readlane_b32 s49, v243, 8
	v_readlane_b32 s50, v243, 9
	v_readlane_b32 s51, v243, 10
	v_readlane_b32 s52, v243, 11
	v_readlane_b32 s53, v243, 12
	v_readlane_b32 s54, v243, 13
	v_readlane_b32 s55, v243, 14
	v_readlane_b32 s56, v243, 15
	v_readlane_b32 s57, v243, 16
	v_readlane_b32 s58, v243, 17
	v_readlane_b32 s59, v243, 18
	s_waitcnt vmcnt(0)
	v_mov_b32_e32 v208, v152
	v_mov_b32_e32 v209, v156
	v_mov_b32_e32 v156, v153
	v_mov_b32_e32 v152, v154
	v_mov_b32_e32 v153, v158
	v_mov_b32_e32 v158, v155
	v_pk_add_f32 v[154:155], v[208:209], v[156:157]
	v_pk_add_f32 v[152:153], v[152:153], v[158:159]
	v_mov_b32_e32 v156, v188
	v_mov_b32_e32 v157, v192
	v_mov_b32_e32 v192, v189
	v_mov_b32_e32 v158, v190
	v_mov_b32_e32 v159, v194
	v_mov_b32_e32 v194, v191
	v_pk_add_f32 v[152:153], v[154:155], v[152:153]
	v_pk_add_f32 v[154:155], v[156:157], v[192:193]
	v_pk_add_f32 v[156:157], v[158:159], v[194:195]
	v_mov_b32_e32 v188, v212
	v_pk_add_f32 v[154:155], v[154:155], v[156:157]
	v_mov_b32_e32 v157, v152
	v_mov_b32_e32 v156, v154
	v_mov_b32_e32 v152, v155
	v_pk_add_f32 v[152:153], v[156:157], v[152:153]
	ds_bpermute_b32 v155, v196, v153
	ds_bpermute_b32 v154, v196, v152
	v_mov_b32_e32 v189, v216
	v_mov_b32_e32 v216, v213
	v_mov_b32_e32 v190, v214
	v_mov_b32_e32 v191, v218
	s_waitcnt lgkmcnt(0)
; DI unsigned pack2(float lo, float hi) { f32x2 v = {lo, hi}; bf16v2 r = __builtin_convertvector(v, bf16v2); return __builtin_bit_cast(unsigned, r); }
; DI float dpp_ror1(float v) { return __int_as_float(__builtin_amdgcn_update_dpp(0, __float_as_int(v), 0x121, 0xf, 0xf, false)); }
; DI float dpp_ror2(float v) { return __int_as_float(__builtin_amdgcn_update_dpp(0, __float_as_int(v), 0x122, 0xf, 0xf, false)); }
;   DI void operator()(const f32x4 (&acc)[2][2][4][2], const Unit& u, int wr, int wc, int fr, int fq) const {
;     ...
;       for (int m = 0; m < 4; ++m) {
;         float g[8], a[8];
;         const float rs1 = rsv[m], rs2 = rs1 * rs1;
; #pragma unroll
;         for (int e = 0; e < 4; ++e) { g[e] = acc[ai][0][m][0][e] * acc[ai][1][m][0][e] * rs2; g[4 + e] = acc[ai][0][m][1][e] * acc[ai][1][m][1][e] * rs2; }
; #pragma unroll
;         for (int e = 0; e < 8; ++e) {
;           const float x1 = dpp_ror1(g[e]), x2 = dpp_ror2(g[e]);
;           const float pr1 = (fr == 0) ? p1[e] : x1, pr2 = (fr < 2) ? p2[e] : x2;
;           a[e] = w2[e] * g[e] + w1[e] * pr1 + w0[e] * pr2;
;           p1[e] = x1; p2[e] = x2;
;         }
;         if (m == 0 && fr < 2) {
;           float* hc = headC + (size_t)(span * 2 + fr) * 2048 + col;
;           *(f32x4*)hc = (f32x4){a[0], a[1], a[2], a[3]}; *(f32x4*)(hc + 4) = (f32x4){a[4], a[5], a[6], a[7]};
;         } else {
;           u32x4 w; w.x = pack2(a[0] * rs1, a[1] * rs1); w.y = pack2(a[2] * rs1, a[3] * rs1); w.z = pack2(a[4] * rs1, a[5] * rs1); w.w = pack2(a[6] * rs1, a[7] * rs1);
;           *(u32x4*)(C + (size_t)(row0 + 16 * m + fr) * 2048 + col) = w;
	v_pk_add_f32 v[152:153], v[152:153], v[154:155]
	ds_bpermute_b32 v155, v207, v153
	ds_bpermute_b32 v154, v207, v152
	v_mov_b32_e32 v218, v215
	v_mov_b32_e32 v208, v220
	v_mov_b32_e32 v209, v224
	v_mov_b32_e32 v224, v221
	v_mov_b32_e32 v212, v222
	v_mov_b32_e32 v213, v226
	v_mov_b32_e32 v226, v223
	v_pk_add_f32 v[156:157], v[188:189], v[216:217]
	v_pk_add_f32 v[158:159], v[190:191], v[218:219]
	v_pk_add_f32 v[188:189], v[208:209], v[224:225]
	v_pk_add_f32 v[190:191], v[212:213], v[226:227]
	s_waitcnt lgkmcnt(0)
	v_pk_add_f32 v[152:153], v[152:153], v[154:155]
	v_pk_add_f32 v[156:157], v[156:157], v[158:159]
	v_pk_add_f32 v[158:159], v[188:189], v[190:191]
	v_pk_fma_f32 v[188:189], v[152:153], s[30:31], v[176:177] op_sel_hi:[1,0,0]
	v_mov_b32_e32 v153, v156
	v_mul_f32_e32 v152, 0x4b800000, v189
	v_cmp_gt_f32_e64 s[10:11], s84, v189
	v_mov_b32_e32 v156, v159
	v_mov_b32_e32 v194, v123
	v_cndmask_b32_e64 v152, v189, v152, s[10:11]
	v_rsq_f32_e32 v168, v152
	v_mov_b32_e32 v152, v158
	v_pk_add_f32 v[152:153], v[152:153], v[156:157]
	ds_bpermute_b32 v155, v196, v153
	ds_bpermute_b32 v154, v196, v152
	v_mul_f32_e32 v156, 0x45800000, v168
	v_cndmask_b32_e64 v195, v168, v156, s[10:11]
	v_mov_b32_e32 v217, 0
	v_mul_f32_e32 v156, v125, v113
	s_waitcnt lgkmcnt(0)
	v_pk_add_f32 v[190:191], v[152:153], v[154:155]
	v_mov_b32_e32 v152, v111
	v_mov_b32_e32 v153, v195
	v_mul_f32_e32 v154, v124, v112
	v_pk_mul_f32 v[152:153], v[194:195], v[152:153]
	v_mul_f32_e32 v155, v120, v108
	v_mul_f32_e32 v154, v154, v153
	v_pk_mul_f32 v[222:223], v[152:153], v[152:153] op_sel:[0,1] op_sel_hi:[1,0]
	v_mov_b32_e32 v213, 0
	v_mov_b32_dpp v217, v154 row_ror:1 row_mask:0xf bank_mask:0xf
	v_cndmask_b32_e64 v152, v217, 0, s[0:1]
	v_mul_f32_e32 v157, v121, v109
	v_mul_f32_e32 v158, v126, v114
	v_mul_f32_e32 v159, v122, v110
	v_mul_f32_e32 v168, v127, v115
	v_mul_f32_e32 v194, v155, v153
	v_mul_f32_e32 v155, v156, v153
	v_mov_b32_dpp v213, v154 row_ror:2 row_mask:0xf bank_mask:0xf
	v_mov_b32_e32 v221, 0
	v_mul_f32_e32 v152, v144, v152
	v_mul_f32_e32 v208, v157, v153
	v_mul_f32_e32 v156, v158, v153
	v_mul_f32_e32 v159, v159, v153
	v_mul_f32_e32 v157, v168, v153
	v_mov_b32_dpp v221, v155 row_ror:1 row_mask:0xf bank_mask:0xf
	v_cndmask_b32_e64 v153, v213, 0, s[8:9]
	v_fmac_f32_e32 v152, v148, v154
	v_mov_b32_e32 v219, 0
	v_fmac_f32_e32 v152, v140, v153
	v_cndmask_b32_e64 v153, v221, 0, s[0:1]
	v_mov_b32_dpp v219, v155 row_ror:2 row_mask:0xf bank_mask:0xf
	v_mul_f32_e32 v153, v145, v153
	v_mov_b32_e32 v216, 0
	v_cndmask_b32_e64 v154, v219, 0, s[8:9]
	v_fmac_f32_e32 v153, v149, v155
	v_mov_b32_dpp v216, v156 row_ror:1 row_mask:0xf bank_mask:0xf
	v_fmac_f32_e32 v153, v141, v154
	v_mov_b32_e32 v212, 0
	v_cndmask_b32_e64 v154, v216, 0, s[0:1]
	v_mov_b32_e32 v220, 0
	v_mov_b32_dpp v212, v156 row_ror:2 row_mask:0xf bank_mask:0xf
	v_mul_f32_e32 v154, v146, v154
	v_mov_b32_dpp v220, v157 row_ror:1 row_mask:0xf bank_mask:0xf
	v_cndmask_b32_e64 v155, v212, 0, s[8:9]
	v_fmac_f32_e32 v154, v150, v156
	v_mov_b32_e32 v218, 0
	v_fmac_f32_e32 v154, v142, v155
	v_cndmask_b32_e64 v155, v220, 0, s[0:1]
	v_mov_b32_dpp v218, v157 row_ror:2 row_mask:0xf bank_mask:0xf
	v_mul_f32_e32 v155, v147, v155
	v_cndmask_b32_e64 v156, v218, 0, s[8:9]
	v_fmac_f32_e32 v155, v151, v157
	v_mov_b32_dpp v197, v194 row_ror:1 row_mask:0xf bank_mask:0xf
	v_fmac_f32_e32 v155, v143, v156
	v_mov_b32_e32 v189, 0
	v_cndmask_b32_e64 v156, v197, 0, s[0:1]
	v_mov_b32_e32 v214, 0
	v_mov_b32_dpp v189, v194 row_ror:2 row_mask:0xf bank_mask:0xf
	v_mul_f32_e32 v156, v132, v156
	v_mov_b32_dpp v214, v208 row_ror:1 row_mask:0xf bank_mask:0xf
	v_cndmask_b32_e64 v157, v189, 0, s[8:9]
	v_fmac_f32_e32 v156, v136, v194
	v_fmac_f32_e32 v156, v128, v157
	v_cndmask_b32_e64 v157, v214, 0, s[0:1]
	v_mov_b32_e32 v209, 0
	v_mul_f32_e32 v157, v133, v157
	v_fmac_f32_e32 v157, v137, v208
	v_mov_b32_dpp v209, v208 row_ror:2 row_mask:0xf bank_mask:0xf
	v_mov_b32_e32 v208, 0
	v_cndmask_b32_e64 v158, v209, 0, s[8:9]
	v_fmac_f32_e32 v157, v129, v158
	v_mov_b32_dpp v208, v159 row_ror:1 row_mask:0xf bank_mask:0xf
	v_mov_b32_e32 v194, 0
	v_cndmask_b32_e64 v158, v208, 0, s[0:1]
	ds_bpermute_b32 v193, v207, v191
	ds_bpermute_b32 v192, v207, v190
	v_mov_b32_dpp v194, v159 row_ror:2 row_mask:0xf bank_mask:0xf
	v_mov_b32_e32 v215, 0
	v_mul_f32_e32 v158, v134, v158
	v_cndmask_b32_e64 v168, v194, 0, s[8:9]
	v_mov_b32_dpp v215, v222 row_ror:1 row_mask:0xf bank_mask:0xf
	v_fmac_f32_e32 v158, v138, v159
	v_mov_b32_dpp v211, v222 row_ror:2 row_mask:0xf bank_mask:0xf
	v_fmac_f32_e32 v158, v130, v168
	v_cndmask_b32_e64 v168, v215, 0, s[0:1]
	v_mul_f32_e32 v159, v139, v222
	v_cndmask_b32_e64 v223, v211, 0, s[8:9]
	v_fmac_f32_e32 v159, v135, v168
	v_cmp_gt_f32_e32 vcc, s84, v188
	v_fmac_f32_e32 v159, v131, v223
	s_and_saveexec_b64 s[10:11], s[4:5]
	s_xor_b64 s[10:11], exec, s[10:11]
	s_cbranch_execz .LBB0_1056
	v_mul_f32_e32 v152, v195, v152
	v_mul_f32_e32 v153, v195, v153
	v_cvt_pk_bf16_f32 v152, v152, v153
	v_mul_f32_e32 v153, v195, v154
	v_mul_f32_e32 v154, v195, v155
	v_cvt_pk_bf16_f32 v153, v153, v154
	v_mul_f32_e32 v154, v195, v156
	v_mul_f32_e32 v155, v195, v157
	v_cvt_pk_bf16_f32 v154, v154, v155
	v_mul_f32_e32 v155, v195, v158
	v_mul_f32_e32 v156, v195, v159
	v_cvt_pk_bf16_f32 v155, v155, v156
	v_lshlrev_b64 v[156:157], 12, v[186:187]
	v_lshl_add_u64 v[156:157], s[18:19], 0, v[156:157]
	v_lshl_add_u64 v[156:157], v[178:179], 1, v[156:157]
	global_store_dwordx4 v[156:157], v[152:155], off

; #define PG8_STAGE(bufoff, gbase, voff) do { _Pragma("unroll") for (int _i = 0; _i < 2; ++_i) \
;     __builtin_amdgcn_global_load_lds((const unsigned*)((const char*)(gbase) + (voff)[_i]), (LAS unsigned*)(lds + (bufoff) + ldsw + _i * 8192), 16, 0, 0); } while (0)
; #define PG8_LDA(dst, b, h) do { _Pragma("unroll") for (int m = 0; m < 4; ++m) _Pragma("unroll") for (int k = 0; k < 2; ++k) dst[m][k] = *(const LAS bf16x8*)(lds + PG8_SA(b, h) + aoff + m * 2048 + k * 1024); } while (0)
; #define PG8_LDB(dst, b, h) do { _Pragma("unroll") for (int n = 0; n < 2; ++n) _Pragma("unroll") for (int k = 0; k < 2; ++k) dst[n][k] = *(const LAS bf16x8*)(lds + PG8_SB(b, h) + boff + n * 2048 + k * 1024); } while (0)
; #define PG8_WAIT_V(n) asm volatile("s_waitcnt vmcnt(" #n ")" ::: "memory")
; template <class Epi, class Sched = StaticOrder>
; DI void gemm_phase(LAS unsigned char* lds, const Gemm g, const Sched& S, const Epi& E) {
;     ...
;     for (int t = 0; t < nt; t += 2) {
;       const bool last = (t == nt - 2);
;       const char* a1 = cA + (size_t)(t + 1) * kstep;
;       const char* a2 = last ? nA : cA + (size_t)(t + 2) * kstep; const char* b2 = last ? nB : cB + (size_t)(t + 2) * kstep;
;       const char* a3 = a2 + kstep; const char* b3 = b2 + kstep;
;       PG8_LDB(B0, 0, 0); PG8_SCHED; PG8_LDA(At, 0, 0); PG8_STAGE(PG8_SA(1, 1), a1 + hstep, voffA);
;       PG8_WAIT_L(8); PG8_BAR; PG8_WAIT_L(0); PG8_MMA(0, 0, At, B0); PG8_BAR; PG8_SCHED;
;       PG8_LDB(B1, 0, 1); PG8_STAGE(PG8_SB(0, 0), b2, voffB);
;       PG8_BAR; PG8_WAIT_L(0); PG8_MMA(0, 1, At, B1); PG8_BAR;
;       PG8_LDA(At, 0, 1); PG8_STAGE(PG8_SA(0, 0), a2, voffA);
;       PG8_BAR; PG8_WAIT_L(0); PG8_MMA(1, 0, At, B0); PG8_BAR; PG8_SCHED;
;       PG8_STAGE(PG8_SB(0, 1), b2 + hstep, voffB);
;       PG8_WAIT_V(6); PG8_BAR; PG8_MMA(1, 1, At, B1); PG8_BAR;
;       PG8_LDB(B0, 1, 0); PG8_SCHED; PG8_LDA(At, 1, 0); PG8_STAGE(PG8_SA(0, 1), a2 + hstep, voffA);
;       PG8_WAIT_L(8); PG8_BAR; PG8_WAIT_L(0); PG8_MMA(0, 0, At, B0); PG8_BAR; PG8_SCHED;
;       PG8_LDB(B1, 1, 1); PG8_STAGE(PG8_SB(1, 0), b3, voffB);
;       PG8_BAR; PG8_WAIT_L(0); PG8_MMA(0, 1, At, B1); PG8_BAR;
;       PG8_LDA(At, 1, 1); PG8_STAGE(PG8_SA(1, 0), a3, voffA);
;       PG8_BAR; PG8_WAIT_L(0); PG8_MMA(1, 0, At, B0); PG8_BAR; PG8_SCHED;
;       PG8_STAGE(PG8_SB(1, 1), b3 + hstep, voffB);
;       PG8_WAIT_V(6); PG8_BAR; PG8_MMA(1, 1, At, B1); PG8_BAR;
.LBB0_1194:
	s_add_u32 s24, s22, 0xfff80080
	s_addc_u32 s25, s23, -1
	s_cmp_eq_u32 s54, 28
	s_cselect_b32 s27, s17, s25
	s_cselect_b32 s26, s43, s24
	s_cselect_b32 s25, s15, s53
	s_cselect_b32 s24, s51, s52
	s_add_i32 m0, s37, 0xc000
	ds_read_b128 v[144:147], v215
	ds_read_b128 v[148:151], v215 offset:1024
	ds_read_b128 v[152:155], v215 offset:2048
	ds_read_b128 v[156:159], v215 offset:3072
	ds_read_b128 v[160:163], v215 offset:4096
	ds_read_b128 v[164:167], v215 offset:5120
	ds_read_b128 v[168:171], v215 offset:6144
	ds_read_b128 v[172:175], v215 offset:7168
	global_load_lds_dwordx4 v184, s[22:23]
	s_waitcnt lgkmcnt(0)
	s_setprio 1
	s_barrier
	v_mfma_f32_16x16x32_bf16 v[124:127], v[128:131], v[144:147], v[124:127]
	v_mfma_f32_16x16x32_bf16 v[120:123], v[136:139], v[144:147], v[120:123]
	v_mfma_f32_16x16x32_bf16 v[108:111], v[128:131], v[152:155], v[108:111]
	v_mfma_f32_16x16x32_bf16 v[104:107], v[136:139], v[152:155], v[104:107]
	v_mfma_f32_16x16x32_bf16 v[92:95], v[128:131], v[160:163], v[92:95]
	v_mfma_f32_16x16x32_bf16 v[88:91], v[136:139], v[160:163], v[88:91]
	v_mfma_f32_16x16x32_bf16 v[76:79], v[128:131], v[168:171], v[76:79]
	v_mfma_f32_16x16x32_bf16 v[72:75], v[136:139], v[168:171], v[72:75]
	v_mfma_f32_16x16x32_bf16 v[124:127], v[132:135], v[148:151], v[124:127]
	v_mfma_f32_16x16x32_bf16 v[120:123], v[140:143], v[148:151], v[120:123]
	v_mfma_f32_16x16x32_bf16 v[108:111], v[132:135], v[156:159], v[108:111]
	v_mfma_f32_16x16x32_bf16 v[104:107], v[140:143], v[156:159], v[104:107]
	v_mfma_f32_16x16x32_bf16 v[92:95], v[132:135], v[164:167], v[92:95]
	v_mfma_f32_16x16x32_bf16 v[88:91], v[140:143], v[164:167], v[88:91]
	v_mfma_f32_16x16x32_bf16 v[76:79], v[132:135], v[172:175], v[76:79]
	v_mfma_f32_16x16x32_bf16 v[72:75], v[140:143], v[172:175], v[72:75]
	s_barrier
	s_setprio 0
	s_add_i32 m0, s37, 0xe000
	s_nop 0
	global_load_lds_dwordx4 v186, s[22:23]
	s_add_i32 s55, s48, s35
	s_add_u32 s98, s24, 0x80
	s_addc_u32 s99, s25, 0
	s_add_u32 s100, s26, 0x80
	s_addc_u32 s101, s27, 0
	s_mov_b32 m0, s55
	ds_read_b128 v[192:195], v216
	ds_read_b128 v[196:199], v216 offset:1024
	ds_read_b128 v[200:203], v216 offset:2048
	ds_read_b128 v[204:207], v216 offset:3072
	global_load_lds_dwordx4 v180, s[24:25]
	s_add_i32 m0, s55, 0x2000
	s_nop 0
	global_load_lds_dwordx4 v176, s[24:25]
	s_waitcnt lgkmcnt(0)
	s_setprio 1
	s_barrier
	v_mfma_f32_16x16x32_bf16 v[116:119], v[192:195], v[144:147], v[116:119]
	v_mfma_f32_16x16x32_bf16 v[112:115], v[200:203], v[144:147], v[112:115]
	v_mfma_f32_16x16x32_bf16 v[100:103], v[192:195], v[152:155], v[100:103]
	v_mfma_f32_16x16x32_bf16 v[96:99], v[200:203], v[152:155], v[96:99]
	v_mfma_f32_16x16x32_bf16 v[84:87], v[192:195], v[160:163], v[84:87]
	v_mfma_f32_16x16x32_bf16 v[80:83], v[200:203], v[160:163], v[80:83]
	v_mfma_f32_16x16x32_bf16 v[68:71], v[192:195], v[168:171], v[68:71]
	v_mfma_f32_16x16x32_bf16 v[64:67], v[200:203], v[168:171], v[64:67]
	v_mfma_f32_16x16x32_bf16 v[116:119], v[196:199], v[148:151], v[116:119]
	v_mfma_f32_16x16x32_bf16 v[112:115], v[204:207], v[148:151], v[112:115]
	v_mfma_f32_16x16x32_bf16 v[100:103], v[196:199], v[156:159], v[100:103]
	v_mfma_f32_16x16x32_bf16 v[96:99], v[204:207], v[156:159], v[96:99]
	v_mfma_f32_16x16x32_bf16 v[84:87], v[196:199], v[164:167], v[84:87]
	v_mfma_f32_16x16x32_bf16 v[80:83], v[204:207], v[164:167], v[80:83]
	v_mfma_f32_16x16x32_bf16 v[68:71], v[196:199], v[172:175], v[68:71]
	v_mfma_f32_16x16x32_bf16 v[64:67], v[204:207], v[172:175], v[64:67]
	s_barrier
	s_setprio 0
	s_mov_b32 m0, s37
	ds_read_b128 v[144:147], v215 offset:16384
	ds_read_b128 v[148:151], v215 offset:17408
	ds_read_b128 v[152:155], v215 offset:18432
	ds_read_b128 v[156:159], v215 offset:19456
	ds_read_b128 v[160:163], v215 offset:20480
	ds_read_b128 v[164:167], v215 offset:21504
	ds_read_b128 v[168:171], v215 offset:22528
	ds_read_b128 v[172:175], v215 offset:23552
	global_load_lds_dwordx4 v182, s[26:27]
	s_waitcnt vmcnt(9)
	s_waitcnt lgkmcnt(0)
	s_setprio 1
	s_barrier
	v_mfma_f32_16x16x32_bf16 v[60:63], v[128:131], v[144:147], v[60:63]
	v_mfma_f32_16x16x32_bf16 v[56:59], v[136:139], v[144:147], v[56:59]
	v_mfma_f32_16x16x32_bf16 v[44:47], v[128:131], v[152:155], v[44:47]
	v_mfma_f32_16x16x32_bf16 v[40:43], v[136:139], v[152:155], v[40:43]
	v_mfma_f32_16x16x32_bf16 v[28:31], v[128:131], v[160:163], v[28:31]
	v_mfma_f32_16x16x32_bf16 v[24:27], v[136:139], v[160:163], v[24:27]
	v_mfma_f32_16x16x32_bf16 v[12:15], v[128:131], v[168:171], v[12:15]
	v_mfma_f32_16x16x32_bf16 v[8:11], v[136:139], v[168:171], v[8:11]
	v_mfma_f32_16x16x32_bf16 v[60:63], v[132:135], v[148:151], v[60:63]
	v_mfma_f32_16x16x32_bf16 v[56:59], v[140:143], v[148:151], v[56:59]
	v_mfma_f32_16x16x32_bf16 v[44:47], v[132:135], v[156:159], v[44:47]
	v_mfma_f32_16x16x32_bf16 v[40:43], v[140:143], v[156:159], v[40:43]
	v_mfma_f32_16x16x32_bf16 v[28:31], v[132:135], v[164:167], v[28:31]
	v_mfma_f32_16x16x32_bf16 v[24:27], v[140:143], v[164:167], v[24:27]
	v_mfma_f32_16x16x32_bf16 v[12:15], v[132:135], v[172:175], v[12:15]
	v_mfma_f32_16x16x32_bf16 v[8:11], v[140:143], v[172:175], v[8:11]
	s_barrier
	s_setprio 0
	s_mov_b32 m0, s38
	s_nop 0
	global_load_lds_dwordx4 v178, s[26:27]
	s_add_u32 s56, s24, 0x80000
	s_addc_u32 s57, s25, 0
	s_add_i32 s55, s49, s35
	s_mov_b32 m0, s55
	s_nop 0
	global_load_lds_dwordx4 v180, s[56:57]
	s_add_i32 m0, s55, 0x2000
	s_nop 0
	global_load_lds_dwordx4 v176, s[56:57]
	s_add_i32 s55, 0, 0x18000
	v_add_u32_e32 v140, s55, v212
	ds_read_b128 v[128:131], v140
	ds_read_b128 v[132:135], v140 offset:1024
	ds_read_b128 v[136:139], v140 offset:2048
	ds_read_b128 v[140:143], v140 offset:3072
	s_waitcnt vmcnt(6)
	s_setprio 1
	s_barrier
; #define PG8_STAGE(bufoff, gbase, voff) do { _Pragma("unroll") for (int _i = 0; _i < 2; ++_i) \
;     __builtin_amdgcn_global_load_lds((const unsigned*)((const char*)(gbase) + (voff)[_i]), (LAS unsigned*)(lds + (bufoff) + ldsw + _i * 8192), 16, 0, 0); } while (0)
; #define PG8_LDA(dst, b, h) do { _Pragma("unroll") for (int m = 0; m < 4; ++m) _Pragma("unroll") for (int k = 0; k < 2; ++k) dst[m][k] = *(const LAS bf16x8*)(lds + PG8_SA(b, h) + aoff + m * 2048 + k * 1024); } while (0)
; #define PG8_LDB(dst, b, h) do { _Pragma("unroll") for (int n = 0; n < 2; ++n) _Pragma("unroll") for (int k = 0; k < 2; ++k) dst[n][k] = *(const LAS bf16x8*)(lds + PG8_SB(b, h) + boff + n * 2048 + k * 1024); } while (0)
; #define PG8_WAIT_V(n) asm volatile("s_waitcnt vmcnt(" #n ")" ::: "memory")
; template <class Epi, class Sched = StaticOrder>
; DI void gemm_phase(LAS unsigned char* lds, const Gemm g, const Sched& S, const Epi& E) {
;     ...
;     for (int t = 0; t < nt; t += 2) {
;       const bool last = (t == nt - 2);
;       const char* a1 = cA + (size_t)(t + 1) * kstep;
;       const char* a2 = last ? nA : cA + (size_t)(t + 2) * kstep; const char* b2 = last ? nB : cB + (size_t)(t + 2) * kstep;
;       const char* a3 = a2 + kstep; const char* b3 = b2 + kstep;
;       PG8_LDB(B0, 0, 0); PG8_SCHED; PG8_LDA(At, 0, 0); PG8_STAGE(PG8_SA(1, 1), a1 + hstep, voffA);
;       PG8_WAIT_L(8); PG8_BAR; PG8_WAIT_L(0); PG8_MMA(0, 0, At, B0); PG8_BAR; PG8_SCHED;
;       PG8_LDB(B1, 0, 1); PG8_STAGE(PG8_SB(0, 0), b2, voffB);
;       PG8_BAR; PG8_WAIT_L(0); PG8_MMA(0, 1, At, B1); PG8_BAR;
;       PG8_LDA(At, 0, 1); PG8_STAGE(PG8_SA(0, 0), a2, voffA);
;       PG8_BAR; PG8_WAIT_L(0); PG8_MMA(1, 0, At, B0); PG8_BAR; PG8_SCHED;
;       PG8_STAGE(PG8_SB(0, 1), b2 + hstep, voffB);
;       PG8_WAIT_V(6); PG8_BAR; PG8_MMA(1, 1, At, B1); PG8_BAR;
;       PG8_LDB(B0, 1, 0); PG8_SCHED; PG8_LDA(At, 1, 0); PG8_STAGE(PG8_SA(0, 1), a2 + hstep, voffA);
;       PG8_WAIT_L(8); PG8_BAR; PG8_WAIT_L(0); PG8_MMA(0, 0, At, B0); PG8_BAR; PG8_SCHED;
;       PG8_LDB(B1, 1, 1); PG8_STAGE(PG8_SB(1, 0), b3, voffB);
;       PG8_BAR; PG8_WAIT_L(0); PG8_MMA(0, 1, At, B1); PG8_BAR;
;       PG8_LDA(At, 1, 1); PG8_STAGE(PG8_SA(1, 0), a3, voffA);
;       PG8_BAR; PG8_WAIT_L(0); PG8_MMA(1, 0, At, B0); PG8_BAR; PG8_SCHED;
;       PG8_STAGE(PG8_SB(1, 1), b3 + hstep, voffB);
;       PG8_WAIT_V(6); PG8_BAR; PG8_MMA(1, 1, At, B1); PG8_BAR;
	v_mfma_f32_16x16x32_bf16 v[52:55], v[192:195], v[144:147], v[52:55]
	v_mfma_f32_16x16x32_bf16 v[48:51], v[200:203], v[144:147], v[48:51]
	v_mfma_f32_16x16x32_bf16 v[36:39], v[192:195], v[152:155], v[36:39]
	v_mfma_f32_16x16x32_bf16 v[32:35], v[200:203], v[152:155], v[32:35]
	v_mfma_f32_16x16x32_bf16 v[20:23], v[192:195], v[160:163], v[20:23]
	v_mfma_f32_16x16x32_bf16 v[16:19], v[200:203], v[160:163], v[16:19]
	v_mfma_f32_16x16x32_bf16 v[4:7], v[192:195], v[168:171], v[4:7]
	v_mfma_f32_16x16x32_bf16 v[0:3], v[200:203], v[168:171], v[0:3]
	v_mfma_f32_16x16x32_bf16 v[52:55], v[196:199], v[148:151], v[52:55]
	v_mfma_f32_16x16x32_bf16 v[48:51], v[204:207], v[148:151], v[48:51]
	v_mfma_f32_16x16x32_bf16 v[36:39], v[196:199], v[156:159], v[36:39]
	v_mfma_f32_16x16x32_bf16 v[32:35], v[204:207], v[156:159], v[32:35]
	v_mfma_f32_16x16x32_bf16 v[20:23], v[196:199], v[164:167], v[20:23]
	v_mfma_f32_16x16x32_bf16 v[16:19], v[204:207], v[164:167], v[16:19]
	v_mfma_f32_16x16x32_bf16 v[4:7], v[196:199], v[172:175], v[4:7]
	v_mfma_f32_16x16x32_bf16 v[0:3], v[204:207], v[172:175], v[0:3]
	s_barrier
	s_setprio 0
	s_add_u32 s26, s26, 0x80000
	s_addc_u32 s27, s27, 0
	s_mov_b32 m0, s39
	ds_read_b128 v[144:147], v215 offset:32768
	ds_read_b128 v[148:151], v215 offset:33792
	ds_read_b128 v[152:155], v215 offset:34816
	ds_read_b128 v[156:159], v215 offset:35840
	ds_read_b128 v[160:163], v215 offset:36864
	ds_read_b128 v[164:167], v215 offset:37888
	ds_read_b128 v[168:171], v215 offset:38912
	ds_read_b128 v[172:175], v215 offset:39936
	global_load_lds_dwordx4 v182, s[26:27]
	s_waitcnt lgkmcnt(0)
	s_setprio 1
	s_barrier
	v_mfma_f32_16x16x32_bf16 v[124:127], v[128:131], v[144:147], v[124:127]
	v_mfma_f32_16x16x32_bf16 v[120:123], v[136:139], v[144:147], v[120:123]
	v_mfma_f32_16x16x32_bf16 v[108:111], v[128:131], v[152:155], v[108:111]
	v_mfma_f32_16x16x32_bf16 v[104:107], v[136:139], v[152:155], v[104:107]
	v_mfma_f32_16x16x32_bf16 v[92:95], v[128:131], v[160:163], v[92:95]
	v_mfma_f32_16x16x32_bf16 v[88:91], v[136:139], v[160:163], v[88:91]
	v_mfma_f32_16x16x32_bf16 v[76:79], v[128:131], v[168:171], v[76:79]
	v_mfma_f32_16x16x32_bf16 v[72:75], v[136:139], v[168:171], v[72:75]
	v_mfma_f32_16x16x32_bf16 v[124:127], v[132:135], v[148:151], v[124:127]
	v_mfma_f32_16x16x32_bf16 v[120:123], v[140:143], v[148:151], v[120:123]
	v_mfma_f32_16x16x32_bf16 v[108:111], v[132:135], v[156:159], v[108:111]
	v_mfma_f32_16x16x32_bf16 v[104:107], v[140:143], v[156:159], v[104:107]
	v_mfma_f32_16x16x32_bf16 v[92:95], v[132:135], v[164:167], v[92:95]
	v_mfma_f32_16x16x32_bf16 v[88:91], v[140:143], v[164:167], v[88:91]
	v_mfma_f32_16x16x32_bf16 v[76:79], v[132:135], v[172:175], v[76:79]
	v_mfma_f32_16x16x32_bf16 v[72:75], v[140:143], v[172:175], v[72:75]
	s_barrier
	s_setprio 0
	s_mov_b32 m0, s40
	s_nop 0
	global_load_lds_dwordx4 v178, s[26:27]
	s_add_i32 s26, 0, 0x1c000
	s_add_i32 s27, s55, s35
	v_add_u32_e32 v204, s26, v212
	s_mov_b32 m0, s27
	ds_read_b128 v[192:195], v204
	ds_read_b128 v[196:199], v204 offset:1024
	ds_read_b128 v[200:203], v204 offset:2048
	ds_read_b128 v[204:207], v204 offset:3072
	global_load_lds_dwordx4 v180, s[98:99]
	s_add_i32 m0, s27, 0x2000
	s_nop 0
	global_load_lds_dwordx4 v176, s[98:99]
	s_waitcnt lgkmcnt(0)
	s_setprio 1
	s_barrier
	v_mfma_f32_16x16x32_bf16 v[116:119], v[192:195], v[144:147], v[116:119]
	v_mfma_f32_16x16x32_bf16 v[112:115], v[200:203], v[144:147], v[112:115]
	v_mfma_f32_16x16x32_bf16 v[100:103], v[192:195], v[152:155], v[100:103]
	v_mfma_f32_16x16x32_bf16 v[96:99], v[200:203], v[152:155], v[96:99]
	v_mfma_f32_16x16x32_bf16 v[84:87], v[192:195], v[160:163], v[84:87]
	v_mfma_f32_16x16x32_bf16 v[80:83], v[200:203], v[160:163], v[80:83]
	v_mfma_f32_16x16x32_bf16 v[68:71], v[192:195], v[168:171], v[68:71]
	v_mfma_f32_16x16x32_bf16 v[64:67], v[200:203], v[168:171], v[64:67]
	v_mfma_f32_16x16x32_bf16 v[116:119], v[196:199], v[148:151], v[116:119]
	v_mfma_f32_16x16x32_bf16 v[112:115], v[204:207], v[148:151], v[112:115]
	v_mfma_f32_16x16x32_bf16 v[100:103], v[196:199], v[156:159], v[100:103]
	v_mfma_f32_16x16x32_bf16 v[96:99], v[204:207], v[156:159], v[96:99]
	v_mfma_f32_16x16x32_bf16 v[84:87], v[196:199], v[164:167], v[84:87]
	v_mfma_f32_16x16x32_bf16 v[80:83], v[204:207], v[164:167], v[80:83]
	v_mfma_f32_16x16x32_bf16 v[68:71], v[196:199], v[172:175], v[68:71]
	v_mfma_f32_16x16x32_bf16 v[64:67], v[204:207], v[172:175], v[64:67]
	s_barrier
	s_setprio 0
	s_mov_b32 m0, s44
	ds_read_b128 v[144:147], v215 offset:49152
	ds_read_b128 v[148:151], v215 offset:50176
	ds_read_b128 v[152:155], v215 offset:51200
	ds_read_b128 v[156:159], v215 offset:52224
	ds_read_b128 v[160:163], v215 offset:53248
	ds_read_b128 v[164:167], v215 offset:54272
	ds_read_b128 v[168:171], v215 offset:55296
	ds_read_b128 v[172:175], v215 offset:56320
	global_load_lds_dwordx4 v182, s[100:101]
	s_waitcnt vmcnt(9)
	s_waitcnt lgkmcnt(0)
	s_setprio 1
	s_barrier
	v_mfma_f32_16x16x32_bf16 v[60:63], v[128:131], v[144:147], v[60:63]
	v_mfma_f32_16x16x32_bf16 v[56:59], v[136:139], v[144:147], v[56:59]
	v_mfma_f32_16x16x32_bf16 v[44:47], v[128:131], v[152:155], v[44:47]
	v_mfma_f32_16x16x32_bf16 v[40:43], v[136:139], v[152:155], v[40:43]
	v_mfma_f32_16x16x32_bf16 v[28:31], v[128:131], v[160:163], v[28:31]
	v_mfma_f32_16x16x32_bf16 v[24:27], v[136:139], v[160:163], v[24:27]
	v_mfma_f32_16x16x32_bf16 v[12:15], v[128:131], v[168:171], v[12:15]
	v_mfma_f32_16x16x32_bf16 v[8:11], v[136:139], v[168:171], v[8:11]
	v_mfma_f32_16x16x32_bf16 v[60:63], v[132:135], v[148:151], v[60:63]
	v_mfma_f32_16x16x32_bf16 v[56:59], v[140:143], v[148:151], v[56:59]
	v_mfma_f32_16x16x32_bf16 v[44:47], v[132:135], v[156:159], v[44:47]
	v_mfma_f32_16x16x32_bf16 v[40:43], v[140:143], v[156:159], v[40:43]
	v_mfma_f32_16x16x32_bf16 v[28:31], v[132:135], v[164:167], v[28:31]
	v_mfma_f32_16x16x32_bf16 v[24:27], v[140:143], v[164:167], v[24:27]
	v_mfma_f32_16x16x32_bf16 v[12:15], v[132:135], v[172:175], v[12:15]
	v_mfma_f32_16x16x32_bf16 v[8:11], v[140:143], v[172:175], v[8:11]
	s_barrier
; DI unsigned pack2(float lo, float hi) { f32x2 v = {lo, hi}; bf16v2 r = __builtin_convertvector(v, bf16v2); return __builtin_bit_cast(unsigned, r); }
; #define PG8_STAGE(bufoff, gbase, voff) do { _Pragma("unroll") for (int _i = 0; _i < 2; ++_i) \
;     __builtin_amdgcn_global_load_lds((const unsigned*)((const char*)(gbase) + (voff)[_i]), (LAS unsigned*)(lds + (bufoff) + ldsw + _i * 8192), 16, 0, 0); } while (0)
; #define PG8_BAR __builtin_amdgcn_s_barrier()
;   DI void operator()(const f32x4 (&acc)[2][2][4][2], const Unit& u, int wr, int wc, int fr, int fq) const {
;     const int row0 = u.pm * BM + wr * 64 + fr, col0 = u.pn * BM + wc * 32 + 8 * fq;
; #pragma unroll
;     for (int ai = 0; ai < 2; ++ai) {
;       f32x4 bv[4][2][2];
; #pragma unroll
;       for (int m = 0; m < 4; ++m)
; #pragma unroll
;         for (int bj = 0; bj < 2; ++bj) {
;           const float* bp = base + (size_t)(row0 + ai * HALF + m * 16) * 2048 + col0 + bj * HALF;
;           bv[m][bj][0] = *(const f32x4*)bp; bv[m][bj][1] = *(const f32x4*)(bp + 4);
;         }
; #pragma unroll
;       for (int m = 0; m < 4; ++m) {
;         const int row = row0 + ai * HALF + m * 16;
;         const size_t off = (size_t)row * 2048 + col0;
;         float ss = 0.f;
; #pragma unroll
;         for (int bj = 0; bj < 2; ++bj) {
;           const f32x4 v0 = acc[ai][bj][m][0] + bv[m][bj][0], v1 = acc[ai][bj][m][1] + bv[m][bj][1];
;           *(f32x4*)(C + off + bj * HALF) = v0; *(f32x4*)(C + off + bj * HALF + 4) = v1;
;           if (xb) {
;             u32x4 w; w.x = pack2(v0[0], v0[1]); w.y = pack2(v0[2], v0[3]); w.z = pack2(v1[0], v1[1]); w.w = pack2(v1[2], v1[3]);
;             *(u32x4*)(xb + off + bj * HALF) = w;
;             ss += v0[0] * v0[0] + v0[1] * v0[1] + v0[2] * v0[2] + v0[3] * v0[3] + v1[0] * v1[0] + v1[1] * v1[1] + v1[2] * v1[2] + v1[3] * v1[3];
;           }
;         }
;         if (xb) {
;           ss += __shfl_xor(ss, 16); ss += __shfl_xor(ss, 32);
;           if (fq == 0) ssq[(size_t)row * 32 + u.pn * 4 + wc] = ss;
; template <class Epi, class Sched = StaticOrder>
; DI void gemm_phase(LAS unsigned char* lds, const Gemm g, const Sched& S, const Epi& E) {
;     ...
;       PG8_BAR; PG8_WAIT_L(0); PG8_MMA(1, 0, At, B0); PG8_BAR; PG8_SCHED;
;       PG8_STAGE(PG8_SB(1, 1), b3 + hstep, voffB);
;       PG8_WAIT_V(6); PG8_BAR; PG8_MMA(1, 1, At, B1); PG8_BAR;
;     }
;     E(acc, cur, wr, wc, fr, fq);
	s_setprio 0
	s_mov_b32 m0, s45
	s_nop 0
	global_load_lds_dwordx4 v178, s[100:101]
	s_add_u32 s24, s24, 0x80080
	s_addc_u32 s25, s25, 0
	s_add_i32 s26, s26, s35
	s_mov_b32 m0, s26
	s_nop 0
	global_load_lds_dwordx4 v180, s[24:25]
	s_add_i32 m0, s26, 0x2000
	s_nop 0
	global_load_lds_dwordx4 v176, s[24:25]
	ds_read_b128 v[128:131], v214
	ds_read_b128 v[132:135], v214 offset:1024
	ds_read_b128 v[136:139], v214 offset:2048
	ds_read_b128 v[140:143], v214 offset:3072
	s_waitcnt vmcnt(6)
	s_setprio 1
	s_barrier
	v_mfma_f32_16x16x32_bf16 v[52:55], v[192:195], v[144:147], v[52:55]
	v_mfma_f32_16x16x32_bf16 v[48:51], v[200:203], v[144:147], v[48:51]
	v_mfma_f32_16x16x32_bf16 v[36:39], v[192:195], v[152:155], v[36:39]
	v_mfma_f32_16x16x32_bf16 v[32:35], v[200:203], v[152:155], v[32:35]
	v_mfma_f32_16x16x32_bf16 v[20:23], v[192:195], v[160:163], v[20:23]
	v_mfma_f32_16x16x32_bf16 v[16:19], v[200:203], v[160:163], v[16:19]
	v_mfma_f32_16x16x32_bf16 v[4:7], v[192:195], v[168:171], v[4:7]
	v_mfma_f32_16x16x32_bf16 v[0:3], v[200:203], v[168:171], v[0:3]
	v_mfma_f32_16x16x32_bf16 v[52:55], v[196:199], v[148:151], v[52:55]
	v_mfma_f32_16x16x32_bf16 v[48:51], v[204:207], v[148:151], v[48:51]
	v_mfma_f32_16x16x32_bf16 v[36:39], v[196:199], v[156:159], v[36:39]
	v_mfma_f32_16x16x32_bf16 v[32:35], v[204:207], v[156:159], v[32:35]
	v_mfma_f32_16x16x32_bf16 v[20:23], v[196:199], v[164:167], v[20:23]
	v_mfma_f32_16x16x32_bf16 v[16:19], v[204:207], v[164:167], v[16:19]
	v_mfma_f32_16x16x32_bf16 v[4:7], v[196:199], v[172:175], v[4:7]
	v_mfma_f32_16x16x32_bf16 v[0:3], v[204:207], v[172:175], v[0:3]
	s_add_i32 s54, s54, 2
	s_add_u32 s22, s22, 0x100
	s_addc_u32 s23, s23, 0
	s_add_u32 s52, s52, 0x100
	s_addc_u32 s53, s53, 0
	s_cmp_gt_u32 s54, 29
	s_barrier
	s_setprio 0
	s_cbranch_scc0 .LBB0_1194
	s_waitcnt lgkmcnt(0)
	v_lshl_add_u32 v194, s12, 8, v211
	v_lshl_or_b32 v192, s42, 8, v213
	v_readlane_b32 s52, v243, 3
	v_ashrrev_i32_e32 v193, 31, v192
	v_readlane_b32 s66, v243, 17
	v_readlane_b32 s67, v243, 18
	v_ashrrev_i32_e32 v195, 31, v194
	v_lshlrev_b64 v[128:129], 13, v[194:195]
	v_lshl_add_u64 v[196:197], v[192:193], 2, s[66:67]
	v_lshl_add_u64 v[236:237], v[196:197], 0, v[128:129]
	global_load_dwordx4 v[220:223], v[236:237], off
	global_load_dwordx4 v[224:227], v[236:237], off offset:16
	global_load_dwordx4 v[228:231], v[236:237], off offset:512
	global_load_dwordx4 v[232:235], v[236:237], off offset:528
	v_or_b32_e32 v206, 16, v194
	v_or_b32_e32 v202, 32, v194
	v_or_b32_e32 v198, 48, v194
	v_ashrrev_i32_e32 v207, 31, v206
	v_ashrrev_i32_e32 v203, 31, v202
	v_ashrrev_i32_e32 v199, 31, v198
	v_lshlrev_b64 v[128:129], 13, v[206:207]
	v_lshlrev_b64 v[130:131], 13, v[202:203]
	v_lshlrev_b64 v[132:133], 13, v[198:199]
	v_lshl_add_u64 v[208:209], v[196:197], 0, v[128:129]
	v_lshl_add_u64 v[204:205], v[196:197], 0, v[130:131]
	v_lshl_add_u64 v[200:201], v[196:197], 0, v[132:133]
	global_load_dwordx4 v[168:171], v[208:209], off offset:16
	global_load_dwordx4 v[172:175], v[208:209], off
	global_load_dwordx4 v[160:163], v[208:209], off offset:528
	global_load_dwordx4 v[164:167], v[208:209], off offset:512
	global_load_dwordx4 v[152:155], v[204:205], off offset:16
	global_load_dwordx4 v[156:159], v[204:205], off
	global_load_dwordx4 v[144:147], v[204:205], off offset:528
	global_load_dwordx4 v[148:151], v[204:205], off offset:512
	global_load_dwordx4 v[136:139], v[200:201], off offset:16
	global_load_dwordx4 v[140:143], v[200:201], off
	global_load_dwordx4 v[128:131], v[200:201], off offset:528
	global_load_dwordx4 v[132:135], v[200:201], off offset:512
	v_and_b32_e32 v218, 64, v217
	v_xor_b32_e32 v238, 16, v217
	v_add_u32_e32 v240, 64, v218
	v_xor_b32_e32 v239, 32, v217
	v_cmp_lt_i32_e32 vcc, v238, v240
	v_lshlrev_b64 v[218:219], 11, v[194:195]
	s_lshl_b32 s22, s42, 2
	v_cndmask_b32_e32 v241, v217, v238, vcc
	v_cmp_lt_i32_e32 vcc, v239, v240
	s_ashr_i32 s23, s22, 31
	v_readlane_b32 s53, v243, 4
	v_cndmask_b32_e32 v240, v217, v239, vcc
	v_lshl_add_u64 v[238:239], v[218:219], 0, v[192:193]
	v_lshlrev_b32_e32 v218, 2, v241
	v_lshl_add_u64 v[238:239], v[238:239], 1, s[2:3]
	v_readlane_b32 s54, v243, 5
	v_readlane_b32 s55, v243, 6
	v_readlane_b32 s56, v243, 7
	v_readlane_b32 s57, v243, 8
	v_readlane_b32 s58, v243, 9
	v_readlane_b32 s59, v243, 10
	v_readlane_b32 s60, v243, 11
	v_readlane_b32 s61, v243, 12
	v_readlane_b32 s62, v243, 13
	v_readlane_b32 s63, v243, 14
	v_readlane_b32 s64, v243, 15
	v_readlane_b32 s65, v243, 16
	s_waitcnt vmcnt(0)
	v_pk_add_f32 v[126:127], v[126:127], v[222:223]
	v_pk_add_f32 v[124:125], v[124:125], v[220:221]
	v_pk_add_f32 v[116:117], v[116:117], v[228:229]
	v_pk_add_f32 v[122:123], v[122:123], v[226:227]
	v_pk_add_f32 v[120:121], v[120:121], v[224:225]
	v_pk_add_f32 v[220:221], v[112:113], v[232:233]
	global_store_dwordx4 v[236:237], v[124:127], off
	global_store_dwordx4 v[236:237], v[120:123], off offset:16
	v_cvt_pk_bf16_f32 v112, v124, v125
	v_mul_f32_e32 v125, v125, v125
	v_mul_f32_e32 v219, v117, v117
	v_pk_add_f32 v[118:119], v[118:119], v[230:231]
	v_fmac_f32_e32 v125, v124, v124
	v_fmac_f32_e32 v219, v116, v116
	v_fmac_f32_e32 v125, v126, v126
	v_fmac_f32_e32 v219, v118, v118
	v_fmac_f32_e32 v125, v127, v127
	v_fmac_f32_e32 v219, v119, v119
	v_fmac_f32_e32 v125, v120, v120
	v_fmac_f32_e32 v219, v220, v220
	v_pk_add_f32 v[222:223], v[114:115], v[234:235]
	v_fmac_f32_e32 v125, v121, v121
	v_fmac_f32_e32 v219, v221, v221
	v_fmac_f32_e32 v125, v122, v122
	v_fmac_f32_e32 v219, v222, v222
	v_fmac_f32_e32 v125, v123, v123
	v_fmac_f32_e32 v219, v223, v223
	v_cvt_pk_bf16_f32 v114, v120, v121
	v_add_f32_e32 v121, v125, v219
	v_cvt_pk_bf16_f32 v115, v122, v123
	ds_bpermute_b32 v122, v218, v121
	v_cvt_pk_bf16_f32 v113, v126, v127
	global_store_dwordx4 v[238:239], v[112:115], off
	global_store_dwordx4 v[236:237], v[116:119], off offset:512
	global_store_dwordx4 v[236:237], v[220:223], off offset:528
	v_lshlrev_b32_e32 v126, 2, v240
	v_cvt_pk_bf16_f32 v120, v116, v117
	s_waitcnt lgkmcnt(0)
	v_add_f32_e32 v112, v121, v122
	ds_bpermute_b32 v113, v126, v112
	v_cvt_pk_bf16_f32 v121, v118, v119
	v_cvt_pk_bf16_f32 v122, v220, v221
	v_cvt_pk_bf16_f32 v123, v222, v223
	global_store_dwordx4 v[238:239], v[120:123], off offset:256
	s_and_saveexec_b64 s[24:25], s[0:1]
	s_cbranch_execz .LBB0_1197
	s_waitcnt lgkmcnt(0)
	v_add_f32_e32 v114, v112, v113
	v_lshlrev_b64 v[112:113], 7, v[194:195]
	v_lshl_add_u64 v[112:113], s[8:9], 0, v[112:113]
	v_lshl_add_u64 v[112:113], s[22:23], 2, v[112:113]
	s_lshl_b32 s12, s41, 2
	v_lshl_add_u64 v[112:113], v[112:113], 0, s[12:13]
	global_store_dword v[112:113], v114, off

; #define PG8_STAGE(bufoff, gbase, voff) do { _Pragma("unroll") for (int _i = 0; _i < 2; ++_i) \
;     __builtin_amdgcn_global_load_lds((const unsigned*)((const char*)(gbase) + (voff)[_i]), (LAS unsigned*)(lds + (bufoff) + ldsw + _i * 8192), 16, 0, 0); } while (0)
; #define PG8_LDA(dst, b, h) do { _Pragma("unroll") for (int m = 0; m < 4; ++m) _Pragma("unroll") for (int k = 0; k < 2; ++k) dst[m][k] = *(const LAS bf16x8*)(lds + PG8_SA(b, h) + aoff + m * 2048 + k * 1024); } while (0)
; #define PG8_LDB(dst, b, h) do { _Pragma("unroll") for (int n = 0; n < 2; ++n) _Pragma("unroll") for (int k = 0; k < 2; ++k) dst[n][k] = *(const LAS bf16x8*)(lds + PG8_SB(b, h) + boff + n * 2048 + k * 1024); } while (0)
; #define PG8_WAIT_V(n) asm volatile("s_waitcnt vmcnt(" #n ")" ::: "memory")
; template <class Epi, class Sched = StaticOrder>
; DI void gemm_phase(LAS unsigned char* lds, const Gemm g, const Sched& S, const Epi& E) {
;     ...
;     for (int t = 0; t < nt; t += 2) {
;       const bool last = (t == nt - 2);
;       const char* a1 = cA + (size_t)(t + 1) * kstep;
;       const char* a2 = last ? nA : cA + (size_t)(t + 2) * kstep; const char* b2 = last ? nB : cB + (size_t)(t + 2) * kstep;
;       const char* a3 = a2 + kstep; const char* b3 = b2 + kstep;
;       PG8_LDB(B0, 0, 0); PG8_SCHED; PG8_LDA(At, 0, 0); PG8_STAGE(PG8_SA(1, 1), a1 + hstep, voffA);
;       PG8_WAIT_L(8); PG8_BAR; PG8_WAIT_L(0); PG8_MMA(0, 0, At, B0); PG8_BAR; PG8_SCHED;
;       PG8_LDB(B1, 0, 1); PG8_STAGE(PG8_SB(0, 0), b2, voffB);
;       PG8_BAR; PG8_WAIT_L(0); PG8_MMA(0, 1, At, B1); PG8_BAR;
;       PG8_LDA(At, 0, 1); PG8_STAGE(PG8_SA(0, 0), a2, voffA);
;       PG8_BAR; PG8_WAIT_L(0); PG8_MMA(1, 0, At, B0); PG8_BAR; PG8_SCHED;
;       PG8_STAGE(PG8_SB(0, 1), b2 + hstep, voffB);
;       PG8_WAIT_V(6); PG8_BAR; PG8_MMA(1, 1, At, B1); PG8_BAR;
;       PG8_LDB(B0, 1, 0); PG8_SCHED; PG8_LDA(At, 1, 0); PG8_STAGE(PG8_SA(0, 1), a2 + hstep, voffA);
;       PG8_WAIT_L(8); PG8_BAR; PG8_WAIT_L(0); PG8_MMA(0, 0, At, B0); PG8_BAR; PG8_SCHED;
;       PG8_LDB(B1, 1, 1); PG8_STAGE(PG8_SB(1, 0), b3, voffB);
;       PG8_BAR; PG8_WAIT_L(0); PG8_MMA(0, 1, At, B1); PG8_BAR;
;       PG8_LDA(At, 1, 1); PG8_STAGE(PG8_SA(1, 0), a3, voffA);
;       PG8_BAR; PG8_WAIT_L(0); PG8_MMA(1, 0, At, B0); PG8_BAR; PG8_SCHED;
;       PG8_STAGE(PG8_SB(1, 1), b3 + hstep, voffB);
;       PG8_WAIT_V(6); PG8_BAR; PG8_MMA(1, 1, At, B1); PG8_BAR;
.LBB0_1277:
	s_add_u32 s48, s14, 0xfff80080
	s_addc_u32 s49, s15, -1
	s_cmp_eq_u32 s58, 28
	s_cselect_b32 s51, s41, s49
	s_cselect_b32 s50, s42, s48
	s_cselect_b32 s49, s39, s53
	s_cselect_b32 s48, s43, s52
	s_add_i32 m0, s64, 0xc000
	ds_read_b128 v[80:83], v202
	ds_read_b128 v[84:87], v202 offset:1024
	ds_read_b128 v[88:91], v202 offset:2048
	ds_read_b128 v[92:95], v202 offset:3072
	ds_read_b128 v[180:183], v202 offset:4096
	ds_read_b128 v[184:187], v202 offset:5120
	ds_read_b128 v[188:191], v202 offset:6144
	ds_read_b128 v[192:195], v202 offset:7168
	global_load_lds_dwordx4 v170, s[14:15]
	s_waitcnt lgkmcnt(0)
	s_setprio 1
	s_barrier
	v_mfma_f32_16x16x32_bf16 v[156:159], v[64:67], v[80:83], v[156:159]
	v_mfma_f32_16x16x32_bf16 v[144:147], v[72:75], v[80:83], v[144:147]
	v_mfma_f32_16x16x32_bf16 v[140:143], v[64:67], v[88:91], v[140:143]
	v_mfma_f32_16x16x32_bf16 v[132:135], v[72:75], v[88:91], v[132:135]
	v_mfma_f32_16x16x32_bf16 v[124:127], v[64:67], v[180:183], v[124:127]
	v_mfma_f32_16x16x32_bf16 v[116:119], v[72:75], v[180:183], v[116:119]
	v_mfma_f32_16x16x32_bf16 v[112:115], v[64:67], v[188:191], v[112:115]
	v_mfma_f32_16x16x32_bf16 v[108:111], v[72:75], v[188:191], v[108:111]
	v_mfma_f32_16x16x32_bf16 v[156:159], v[68:71], v[84:87], v[156:159]
	v_mfma_f32_16x16x32_bf16 v[144:147], v[76:79], v[84:87], v[144:147]
	v_mfma_f32_16x16x32_bf16 v[140:143], v[68:71], v[92:95], v[140:143]
	v_mfma_f32_16x16x32_bf16 v[132:135], v[76:79], v[92:95], v[132:135]
	v_mfma_f32_16x16x32_bf16 v[124:127], v[68:71], v[184:187], v[124:127]
	v_mfma_f32_16x16x32_bf16 v[116:119], v[76:79], v[184:187], v[116:119]
	v_mfma_f32_16x16x32_bf16 v[112:115], v[68:71], v[192:195], v[112:115]
	v_mfma_f32_16x16x32_bf16 v[108:111], v[76:79], v[192:195], v[108:111]
	s_barrier
	s_setprio 0
	s_add_i32 m0, s64, 0xe000
	s_nop 0
	global_load_lds_dwordx4 v172, s[14:15]
	s_add_i32 s59, s72, s62
	s_add_u32 s98, s48, 0x80
	s_addc_u32 s99, s49, 0
	s_add_u32 s100, s50, 0x80
	s_addc_u32 s101, s51, 0
	s_mov_b32 m0, s59
	ds_read_b128 v[206:209], v203
	ds_read_b128 v[212:215], v203 offset:1024
	ds_read_b128 v[216:219], v203 offset:2048
	ds_read_b128 v[220:223], v203 offset:3072
	global_load_lds_dwordx4 v164, s[48:49]
	s_add_i32 m0, s59, 0x2000
	s_nop 0
	global_load_lds_dwordx4 v160, s[48:49]
	s_waitcnt lgkmcnt(0)
	s_setprio 1
	s_barrier
	v_mfma_f32_16x16x32_bf16 v[152:155], v[206:209], v[80:83], v[152:155]
	v_mfma_f32_16x16x32_bf16 v[80:83], v[216:219], v[80:83], v[148:151]
	v_mfma_f32_16x16x32_bf16 v[152:155], v[212:215], v[84:87], v[152:155]
	v_mfma_f32_16x16x32_bf16 v[80:83], v[220:223], v[84:87], v[80:83]
	v_mfma_f32_16x16x32_bf16 v[84:87], v[206:209], v[88:91], v[136:139]
	v_mfma_f32_16x16x32_bf16 v[88:91], v[216:219], v[88:91], v[128:131]
	v_mfma_f32_16x16x32_bf16 v[104:107], v[216:219], v[180:183], v[104:107]
	v_mfma_f32_16x16x32_bf16 v[100:103], v[206:209], v[188:191], v[100:103]
	v_mfma_f32_16x16x32_bf16 v[96:99], v[216:219], v[188:191], v[96:99]
	v_mfma_f32_16x16x32_bf16 v[84:87], v[212:215], v[92:95], v[84:87]
	v_mfma_f32_16x16x32_bf16 v[88:91], v[220:223], v[92:95], v[88:91]
	v_mfma_f32_16x16x32_bf16 v[92:95], v[206:209], v[180:183], v[120:123]
	v_mfma_f32_16x16x32_bf16 v[104:107], v[220:223], v[184:187], v[104:107]
	v_mfma_f32_16x16x32_bf16 v[100:103], v[212:215], v[192:195], v[100:103]
	v_mfma_f32_16x16x32_bf16 v[96:99], v[220:223], v[192:195], v[96:99]
	v_mfma_f32_16x16x32_bf16 v[92:95], v[212:215], v[184:187], v[92:95]
	s_barrier
	s_setprio 0
	s_mov_b32 m0, s64
	ds_read_b128 v[120:123], v202 offset:16384
	ds_read_b128 v[128:131], v202 offset:17408
	ds_read_b128 v[136:139], v202 offset:18432
	ds_read_b128 v[148:151], v202 offset:19456
	ds_read_b128 v[180:183], v202 offset:20480
	ds_read_b128 v[184:187], v202 offset:21504
	ds_read_b128 v[188:191], v202 offset:22528
	ds_read_b128 v[192:195], v202 offset:23552
	global_load_lds_dwordx4 v166, s[50:51]
	s_waitcnt vmcnt(9)
	s_waitcnt lgkmcnt(0)
	s_setprio 1
	s_barrier
	v_mfma_f32_16x16x32_bf16 v[60:63], v[64:67], v[120:123], v[60:63]
	v_mfma_f32_16x16x32_bf16 v[48:51], v[72:75], v[120:123], v[48:51]
	v_mfma_f32_16x16x32_bf16 v[44:47], v[64:67], v[136:139], v[44:47]
	v_mfma_f32_16x16x32_bf16 v[36:39], v[72:75], v[136:139], v[36:39]
	v_mfma_f32_16x16x32_bf16 v[28:31], v[64:67], v[180:183], v[28:31]
	v_mfma_f32_16x16x32_bf16 v[20:23], v[72:75], v[180:183], v[20:23]
	v_mfma_f32_16x16x32_bf16 v[16:19], v[64:67], v[188:191], v[16:19]
	v_mfma_f32_16x16x32_bf16 v[12:15], v[72:75], v[188:191], v[12:15]
	v_mfma_f32_16x16x32_bf16 v[60:63], v[68:71], v[128:131], v[60:63]
	v_mfma_f32_16x16x32_bf16 v[48:51], v[76:79], v[128:131], v[48:51]
	v_mfma_f32_16x16x32_bf16 v[44:47], v[68:71], v[148:151], v[44:47]
	v_mfma_f32_16x16x32_bf16 v[36:39], v[76:79], v[148:151], v[36:39]
	v_mfma_f32_16x16x32_bf16 v[28:31], v[68:71], v[184:187], v[28:31]
	v_mfma_f32_16x16x32_bf16 v[20:23], v[76:79], v[184:187], v[20:23]
	v_mfma_f32_16x16x32_bf16 v[16:19], v[68:71], v[192:195], v[16:19]
	v_mfma_f32_16x16x32_bf16 v[12:15], v[76:79], v[192:195], v[12:15]
	s_barrier
	s_setprio 0
	s_mov_b32 m0, s65
	s_nop 0
	global_load_lds_dwordx4 v162, s[50:51]
	s_add_u32 s78, s48, 0x80000
	s_addc_u32 s79, s49, 0
	s_add_i32 s59, s73, s62
	s_mov_b32 m0, s59
	s_nop 0
	global_load_lds_dwordx4 v164, s[78:79]
	s_add_i32 m0, s59, 0x2000
	s_nop 0
	global_load_lds_dwordx4 v160, s[78:79]
	s_add_i32 s59, 0, 0x18000
	v_add_u32_e32 v76, s59, v198
	ds_read_b128 v[64:67], v76
	ds_read_b128 v[68:71], v76 offset:1024
	ds_read_b128 v[72:75], v76 offset:2048
	ds_read_b128 v[76:79], v76 offset:3072
	s_waitcnt vmcnt(6)
	s_setprio 1
	s_barrier
; #define PG8_STAGE(bufoff, gbase, voff) do { _Pragma("unroll") for (int _i = 0; _i < 2; ++_i) \
;     __builtin_amdgcn_global_load_lds((const unsigned*)((const char*)(gbase) + (voff)[_i]), (LAS unsigned*)(lds + (bufoff) + ldsw + _i * 8192), 16, 0, 0); } while (0)
; #define PG8_LDA(dst, b, h) do { _Pragma("unroll") for (int m = 0; m < 4; ++m) _Pragma("unroll") for (int k = 0; k < 2; ++k) dst[m][k] = *(const LAS bf16x8*)(lds + PG8_SA(b, h) + aoff + m * 2048 + k * 1024); } while (0)
; #define PG8_LDB(dst, b, h) do { _Pragma("unroll") for (int n = 0; n < 2; ++n) _Pragma("unroll") for (int k = 0; k < 2; ++k) dst[n][k] = *(const LAS bf16x8*)(lds + PG8_SB(b, h) + boff + n * 2048 + k * 1024); } while (0)
; #define PG8_WAIT_V(n) asm volatile("s_waitcnt vmcnt(" #n ")" ::: "memory")
; template <class Epi, class Sched = StaticOrder>
; DI void gemm_phase(LAS unsigned char* lds, const Gemm g, const Sched& S, const Epi& E) {
;     ...
;     for (int t = 0; t < nt; t += 2) {
;       const bool last = (t == nt - 2);
;       const char* a1 = cA + (size_t)(t + 1) * kstep;
;       const char* a2 = last ? nA : cA + (size_t)(t + 2) * kstep; const char* b2 = last ? nB : cB + (size_t)(t + 2) * kstep;
;       const char* a3 = a2 + kstep; const char* b3 = b2 + kstep;
;       PG8_LDB(B0, 0, 0); PG8_SCHED; PG8_LDA(At, 0, 0); PG8_STAGE(PG8_SA(1, 1), a1 + hstep, voffA);
;       PG8_WAIT_L(8); PG8_BAR; PG8_WAIT_L(0); PG8_MMA(0, 0, At, B0); PG8_BAR; PG8_SCHED;
;       PG8_LDB(B1, 0, 1); PG8_STAGE(PG8_SB(0, 0), b2, voffB);
;       PG8_BAR; PG8_WAIT_L(0); PG8_MMA(0, 1, At, B1); PG8_BAR;
;       PG8_LDA(At, 0, 1); PG8_STAGE(PG8_SA(0, 0), a2, voffA);
;       PG8_BAR; PG8_WAIT_L(0); PG8_MMA(1, 0, At, B0); PG8_BAR; PG8_SCHED;
;       PG8_STAGE(PG8_SB(0, 1), b2 + hstep, voffB);
;       PG8_WAIT_V(6); PG8_BAR; PG8_MMA(1, 1, At, B1); PG8_BAR;
;       PG8_LDB(B0, 1, 0); PG8_SCHED; PG8_LDA(At, 1, 0); PG8_STAGE(PG8_SA(0, 1), a2 + hstep, voffA);
;       PG8_WAIT_L(8); PG8_BAR; PG8_WAIT_L(0); PG8_MMA(0, 0, At, B0); PG8_BAR; PG8_SCHED;
;       PG8_LDB(B1, 1, 1); PG8_STAGE(PG8_SB(1, 0), b3, voffB);
;       PG8_BAR; PG8_WAIT_L(0); PG8_MMA(0, 1, At, B1); PG8_BAR;
;       PG8_LDA(At, 1, 1); PG8_STAGE(PG8_SA(1, 0), a3, voffA);
;       PG8_BAR; PG8_WAIT_L(0); PG8_MMA(1, 0, At, B0); PG8_BAR; PG8_SCHED;
;       PG8_STAGE(PG8_SB(1, 1), b3 + hstep, voffB);
;       PG8_WAIT_V(6); PG8_BAR; PG8_MMA(1, 1, At, B1); PG8_BAR;
	v_mfma_f32_16x16x32_bf16 v[56:59], v[206:209], v[120:123], v[56:59]
	v_mfma_f32_16x16x32_bf16 v[52:55], v[216:219], v[120:123], v[52:55]
	v_mfma_f32_16x16x32_bf16 v[40:43], v[206:209], v[136:139], v[40:43]
	v_mfma_f32_16x16x32_bf16 v[32:35], v[216:219], v[136:139], v[32:35]
	v_mfma_f32_16x16x32_bf16 v[24:27], v[206:209], v[180:183], v[24:27]
	v_mfma_f32_16x16x32_bf16 v[8:11], v[216:219], v[180:183], v[8:11]
	v_mfma_f32_16x16x32_bf16 v[4:7], v[206:209], v[188:191], v[4:7]
	v_mfma_f32_16x16x32_bf16 v[0:3], v[216:219], v[188:191], v[0:3]
	v_mfma_f32_16x16x32_bf16 v[56:59], v[212:215], v[128:131], v[56:59]
	v_mfma_f32_16x16x32_bf16 v[52:55], v[220:223], v[128:131], v[52:55]
	v_mfma_f32_16x16x32_bf16 v[40:43], v[212:215], v[148:151], v[40:43]
	v_mfma_f32_16x16x32_bf16 v[32:35], v[220:223], v[148:151], v[32:35]
	v_mfma_f32_16x16x32_bf16 v[24:27], v[212:215], v[184:187], v[24:27]
	v_mfma_f32_16x16x32_bf16 v[8:11], v[220:223], v[184:187], v[8:11]
	v_mfma_f32_16x16x32_bf16 v[4:7], v[212:215], v[192:195], v[4:7]
	v_mfma_f32_16x16x32_bf16 v[0:3], v[220:223], v[192:195], v[0:3]
	s_barrier
	s_setprio 0
	s_add_u32 s50, s50, 0x80000
	s_addc_u32 s51, s51, 0
	s_mov_b32 m0, s66
	ds_read_b128 v[120:123], v202 offset:32768
	ds_read_b128 v[128:131], v202 offset:33792
	ds_read_b128 v[180:183], v202 offset:34816
	ds_read_b128 v[184:187], v202 offset:35840
	ds_read_b128 v[188:191], v202 offset:36864
	ds_read_b128 v[192:195], v202 offset:37888
	ds_read_b128 v[206:209], v202 offset:38912
	ds_read_b128 v[212:215], v202 offset:39936
	global_load_lds_dwordx4 v166, s[50:51]
	s_waitcnt lgkmcnt(0)
	s_setprio 1
	s_barrier
	v_mfma_f32_16x16x32_bf16 v[136:139], v[64:67], v[120:123], v[156:159]
	v_mfma_f32_16x16x32_bf16 v[156:159], v[68:71], v[128:131], v[136:139]
	v_mfma_f32_16x16x32_bf16 v[136:139], v[72:75], v[120:123], v[144:147]
	v_mfma_f32_16x16x32_bf16 v[144:147], v[76:79], v[128:131], v[136:139]
	v_mfma_f32_16x16x32_bf16 v[136:139], v[64:67], v[180:183], v[140:143]
	v_mfma_f32_16x16x32_bf16 v[132:135], v[72:75], v[180:183], v[132:135]
	v_mfma_f32_16x16x32_bf16 v[124:127], v[64:67], v[188:191], v[124:127]
	v_mfma_f32_16x16x32_bf16 v[116:119], v[72:75], v[188:191], v[116:119]
	v_mfma_f32_16x16x32_bf16 v[112:115], v[64:67], v[206:209], v[112:115]
	v_mfma_f32_16x16x32_bf16 v[108:111], v[72:75], v[206:209], v[108:111]
	v_mfma_f32_16x16x32_bf16 v[140:143], v[68:71], v[184:187], v[136:139]
	v_mfma_f32_16x16x32_bf16 v[132:135], v[76:79], v[184:187], v[132:135]
	v_mfma_f32_16x16x32_bf16 v[124:127], v[68:71], v[192:195], v[124:127]
	v_mfma_f32_16x16x32_bf16 v[116:119], v[76:79], v[192:195], v[116:119]
	v_mfma_f32_16x16x32_bf16 v[112:115], v[68:71], v[212:215], v[112:115]
	v_mfma_f32_16x16x32_bf16 v[108:111], v[76:79], v[212:215], v[108:111]
	s_barrier
	s_setprio 0
	s_mov_b32 m0, s67
	s_nop 0
	global_load_lds_dwordx4 v162, s[50:51]
	s_add_i32 s50, 0, 0x1c000
	v_add_u32_e32 v136, s50, v198
	s_add_i32 s51, s59, s62
	ds_read_b128 v[216:219], v136
	ds_read_b128 v[220:223], v136 offset:1024
	ds_read_b128 v[224:227], v136 offset:2048
	ds_read_b128 v[228:231], v136 offset:3072
	s_mov_b32 m0, s51
	s_nop 0
	global_load_lds_dwordx4 v164, s[98:99]
	s_add_i32 m0, s51, 0x2000
	s_nop 0
	global_load_lds_dwordx4 v160, s[98:99]
	s_waitcnt lgkmcnt(0)
	s_setprio 1
	s_barrier
	v_mfma_f32_16x16x32_bf16 v[80:83], v[224:227], v[120:123], v[80:83]
	v_mfma_f32_16x16x32_bf16 v[136:139], v[216:219], v[120:123], v[152:155]
	v_mfma_f32_16x16x32_bf16 v[148:151], v[228:231], v[128:131], v[80:83]
	v_mfma_f32_16x16x32_bf16 v[80:83], v[216:219], v[180:183], v[84:87]
	v_mfma_f32_16x16x32_bf16 v[152:155], v[220:223], v[128:131], v[136:139]
	v_mfma_f32_16x16x32_bf16 v[136:139], v[220:223], v[184:187], v[80:83]
	v_mfma_f32_16x16x32_bf16 v[80:83], v[224:227], v[180:183], v[88:91]
	v_mfma_f32_16x16x32_bf16 v[128:131], v[228:231], v[184:187], v[80:83]
	v_mfma_f32_16x16x32_bf16 v[80:83], v[216:219], v[188:191], v[92:95]
	v_mfma_f32_16x16x32_bf16 v[120:123], v[220:223], v[192:195], v[80:83]
	v_mfma_f32_16x16x32_bf16 v[80:83], v[224:227], v[188:191], v[104:107]
	v_mfma_f32_16x16x32_bf16 v[104:107], v[228:231], v[192:195], v[80:83]
	v_mfma_f32_16x16x32_bf16 v[80:83], v[216:219], v[206:209], v[100:103]
	v_mfma_f32_16x16x32_bf16 v[100:103], v[220:223], v[212:215], v[80:83]
	v_mfma_f32_16x16x32_bf16 v[80:83], v[224:227], v[206:209], v[96:99]
	v_mfma_f32_16x16x32_bf16 v[96:99], v[228:231], v[212:215], v[80:83]
	s_barrier
	s_setprio 0
	s_mov_b32 m0, s55
	s_nop 2
	ds_read_b128 v[80:83], v202 offset:49152
	ds_read_b128 v[84:87], v202 offset:50176
	ds_read_b128 v[88:91], v202 offset:51200
	ds_read_b128 v[92:95], v202 offset:52224
	ds_read_b128 v[180:183], v202 offset:53248
	ds_read_b128 v[184:187], v202 offset:54272
	ds_read_b128 v[188:191], v202 offset:55296
	ds_read_b128 v[192:195], v202 offset:56320
	global_load_lds_dwordx4 v166, s[100:101]
	s_waitcnt vmcnt(9)
	s_waitcnt lgkmcnt(0)
	s_setprio 1
	s_barrier
	v_mfma_f32_16x16x32_bf16 v[60:63], v[64:67], v[80:83], v[60:63]
	v_mfma_f32_16x16x32_bf16 v[48:51], v[72:75], v[80:83], v[48:51]
	v_mfma_f32_16x16x32_bf16 v[44:47], v[64:67], v[88:91], v[44:47]
	v_mfma_f32_16x16x32_bf16 v[36:39], v[72:75], v[88:91], v[36:39]
	v_mfma_f32_16x16x32_bf16 v[28:31], v[64:67], v[180:183], v[28:31]
	v_mfma_f32_16x16x32_bf16 v[20:23], v[72:75], v[180:183], v[20:23]
	v_mfma_f32_16x16x32_bf16 v[16:19], v[64:67], v[188:191], v[16:19]
	v_mfma_f32_16x16x32_bf16 v[12:15], v[72:75], v[188:191], v[12:15]
	v_mfma_f32_16x16x32_bf16 v[60:63], v[68:71], v[84:87], v[60:63]
	v_mfma_f32_16x16x32_bf16 v[48:51], v[76:79], v[84:87], v[48:51]
	v_mfma_f32_16x16x32_bf16 v[44:47], v[68:71], v[92:95], v[44:47]
	v_mfma_f32_16x16x32_bf16 v[36:39], v[76:79], v[92:95], v[36:39]
	v_mfma_f32_16x16x32_bf16 v[28:31], v[68:71], v[184:187], v[28:31]
	v_mfma_f32_16x16x32_bf16 v[20:23], v[76:79], v[184:187], v[20:23]
	v_mfma_f32_16x16x32_bf16 v[16:19], v[68:71], v[192:195], v[16:19]
	v_mfma_f32_16x16x32_bf16 v[12:15], v[76:79], v[192:195], v[12:15]
	s_barrier
; #define PG8_STAGE(bufoff, gbase, voff) do { _Pragma("unroll") for (int _i = 0; _i < 2; ++_i) \
;     __builtin_amdgcn_global_load_lds((const unsigned*)((const char*)(gbase) + (voff)[_i]), (LAS unsigned*)(lds + (bufoff) + ldsw + _i * 8192), 16, 0, 0); } while (0)
; #define PG8_MMA(ai, bj, At, Bt) do { __builtin_amdgcn_s_setprio(1); _Pragma("unroll") for (int m = 0; m < 4; ++m) _Pragma("unroll") for (int n = 0; n < 2; ++n) _Pragma("unroll") for (int k = 0; k < 2; ++k) \
;     acc[ai][bj][m][n] = __builtin_amdgcn_mfma_f32_16x16x32_bf16(Bt[n][k], At[m][k], acc[ai][bj][m][n], 0, 0, 0); __builtin_amdgcn_s_setprio(0); } while (0)
; #define PG8_WAIT_V(n) asm volatile("s_waitcnt vmcnt(" #n ")" ::: "memory")
; #define PG8_WAIT_L(n) asm volatile("s_waitcnt lgkmcnt(" #n ")" ::: "memory")
; #define PG8_BAR __builtin_amdgcn_s_barrier()
; #define PG8_SCHED __builtin_amdgcn_sched_barrier(0)
;   DI void operator()(const f32x4 (&acc)[2][2][4][2], const Unit& u, int wr, int wc, int fr, int fq) const {
;     const int col = u.pn * 128 + wc * 32 + 8 * fq;
;     float w0[8], w1[8], w2[8], bb[8];
; #pragma unroll
;     for (int e = 0; e < 8; ++e) { w0[e] = cw[col + e]; w1[e] = cw[5632 + col + e]; w2[e] = cw[2 * 5632 + col + e]; bb[e] = cb[col + e]; }
; #pragma unroll
;     for (int ai = 0; ai < 2; ++ai) {
;       const int row0 = u.pm * BM + ai * HALF + wr * 64, span = row0 >> 6;
;       float rsv[4];
; #pragma unroll
;       for (int m = 0; m < 4; ++m) rsv[m] = row_rstd(ssq, row0 + 16 * m + fr, fq);
; template <class Epi, class Sched = StaticOrder>
; DI void gemm_phase(LAS unsigned char* lds, const Gemm g, const Sched& S, const Epi& E) {
;     ...
;       PG8_BAR; PG8_WAIT_L(0); PG8_MMA(1, 0, At, B0); PG8_BAR; PG8_SCHED;
;       PG8_STAGE(PG8_SB(1, 1), b3 + hstep, voffB);
;       PG8_WAIT_V(6); PG8_BAR; PG8_MMA(1, 1, At, B1); PG8_BAR;
;     }
;     E(acc, cur, wr, wc, fr, fq);
	s_setprio 0
	s_mov_b32 m0, s68
	s_nop 0
	global_load_lds_dwordx4 v162, s[100:101]
	s_add_u32 s48, s48, 0x80080
	s_addc_u32 s49, s49, 0
	s_add_i32 s50, s50, s62
	s_mov_b32 m0, s50
	s_nop 0
	global_load_lds_dwordx4 v164, s[48:49]
	s_add_i32 m0, s50, 0x2000
	s_nop 0
	global_load_lds_dwordx4 v160, s[48:49]
	ds_read_b128 v[64:67], v201
	ds_read_b128 v[68:71], v201 offset:1024
	ds_read_b128 v[72:75], v201 offset:2048
	ds_read_b128 v[76:79], v201 offset:3072
	s_waitcnt vmcnt(6)
	s_setprio 1
	s_barrier
	v_mfma_f32_16x16x32_bf16 v[56:59], v[216:219], v[80:83], v[56:59]
	v_mfma_f32_16x16x32_bf16 v[52:55], v[224:227], v[80:83], v[52:55]
	v_mfma_f32_16x16x32_bf16 v[40:43], v[216:219], v[88:91], v[40:43]
	v_mfma_f32_16x16x32_bf16 v[32:35], v[224:227], v[88:91], v[32:35]
	v_mfma_f32_16x16x32_bf16 v[24:27], v[216:219], v[180:183], v[24:27]
	v_mfma_f32_16x16x32_bf16 v[8:11], v[224:227], v[180:183], v[8:11]
	v_mfma_f32_16x16x32_bf16 v[4:7], v[216:219], v[188:191], v[4:7]
	v_mfma_f32_16x16x32_bf16 v[0:3], v[224:227], v[188:191], v[0:3]
	v_mfma_f32_16x16x32_bf16 v[56:59], v[220:223], v[84:87], v[56:59]
	v_mfma_f32_16x16x32_bf16 v[52:55], v[228:231], v[84:87], v[52:55]
	v_mfma_f32_16x16x32_bf16 v[40:43], v[220:223], v[92:95], v[40:43]
	v_mfma_f32_16x16x32_bf16 v[32:35], v[228:231], v[92:95], v[32:35]
	v_mfma_f32_16x16x32_bf16 v[24:27], v[220:223], v[184:187], v[24:27]
	v_mfma_f32_16x16x32_bf16 v[8:11], v[228:231], v[184:187], v[8:11]
	v_mfma_f32_16x16x32_bf16 v[4:7], v[220:223], v[192:195], v[4:7]
	v_mfma_f32_16x16x32_bf16 v[0:3], v[228:231], v[192:195], v[0:3]
	s_add_i32 s58, s58, 2
	s_add_u32 s14, s14, 0x100
	s_addc_u32 s15, s15, 0
	s_add_u32 s52, s52, 0x100
	s_addc_u32 s53, s53, 0
	s_cmp_gt_u32 s58, 29
	s_barrier
	s_setprio 0
	s_cbranch_scc0 .LBB0_1277
	s_waitcnt lgkmcnt(0)
	s_lshl_b32 s39, s12, 8
	s_add_i32 s39, s39, s54
	v_or_b32_e32 v190, s39, v179
	v_ashrrev_i32_e32 v191, 31, v190
	v_lshlrev_b64 v[64:65], 7, v[190:191]
	v_or_b32_e32 v188, 16, v190
	v_lshl_add_u64 v[64:65], v[168:169], 0, v[64:65]
	v_ashrrev_i32_e32 v189, 31, v188
	global_load_dwordx4 v[192:195], v[64:65], off
	global_load_dwordx4 v[206:209], v[64:65], off offset:16
	v_lshlrev_b64 v[64:65], 7, v[188:189]
	v_lshl_add_u64 v[64:65], v[168:169], 0, v[64:65]
	global_load_dwordx4 v[212:215], v[64:65], off
	global_load_dwordx4 v[216:219], v[64:65], off offset:16
	v_or_b32_e32 v186, 32, v190
	v_ashrrev_i32_e32 v187, 31, v186
	v_lshlrev_b64 v[64:65], 7, v[186:187]
	v_or_b32_e32 v184, 48, v190
	v_lshl_add_u64 v[64:65], v[168:169], 0, v[64:65]
	v_ashrrev_i32_e32 v185, 31, v184
	global_load_dwordx4 v[220:223], v[64:65], off
	global_load_dwordx4 v[224:227], v[64:65], off offset:16
	v_lshlrev_b64 v[64:65], 7, v[184:185]
	v_lshl_add_u64 v[64:65], v[168:169], 0, v[64:65]
	global_load_dwordx4 v[228:231], v[64:65], off
	global_load_dwordx4 v[232:235], v[64:65], off offset:16
	v_lshl_or_b32 v180, s13, 7, v200
	v_and_b32_e32 v65, 64, v204
	v_xor_b32_e32 v64, 16, v204
	v_ashrrev_i32_e32 v181, 31, v180
	v_add_u32_e32 v65, 64, v65
	v_xor_b32_e32 v66, 32, v204
	v_lshlrev_b64 v[182:183], 2, v[180:181]
	v_cmp_lt_i32_e32 vcc, v64, v65
	v_lshl_add_u64 v[88:89], s[16:17], 0, v[182:183]
	v_lshl_add_u64 v[72:73], s[18:19], 0, v[182:183]
	v_cndmask_b32_e32 v64, v204, v64, vcc
	v_cmp_lt_i32_e32 vcc, v66, v65
	v_lshl_add_u64 v[74:75], v[88:89], 0, s[30:31]
	v_lshl_add_u64 v[76:77], v[88:89], 0, s[34:35]
	v_cndmask_b32_e32 v65, v204, v66, vcc
	v_add_co_u32_e32 v90, vcc, 0x5000, v88
	v_lshlrev_b32_e32 v187, 2, v64
	s_nop 0
	v_addc_co_u32_e32 v91, vcc, 0, v89, vcc
	v_add_co_u32_e32 v92, vcc, 0xb000, v88
	v_lshlrev_b32_e32 v185, 2, v65
	s_nop 0
	v_addc_co_u32_e32 v93, vcc, 0, v89, vcc
	global_load_dwordx4 v[64:67], v[88:89], off offset:16
	global_load_dwordx4 v[80:83], v[88:89], off
	global_load_dwordx4 v[68:71], v[72:73], off offset:16
	global_load_dwordx4 v[84:87], v[72:73], off
	s_nop 0
	global_load_dwordx4 v[72:75], v[74:75], off offset:16
	s_nop 0
	global_load_dwordx4 v[76:79], v[76:77], off offset:16
	s_nop 0
	global_load_dwordx4 v[88:91], v[90:91], off offset:2048
	s_nop 0
	global_load_dwordx4 v[92:95], v[92:93], off
	v_mov_b32_e32 v211, 0
	v_mov_b32_e32 v205, 0
	s_waitcnt vmcnt(0)
	v_mov_b32_e32 v196, v192
	v_mov_b32_e32 v197, v206
	v_mov_b32_e32 v206, v193
	v_mov_b32_e32 v192, v194
	v_mov_b32_e32 v193, v208
	v_mov_b32_e32 v208, v195
	v_pk_add_f32 v[194:195], v[196:197], v[206:207]
	v_pk_add_f32 v[192:193], v[192:193], v[208:209]
	v_mov_b32_e32 v196, v212
	v_mov_b32_e32 v197, v216
	v_mov_b32_e32 v216, v213
	v_mov_b32_e32 v206, v214
	v_mov_b32_e32 v207, v218
	v_mov_b32_e32 v218, v215
	v_pk_add_f32 v[192:193], v[194:195], v[192:193]
	v_pk_add_f32 v[194:195], v[196:197], v[216:217]
	v_pk_add_f32 v[196:197], v[206:207], v[218:219]
	v_mov_b32_e32 v208, v220
	v_pk_add_f32 v[194:195], v[194:195], v[196:197]
	v_mov_b32_e32 v197, v192
	v_mov_b32_e32 v196, v194
	v_mov_b32_e32 v192, v195
	v_pk_add_f32 v[192:193], v[196:197], v[192:193]
	ds_bpermute_b32 v195, v187, v193
	ds_bpermute_b32 v194, v187, v192
	v_mov_b32_e32 v209, v224
	v_mov_b32_e32 v224, v221
	v_mov_b32_e32 v212, v222
	v_mov_b32_e32 v213, v226
	s_waitcnt lgkmcnt(0)
	v_pk_add_f32 v[192:193], v[192:193], v[194:195]
	ds_bpermute_b32 v195, v185, v193
	ds_bpermute_b32 v194, v185, v192
	v_mov_b32_e32 v226, v223
	v_mov_b32_e32 v196, v228
	v_mov_b32_e32 v197, v232
	v_mov_b32_e32 v232, v229
	s_waitcnt lgkmcnt(0)
; DI unsigned pack2(float lo, float hi) { f32x2 v = {lo, hi}; bf16v2 r = __builtin_convertvector(v, bf16v2); return __builtin_bit_cast(unsigned, r); }
; DI float silu_f(float x) { return x * sigmoid_f(x); }
; DI float dpp_ror1(float v) { return __int_as_float(__builtin_amdgcn_update_dpp(0, __float_as_int(v), 0x121, 0xf, 0xf, false)); }
; DI float dpp_ror2(float v) { return __int_as_float(__builtin_amdgcn_update_dpp(0, __float_as_int(v), 0x122, 0xf, 0xf, false)); }
;   DI void operator()(const f32x4 (&acc)[2][2][4][2], const Unit& u, int wr, int wc, int fr, int fq) const {
;     ...
;       float p1[8], p2[8];
; #pragma unroll
;       for (int e = 0; e < 8; ++e) { p1[e] = 0.f; p2[e] = 0.f; }
; #pragma unroll
;       for (int m = 0; m < 4; ++m) {
;         float g[8], uu[8], a[8];
;         const float rs = rsv[m];
; #pragma unroll
;         for (int e = 0; e < 4; ++e) { g[e] = acc[ai][0][m][0][e] * rs; g[4 + e] = acc[ai][0][m][1][e] * rs; uu[e] = acc[ai][1][m][0][e] * rs; uu[4 + e] = acc[ai][1][m][1][e] * rs; }
; #pragma unroll
;         for (int e = 0; e < 8; ++e) {
;           const float x1 = dpp_ror1(g[e]), x2 = dpp_ror2(g[e]);
;           const float pr1 = (fr == 0) ? p1[e] : x1, pr2 = (fr < 2) ? p2[e] : x2;
;           a[e] = w2[e] * g[e] + w1[e] * pr1 + w0[e] * pr2 + bb[e];
;           p1[e] = x1; p2[e] = x2;
;         }
;         if (m == 0 && fr < 2) {
;           float* ha = headA + (size_t)(span * 2 + fr) * 5632 + col; float* hu = headU + (size_t)(span * 2 + fr) * 5632 + col;
;           *(f32x4*)ha = (f32x4){a[0], a[1], a[2], a[3]}; *(f32x4*)(ha + 4) = (f32x4){a[4], a[5], a[6], a[7]};
;           *(f32x4*)hu = (f32x4){uu[0], uu[1], uu[2], uu[3]}; *(f32x4*)(hu + 4) = (f32x4){uu[4], uu[5], uu[6], uu[7]};
;         } else {
;           u32x4 w;
;           w.x = pack2(silu_f(a[0]) * uu[0], silu_f(a[1]) * uu[1]);
;           w.y = pack2(silu_f(a[2]) * uu[2], silu_f(a[3]) * uu[3]);
;           w.z = pack2(silu_f(a[4]) * uu[4], silu_f(a[5]) * uu[5]);
;           w.w = pack2(silu_f(a[6]) * uu[6], silu_f(a[7]) * uu[7]);
;           *(u32x4*)(H + (size_t)(row0 + 16 * m + fr) * 5632 + col) = w;
	v_pk_add_f32 v[192:193], v[192:193], v[194:195]
	v_mov_b32_e32 v206, v230
	v_pk_fma_f32 v[192:193], v[192:193], s[36:37], v[178:179] op_sel_hi:[1,0,0]
	v_mov_b32_e32 v207, v234
	v_mul_f32_e32 v189, 0x4b800000, v193
	v_cmp_gt_f32_e64 s[12:13], s74, v193
	v_mov_b32_e32 v234, v231
	v_pk_add_f32 v[208:209], v[208:209], v[224:225]
	v_cndmask_b32_e64 v189, v193, v189, s[12:13]
	v_rsq_f32_e32 v189, v189
	v_pk_add_f32 v[212:213], v[212:213], v[226:227]
	v_pk_add_f32 v[196:197], v[196:197], v[232:233]
	v_pk_add_f32 v[194:195], v[206:207], v[234:235]
	v_mul_f32_e32 v191, 0x45800000, v189
	v_cndmask_b32_e64 v220, v189, v191, s[12:13]
	v_pk_add_f32 v[208:209], v[208:209], v[212:213]
	v_pk_add_f32 v[194:195], v[196:197], v[194:195]
	v_pk_mul_f32 v[156:157], v[156:157], v[220:221] op_sel_hi:[1,0]
	v_mov_b32_e32 v216, 0
	v_mov_b32_e32 v218, 0
	v_mov_b32_e32 v196, v194
	v_mov_b32_e32 v197, v208
	v_mov_b32_e32 v208, v195
	v_mov_b32_dpp v216, v156 row_ror:1 row_mask:0xf bank_mask:0xf
	v_mov_b32_dpp v218, v157 row_ror:1 row_mask:0xf bank_mask:0xf
	v_pk_add_f32 v[194:195], v[196:197], v[208:209]
	v_cndmask_b32_e64 v207, v218, 0, s[0:1]
	v_cndmask_b32_e64 v206, v216, 0, s[0:1]
	v_pk_mul_f32 v[158:159], v[158:159], v[220:221] op_sel_hi:[1,0]
	v_mov_b32_e32 v212, 0
	v_mov_b32_e32 v214, 0
	ds_bpermute_b32 v197, v187, v195
	ds_bpermute_b32 v196, v187, v194
	v_mov_b32_e32 v215, 0
	v_mov_b32_e32 v217, 0
	v_pk_mul_f32 v[206:207], v[88:89], v[206:207]
	v_mov_b32_dpp v212, v158 row_ror:1 row_mask:0xf bank_mask:0xf
	v_mov_b32_dpp v214, v159 row_ror:1 row_mask:0xf bank_mask:0xf
	v_mov_b32_dpp v215, v156 row_ror:2 row_mask:0xf bank_mask:0xf
	v_mov_b32_dpp v217, v157 row_ror:2 row_mask:0xf bank_mask:0xf
	v_pk_fma_f32 v[156:157], v[92:93], v[156:157], v[206:207]
	v_mov_b32_e32 v213, 0
	v_cndmask_b32_e64 v207, v214, 0, s[0:1]
	v_cndmask_b32_e64 v206, v212, 0, s[0:1]
	v_cndmask_b32_e64 v209, v217, 0, s[4:5]
	v_cndmask_b32_e64 v208, v215, 0, s[4:5]
	v_mov_b32_dpp v211, v158 row_ror:2 row_mask:0xf bank_mask:0xf
	v_mov_b32_dpp v213, v159 row_ror:2 row_mask:0xf bank_mask:0xf
	v_pk_mul_f32 v[206:207], v[90:91], v[206:207]
	v_pk_fma_f32 v[156:157], v[80:81], v[208:209], v[156:157]
	v_cndmask_b32_e64 v209, v213, 0, s[4:5]
	v_cndmask_b32_e64 v208, v211, 0, s[4:5]
	v_pk_fma_f32 v[158:159], v[94:95], v[158:159], v[206:207]
	v_pk_mul_f32 v[144:145], v[144:145], v[220:221] op_sel_hi:[1,0]
	v_pk_fma_f32 v[158:159], v[82:83], v[208:209], v[158:159]
	v_mov_b32_e32 v207, 0
	v_mov_b32_e32 v209, 0
	v_pk_mul_f32 v[146:147], v[146:147], v[220:221] op_sel_hi:[1,0]
	v_mov_b32_e32 v191, 0
	s_waitcnt lgkmcnt(0)
	v_pk_add_f32 v[194:195], v[194:195], v[196:197]
	v_mov_b32_dpp v207, v144 row_ror:1 row_mask:0xf bank_mask:0xf
	v_mov_b32_dpp v209, v145 row_ror:1 row_mask:0xf bank_mask:0xf
	v_mov_b32_dpp v191, v146 row_ror:1 row_mask:0xf bank_mask:0xf
	v_mov_b32_dpp v205, v147 row_ror:1 row_mask:0xf bank_mask:0xf
	ds_bpermute_b32 v197, v185, v195
	ds_bpermute_b32 v196, v185, v194
	v_pk_mul_f32 v[152:153], v[152:153], v[220:221] op_sel_hi:[1,0]
	v_pk_mul_f32 v[148:149], v[148:149], v[220:221] op_sel_hi:[1,0]
	v_pk_mul_f32 v[154:155], v[154:155], v[220:221] op_sel_hi:[1,0]
	v_pk_mul_f32 v[150:151], v[150:151], v[220:221] op_sel_hi:[1,0]
	v_mov_b32_e32 v206, 0
	v_mov_b32_e32 v208, 0
	v_cndmask_b32_e64 v223, v209, 0, s[0:1]
	v_cndmask_b32_e64 v222, v207, 0, s[0:1]
	v_mov_b32_e32 v189, 0
	v_mov_b32_e32 v193, 0
	v_cndmask_b32_e64 v221, v205, 0, s[0:1]
	v_cndmask_b32_e64 v220, v191, 0, s[0:1]
	v_mov_b32_dpp v206, v144 row_ror:2 row_mask:0xf bank_mask:0xf
	v_mov_b32_dpp v208, v145 row_ror:2 row_mask:0xf bank_mask:0xf
	v_pk_mul_f32 v[222:223], v[72:73], v[222:223]
	v_mov_b32_dpp v189, v146 row_ror:2 row_mask:0xf bank_mask:0xf
	v_mov_b32_dpp v193, v147 row_ror:2 row_mask:0xf bank_mask:0xf
	v_pk_mul_f32 v[220:221], v[74:75], v[220:221]
	v_cndmask_b32_e64 v225, v208, 0, s[4:5]
	v_cndmask_b32_e64 v224, v206, 0, s[4:5]
	v_pk_fma_f32 v[144:145], v[76:77], v[144:145], v[222:223]
	v_cndmask_b32_e64 v223, v193, 0, s[4:5]
	v_cndmask_b32_e64 v222, v189, 0, s[4:5]
	v_pk_fma_f32 v[146:147], v[78:79], v[146:147], v[220:221]
	v_pk_fma_f32 v[144:145], v[64:65], v[224:225], v[144:145]
	v_pk_fma_f32 v[146:147], v[66:67], v[222:223], v[146:147]
	v_cmp_gt_f32_e32 vcc, s74, v192
	v_pk_add_f32 v[156:157], v[84:85], v[156:157]
	v_pk_add_f32 v[158:159], v[86:87], v[158:159]
	v_pk_add_f32 v[144:145], v[68:69], v[144:145]
	v_pk_add_f32 v[146:147], v[70:71], v[146:147]
	s_and_saveexec_b64 s[12:13], s[10:11]
	s_xor_b64 s[12:13], exec, s[12:13]
	s_cbranch_execz .LBB0_1280
	v_mul_f32_e32 v219, 0xbfb8aa3b, v156
	v_exp_f32_e32 v219, v219
	v_mul_f32_e32 v220, 0xbfb8aa3b, v157
	v_exp_f32_e32 v220, v220
	v_mul_f32_e32 v222, 0xbfb8aa3b, v159
	v_add_f32_e32 v219, 1.0, v219
	v_exp_f32_e32 v223, v222
	v_add_f32_e32 v221, 1.0, v220
	v_rcp_f32_e32 v220, v219
	v_mul_f32_e32 v219, 0xbfb8aa3b, v158
	v_exp_f32_e32 v219, v219
	v_rcp_f32_e32 v221, v221
	v_add_f32_e32 v219, 1.0, v219
	v_rcp_f32_e32 v222, v219
	v_add_f32_e32 v219, 1.0, v223
	v_rcp_f32_e32 v223, v219
	v_pk_mul_f32 v[156:157], v[156:157], v[220:221]
	s_nop 0
	v_pk_mul_f32 v[152:153], v[152:153], v[156:157]
	v_pk_mul_f32 v[156:157], v[158:159], v[222:223]
	v_cvt_pk_bf16_f32 v152, v152, v153
	v_mul_f32_e32 v153, 0xbfb8aa3b, v144
	v_pk_mul_f32 v[154:155], v[154:155], v[156:157]
	v_exp_f32_e32 v156, v153
	v_mul_f32_e32 v153, 0xbfb8aa3b, v145
	v_exp_f32_e32 v157, v153
	v_cvt_pk_bf16_f32 v153, v154, v155
	v_add_f32_e32 v154, 1.0, v156
	v_mul_f32_e32 v156, 0xbfb8aa3b, v146
	v_add_f32_e32 v155, 1.0, v157
	v_mul_f32_e32 v157, 0xbfb8aa3b, v147
	v_exp_f32_e32 v156, v156
	v_exp_f32_e32 v157, v157
	v_rcp_f32_e32 v154, v154
	v_rcp_f32_e32 v155, v155
	v_add_f32_e32 v156, 1.0, v156
	v_add_f32_e32 v157, 1.0, v157
	v_rcp_f32_e32 v156, v156
	v_rcp_f32_e32 v157, v157
	v_pk_mul_f32 v[144:145], v[144:145], v[154:155]
	s_nop 0
	v_pk_mul_f32 v[144:145], v[148:149], v[144:145]
	s_nop 0
	v_cvt_pk_bf16_f32 v154, v144, v145
	v_pk_mul_f32 v[144:145], v[146:147], v[156:157]
	s_nop 0
	v_pk_mul_f32 v[144:145], v[150:151], v[144:145]
	s_nop 0
	v_cvt_pk_bf16_f32 v155, v144, v145
	v_mov_b64_e32 v[144:145], s[20:21]
	v_mad_i64_i32 v[144:145], s[14:15], v190, s75, v[144:145]
	v_lshl_add_u64 v[144:145], v[180:181], 1, v[144:145]
	global_store_dwordx4 v[144:145], v[152:155], off

; #define PG8_STAGE(bufoff, gbase, voff) do { _Pragma("unroll") for (int _i = 0; _i < 2; ++_i) \
;     __builtin_amdgcn_global_load_lds((const unsigned*)((const char*)(gbase) + (voff)[_i]), (LAS unsigned*)(lds + (bufoff) + ldsw + _i * 8192), 16, 0, 0); } while (0)
; #define PG8_LDA(dst, b, h) do { _Pragma("unroll") for (int m = 0; m < 4; ++m) _Pragma("unroll") for (int k = 0; k < 2; ++k) dst[m][k] = *(const LAS bf16x8*)(lds + PG8_SA(b, h) + aoff + m * 2048 + k * 1024); } while (0)
; #define PG8_LDB(dst, b, h) do { _Pragma("unroll") for (int n = 0; n < 2; ++n) _Pragma("unroll") for (int k = 0; k < 2; ++k) dst[n][k] = *(const LAS bf16x8*)(lds + PG8_SB(b, h) + boff + n * 2048 + k * 1024); } while (0)
; #define PG8_WAIT_V(n) asm volatile("s_waitcnt vmcnt(" #n ")" ::: "memory")
; template <class Epi, class Sched = StaticOrder>
; DI void gemm_phase(LAS unsigned char* lds, const Gemm g, const Sched& S, const Epi& E) {
;     ...
;     for (int t = 0; t < nt; t += 2) {
;       const bool last = (t == nt - 2);
;       const char* a1 = cA + (size_t)(t + 1) * kstep;
;       const char* a2 = last ? nA : cA + (size_t)(t + 2) * kstep; const char* b2 = last ? nB : cB + (size_t)(t + 2) * kstep;
;       const char* a3 = a2 + kstep; const char* b3 = b2 + kstep;
;       PG8_LDB(B0, 0, 0); PG8_SCHED; PG8_LDA(At, 0, 0); PG8_STAGE(PG8_SA(1, 1), a1 + hstep, voffA);
;       PG8_WAIT_L(8); PG8_BAR; PG8_WAIT_L(0); PG8_MMA(0, 0, At, B0); PG8_BAR; PG8_SCHED;
;       PG8_LDB(B1, 0, 1); PG8_STAGE(PG8_SB(0, 0), b2, voffB);
;       PG8_BAR; PG8_WAIT_L(0); PG8_MMA(0, 1, At, B1); PG8_BAR;
;       PG8_LDA(At, 0, 1); PG8_STAGE(PG8_SA(0, 0), a2, voffA);
;       PG8_BAR; PG8_WAIT_L(0); PG8_MMA(1, 0, At, B0); PG8_BAR; PG8_SCHED;
;       PG8_STAGE(PG8_SB(0, 1), b2 + hstep, voffB);
;       PG8_WAIT_V(6); PG8_BAR; PG8_MMA(1, 1, At, B1); PG8_BAR;
;       PG8_LDB(B0, 1, 0); PG8_SCHED; PG8_LDA(At, 1, 0); PG8_STAGE(PG8_SA(0, 1), a2 + hstep, voffA);
;       PG8_WAIT_L(8); PG8_BAR; PG8_WAIT_L(0); PG8_MMA(0, 0, At, B0); PG8_BAR; PG8_SCHED;
;       PG8_LDB(B1, 1, 1); PG8_STAGE(PG8_SB(1, 0), b3, voffB);
;       PG8_BAR; PG8_WAIT_L(0); PG8_MMA(0, 1, At, B1); PG8_BAR;
;       PG8_LDA(At, 1, 1); PG8_STAGE(PG8_SA(1, 0), a3, voffA);
;       PG8_BAR; PG8_WAIT_L(0); PG8_MMA(1, 0, At, B0); PG8_BAR; PG8_SCHED;
;       PG8_STAGE(PG8_SB(1, 1), b3 + hstep, voffB);
;       PG8_WAIT_V(6); PG8_BAR; PG8_MMA(1, 1, At, B1); PG8_BAR;
.LBB0_1424:
	s_add_u32 s18, s16, 0xffea0080
	s_addc_u32 s19, s17, -1
	s_cmpk_eq_i32 s47, 0x54
	s_cselect_b32 s21, s3, s19
	s_cselect_b32 s20, s2, s18
	s_cselect_b32 s19, s5, s46
	s_cselect_b32 s18, s4, s45
	s_add_i32 m0, s30, 0xc000
	ds_read_b128 v[166:169], v160
	ds_read_b128 v[170:173], v160 offset:1024
	ds_read_b128 v[174:177], v160 offset:2048
	ds_read_b128 v[178:181], v160 offset:3072
	ds_read_b128 v[182:185], v160 offset:4096
	ds_read_b128 v[186:189], v160 offset:5120
	ds_read_b128 v[190:193], v160 offset:6144
	ds_read_b128 v[194:197], v160 offset:7168
	global_load_lds_dwordx4 v136, s[16:17]
	s_waitcnt lgkmcnt(0)
	s_setprio 1
	s_barrier
	v_mfma_f32_16x16x32_bf16 v[124:127], v[144:147], v[166:169], v[124:127]
	v_mfma_f32_16x16x32_bf16 v[120:123], v[152:155], v[166:169], v[120:123]
	v_mfma_f32_16x16x32_bf16 v[116:119], v[144:147], v[174:177], v[116:119]
	v_mfma_f32_16x16x32_bf16 v[112:115], v[152:155], v[174:177], v[112:115]
	v_mfma_f32_16x16x32_bf16 v[104:107], v[144:147], v[182:185], v[104:107]
	v_mfma_f32_16x16x32_bf16 v[96:99], v[152:155], v[182:185], v[96:99]
	v_mfma_f32_16x16x32_bf16 v[88:91], v[144:147], v[190:193], v[88:91]
	v_mfma_f32_16x16x32_bf16 v[80:83], v[152:155], v[190:193], v[80:83]
	v_mfma_f32_16x16x32_bf16 v[124:127], v[148:151], v[170:173], v[124:127]
	v_mfma_f32_16x16x32_bf16 v[120:123], v[162:165], v[170:173], v[120:123]
	v_mfma_f32_16x16x32_bf16 v[116:119], v[148:151], v[178:181], v[116:119]
	v_mfma_f32_16x16x32_bf16 v[112:115], v[162:165], v[178:181], v[112:115]
	v_mfma_f32_16x16x32_bf16 v[104:107], v[148:151], v[186:189], v[104:107]
	v_mfma_f32_16x16x32_bf16 v[96:99], v[162:165], v[186:189], v[96:99]
	v_mfma_f32_16x16x32_bf16 v[88:91], v[148:151], v[194:197], v[88:91]
	v_mfma_f32_16x16x32_bf16 v[80:83], v[162:165], v[194:197], v[80:83]
	s_barrier
	s_setprio 0
	s_add_i32 m0, s30, 0xe000
	s_nop 0
	global_load_lds_dwordx4 v138, s[16:17]
	s_add_i32 s48, s39, s28
	s_add_u32 s98, s18, 0x80
	s_addc_u32 s99, s19, 0
	s_add_u32 s100, s20, 0x80
	s_addc_u32 s101, s21, 0
	s_mov_b32 m0, s48
	ds_read_b128 v[198:201], v161
	ds_read_b128 v[202:205], v161 offset:1024
	ds_read_b128 v[206:209], v161 offset:2048
	ds_read_b128 v[210:213], v161 offset:3072
	global_load_lds_dwordx4 v132, s[18:19]
	s_add_i32 m0, s48, 0x2000
	s_nop 0
	global_load_lds_dwordx4 v128, s[18:19]
	s_waitcnt lgkmcnt(0)
	s_setprio 1
	s_barrier
	v_mfma_f32_16x16x32_bf16 v[108:111], v[198:201], v[166:169], v[108:111]
	v_mfma_f32_16x16x32_bf16 v[100:103], v[206:209], v[166:169], v[100:103]
	v_mfma_f32_16x16x32_bf16 v[92:95], v[198:201], v[174:177], v[92:95]
	v_mfma_f32_16x16x32_bf16 v[84:87], v[206:209], v[174:177], v[84:87]
	v_mfma_f32_16x16x32_bf16 v[76:79], v[198:201], v[182:185], v[76:79]
	v_mfma_f32_16x16x32_bf16 v[72:75], v[206:209], v[182:185], v[72:75]
	v_mfma_f32_16x16x32_bf16 v[68:71], v[198:201], v[190:193], v[68:71]
	v_mfma_f32_16x16x32_bf16 v[64:67], v[206:209], v[190:193], v[64:67]
	v_mfma_f32_16x16x32_bf16 v[108:111], v[202:205], v[170:173], v[108:111]
	v_mfma_f32_16x16x32_bf16 v[100:103], v[210:213], v[170:173], v[100:103]
	v_mfma_f32_16x16x32_bf16 v[92:95], v[202:205], v[178:181], v[92:95]
	v_mfma_f32_16x16x32_bf16 v[84:87], v[210:213], v[178:181], v[84:87]
	v_mfma_f32_16x16x32_bf16 v[76:79], v[202:205], v[186:189], v[76:79]
	v_mfma_f32_16x16x32_bf16 v[72:75], v[210:213], v[186:189], v[72:75]
	v_mfma_f32_16x16x32_bf16 v[68:71], v[202:205], v[194:197], v[68:71]
	v_mfma_f32_16x16x32_bf16 v[64:67], v[210:213], v[194:197], v[64:67]
	s_barrier
	s_setprio 0
	s_mov_b32 m0, s30
	ds_read_b128 v[166:169], v160 offset:16384
	ds_read_b128 v[170:173], v160 offset:17408
	ds_read_b128 v[174:177], v160 offset:18432
	ds_read_b128 v[178:181], v160 offset:19456
	ds_read_b128 v[182:185], v160 offset:20480
	ds_read_b128 v[186:189], v160 offset:21504
	ds_read_b128 v[190:193], v160 offset:22528
	ds_read_b128 v[194:197], v160 offset:23552
	global_load_lds_dwordx4 v134, s[20:21]
	s_waitcnt vmcnt(9)
	s_waitcnt lgkmcnt(0)
	s_setprio 1
	s_barrier
	v_mfma_f32_16x16x32_bf16 v[60:63], v[144:147], v[166:169], v[60:63]
	v_mfma_f32_16x16x32_bf16 v[56:59], v[152:155], v[166:169], v[56:59]
	v_mfma_f32_16x16x32_bf16 v[52:55], v[144:147], v[174:177], v[52:55]
	v_mfma_f32_16x16x32_bf16 v[44:47], v[152:155], v[174:177], v[44:47]
	v_mfma_f32_16x16x32_bf16 v[36:39], v[144:147], v[182:185], v[36:39]
	v_mfma_f32_16x16x32_bf16 v[28:31], v[152:155], v[182:185], v[28:31]
	v_mfma_f32_16x16x32_bf16 v[20:23], v[144:147], v[190:193], v[20:23]
	v_mfma_f32_16x16x32_bf16 v[12:15], v[152:155], v[190:193], v[12:15]
	v_mfma_f32_16x16x32_bf16 v[60:63], v[148:151], v[170:173], v[60:63]
	v_mfma_f32_16x16x32_bf16 v[56:59], v[162:165], v[170:173], v[56:59]
	v_mfma_f32_16x16x32_bf16 v[52:55], v[148:151], v[178:181], v[52:55]
	v_mfma_f32_16x16x32_bf16 v[44:47], v[162:165], v[178:181], v[44:47]
	v_mfma_f32_16x16x32_bf16 v[36:39], v[148:151], v[186:189], v[36:39]
	v_mfma_f32_16x16x32_bf16 v[28:31], v[162:165], v[186:189], v[28:31]
	v_mfma_f32_16x16x32_bf16 v[20:23], v[148:151], v[194:197], v[20:23]
	v_mfma_f32_16x16x32_bf16 v[12:15], v[162:165], v[194:197], v[12:15]
	s_barrier
	s_setprio 0
	s_mov_b32 m0, s31
	s_nop 0
	global_load_lds_dwordx4 v130, s[20:21]
	s_add_u32 s48, s18, 0x160000
	s_addc_u32 s49, s19, 0
	s_add_i32 s50, s40, s28
	s_mov_b32 m0, s50
	s_nop 0
	global_load_lds_dwordx4 v132, s[48:49]
	s_add_i32 m0, s50, 0x2000
	s_nop 0
	global_load_lds_dwordx4 v128, s[48:49]
	s_add_i32 s48, 0, 0x18000
	v_add_u32_e32 v162, s48, v157
	ds_read_b128 v[144:147], v162
	ds_read_b128 v[148:151], v162 offset:1024
	ds_read_b128 v[152:155], v162 offset:2048
	ds_read_b128 v[162:165], v162 offset:3072
	s_waitcnt vmcnt(6)
	s_setprio 1
	s_barrier
; #define PG8_STAGE(bufoff, gbase, voff) do { _Pragma("unroll") for (int _i = 0; _i < 2; ++_i) \
;     __builtin_amdgcn_global_load_lds((const unsigned*)((const char*)(gbase) + (voff)[_i]), (LAS unsigned*)(lds + (bufoff) + ldsw + _i * 8192), 16, 0, 0); } while (0)
; #define PG8_LDA(dst, b, h) do { _Pragma("unroll") for (int m = 0; m < 4; ++m) _Pragma("unroll") for (int k = 0; k < 2; ++k) dst[m][k] = *(const LAS bf16x8*)(lds + PG8_SA(b, h) + aoff + m * 2048 + k * 1024); } while (0)
; #define PG8_LDB(dst, b, h) do { _Pragma("unroll") for (int n = 0; n < 2; ++n) _Pragma("unroll") for (int k = 0; k < 2; ++k) dst[n][k] = *(const LAS bf16x8*)(lds + PG8_SB(b, h) + boff + n * 2048 + k * 1024); } while (0)
; #define PG8_WAIT_V(n) asm volatile("s_waitcnt vmcnt(" #n ")" ::: "memory")
; template <class Epi, class Sched = StaticOrder>
; DI void gemm_phase(LAS unsigned char* lds, const Gemm g, const Sched& S, const Epi& E) {
;     ...
;     for (int t = 0; t < nt; t += 2) {
;       const bool last = (t == nt - 2);
;       const char* a1 = cA + (size_t)(t + 1) * kstep;
;       const char* a2 = last ? nA : cA + (size_t)(t + 2) * kstep; const char* b2 = last ? nB : cB + (size_t)(t + 2) * kstep;
;       const char* a3 = a2 + kstep; const char* b3 = b2 + kstep;
;       PG8_LDB(B0, 0, 0); PG8_SCHED; PG8_LDA(At, 0, 0); PG8_STAGE(PG8_SA(1, 1), a1 + hstep, voffA);
;       PG8_WAIT_L(8); PG8_BAR; PG8_WAIT_L(0); PG8_MMA(0, 0, At, B0); PG8_BAR; PG8_SCHED;
;       PG8_LDB(B1, 0, 1); PG8_STAGE(PG8_SB(0, 0), b2, voffB);
;       PG8_BAR; PG8_WAIT_L(0); PG8_MMA(0, 1, At, B1); PG8_BAR;
;       PG8_LDA(At, 0, 1); PG8_STAGE(PG8_SA(0, 0), a2, voffA);
;       PG8_BAR; PG8_WAIT_L(0); PG8_MMA(1, 0, At, B0); PG8_BAR; PG8_SCHED;
;       PG8_STAGE(PG8_SB(0, 1), b2 + hstep, voffB);
;       PG8_WAIT_V(6); PG8_BAR; PG8_MMA(1, 1, At, B1); PG8_BAR;
;       PG8_LDB(B0, 1, 0); PG8_SCHED; PG8_LDA(At, 1, 0); PG8_STAGE(PG8_SA(0, 1), a2 + hstep, voffA);
;       PG8_WAIT_L(8); PG8_BAR; PG8_WAIT_L(0); PG8_MMA(0, 0, At, B0); PG8_BAR; PG8_SCHED;
;       PG8_LDB(B1, 1, 1); PG8_STAGE(PG8_SB(1, 0), b3, voffB);
;       PG8_BAR; PG8_WAIT_L(0); PG8_MMA(0, 1, At, B1); PG8_BAR;
;       PG8_LDA(At, 1, 1); PG8_STAGE(PG8_SA(1, 0), a3, voffA);
;       PG8_BAR; PG8_WAIT_L(0); PG8_MMA(1, 0, At, B0); PG8_BAR; PG8_SCHED;
;       PG8_STAGE(PG8_SB(1, 1), b3 + hstep, voffB);
;       PG8_WAIT_V(6); PG8_BAR; PG8_MMA(1, 1, At, B1); PG8_BAR;
	v_mfma_f32_16x16x32_bf16 v[48:51], v[198:201], v[166:169], v[48:51]
	v_mfma_f32_16x16x32_bf16 v[40:43], v[206:209], v[166:169], v[40:43]
	v_mfma_f32_16x16x32_bf16 v[32:35], v[198:201], v[174:177], v[32:35]
	v_mfma_f32_16x16x32_bf16 v[24:27], v[206:209], v[174:177], v[24:27]
	v_mfma_f32_16x16x32_bf16 v[16:19], v[198:201], v[182:185], v[16:19]
	v_mfma_f32_16x16x32_bf16 v[8:11], v[206:209], v[182:185], v[8:11]
	v_mfma_f32_16x16x32_bf16 v[4:7], v[198:201], v[190:193], v[4:7]
	v_mfma_f32_16x16x32_bf16 v[0:3], v[206:209], v[190:193], v[0:3]
	v_mfma_f32_16x16x32_bf16 v[48:51], v[202:205], v[170:173], v[48:51]
	v_mfma_f32_16x16x32_bf16 v[40:43], v[210:213], v[170:173], v[40:43]
	v_mfma_f32_16x16x32_bf16 v[32:35], v[202:205], v[178:181], v[32:35]
	v_mfma_f32_16x16x32_bf16 v[24:27], v[210:213], v[178:181], v[24:27]
	v_mfma_f32_16x16x32_bf16 v[16:19], v[202:205], v[186:189], v[16:19]
	v_mfma_f32_16x16x32_bf16 v[8:11], v[210:213], v[186:189], v[8:11]
	v_mfma_f32_16x16x32_bf16 v[4:7], v[202:205], v[194:197], v[4:7]
	v_mfma_f32_16x16x32_bf16 v[0:3], v[210:213], v[194:197], v[0:3]
	s_barrier
	s_setprio 0
	s_add_u32 s20, s20, 0x160000
	s_addc_u32 s21, s21, 0
	s_mov_b32 m0, s33
	ds_read_b128 v[166:169], v160 offset:32768
	ds_read_b128 v[170:173], v160 offset:33792
	ds_read_b128 v[174:177], v160 offset:34816
	ds_read_b128 v[178:181], v160 offset:35840
	ds_read_b128 v[182:185], v160 offset:36864
	ds_read_b128 v[186:189], v160 offset:37888
	ds_read_b128 v[190:193], v160 offset:38912
	ds_read_b128 v[194:197], v160 offset:39936
	global_load_lds_dwordx4 v134, s[20:21]
	s_waitcnt lgkmcnt(0)
	s_setprio 1
	s_barrier
	v_mfma_f32_16x16x32_bf16 v[124:127], v[144:147], v[166:169], v[124:127]
	v_mfma_f32_16x16x32_bf16 v[120:123], v[152:155], v[166:169], v[120:123]
	v_mfma_f32_16x16x32_bf16 v[116:119], v[144:147], v[174:177], v[116:119]
	v_mfma_f32_16x16x32_bf16 v[112:115], v[152:155], v[174:177], v[112:115]
	v_mfma_f32_16x16x32_bf16 v[104:107], v[144:147], v[182:185], v[104:107]
	v_mfma_f32_16x16x32_bf16 v[96:99], v[152:155], v[182:185], v[96:99]
	v_mfma_f32_16x16x32_bf16 v[88:91], v[144:147], v[190:193], v[88:91]
	v_mfma_f32_16x16x32_bf16 v[80:83], v[152:155], v[190:193], v[80:83]
	v_mfma_f32_16x16x32_bf16 v[124:127], v[148:151], v[170:173], v[124:127]
	v_mfma_f32_16x16x32_bf16 v[120:123], v[162:165], v[170:173], v[120:123]
	v_mfma_f32_16x16x32_bf16 v[116:119], v[148:151], v[178:181], v[116:119]
	v_mfma_f32_16x16x32_bf16 v[112:115], v[162:165], v[178:181], v[112:115]
	v_mfma_f32_16x16x32_bf16 v[104:107], v[148:151], v[186:189], v[104:107]
	v_mfma_f32_16x16x32_bf16 v[96:99], v[162:165], v[186:189], v[96:99]
	v_mfma_f32_16x16x32_bf16 v[88:91], v[148:151], v[194:197], v[88:91]
	v_mfma_f32_16x16x32_bf16 v[80:83], v[162:165], v[194:197], v[80:83]
	s_barrier
	s_setprio 0
	s_mov_b32 m0, s34
	s_nop 0
	global_load_lds_dwordx4 v130, s[20:21]
	s_add_i32 s20, 0, 0x1c000
	s_add_i32 s21, s48, s28
	v_add_u32_e32 v210, s20, v157
	s_mov_b32 m0, s21
	ds_read_b128 v[198:201], v210
	ds_read_b128 v[202:205], v210 offset:1024
	ds_read_b128 v[206:209], v210 offset:2048
	ds_read_b128 v[210:213], v210 offset:3072
	global_load_lds_dwordx4 v132, s[98:99]
	s_add_i32 m0, s21, 0x2000
	s_nop 0
	global_load_lds_dwordx4 v128, s[98:99]
	s_waitcnt lgkmcnt(0)
	s_setprio 1
	s_barrier
	v_mfma_f32_16x16x32_bf16 v[108:111], v[198:201], v[166:169], v[108:111]
	v_mfma_f32_16x16x32_bf16 v[100:103], v[206:209], v[166:169], v[100:103]
	v_mfma_f32_16x16x32_bf16 v[92:95], v[198:201], v[174:177], v[92:95]
	v_mfma_f32_16x16x32_bf16 v[84:87], v[206:209], v[174:177], v[84:87]
	v_mfma_f32_16x16x32_bf16 v[76:79], v[198:201], v[182:185], v[76:79]
	v_mfma_f32_16x16x32_bf16 v[72:75], v[206:209], v[182:185], v[72:75]
	v_mfma_f32_16x16x32_bf16 v[68:71], v[198:201], v[190:193], v[68:71]
	v_mfma_f32_16x16x32_bf16 v[64:67], v[206:209], v[190:193], v[64:67]
	v_mfma_f32_16x16x32_bf16 v[108:111], v[202:205], v[170:173], v[108:111]
	v_mfma_f32_16x16x32_bf16 v[100:103], v[210:213], v[170:173], v[100:103]
	v_mfma_f32_16x16x32_bf16 v[92:95], v[202:205], v[178:181], v[92:95]
	v_mfma_f32_16x16x32_bf16 v[84:87], v[210:213], v[178:181], v[84:87]
	v_mfma_f32_16x16x32_bf16 v[76:79], v[202:205], v[186:189], v[76:79]
	v_mfma_f32_16x16x32_bf16 v[72:75], v[210:213], v[186:189], v[72:75]
	v_mfma_f32_16x16x32_bf16 v[68:71], v[202:205], v[194:197], v[68:71]
	v_mfma_f32_16x16x32_bf16 v[64:67], v[210:213], v[194:197], v[64:67]
	s_barrier
	s_setprio 0
	s_mov_b32 m0, s35
	ds_read_b128 v[166:169], v160 offset:49152
	ds_read_b128 v[170:173], v160 offset:50176
	ds_read_b128 v[174:177], v160 offset:51200
	ds_read_b128 v[178:181], v160 offset:52224
	ds_read_b128 v[182:185], v160 offset:53248
	ds_read_b128 v[186:189], v160 offset:54272
	ds_read_b128 v[190:193], v160 offset:55296
	ds_read_b128 v[194:197], v160 offset:56320
	global_load_lds_dwordx4 v134, s[100:101]
	s_waitcnt vmcnt(9)
	s_waitcnt lgkmcnt(0)
	s_setprio 1
	s_barrier
	v_mfma_f32_16x16x32_bf16 v[60:63], v[144:147], v[166:169], v[60:63]
	v_mfma_f32_16x16x32_bf16 v[56:59], v[152:155], v[166:169], v[56:59]
	v_mfma_f32_16x16x32_bf16 v[52:55], v[144:147], v[174:177], v[52:55]
	v_mfma_f32_16x16x32_bf16 v[44:47], v[152:155], v[174:177], v[44:47]
	v_mfma_f32_16x16x32_bf16 v[36:39], v[144:147], v[182:185], v[36:39]
	v_mfma_f32_16x16x32_bf16 v[28:31], v[152:155], v[182:185], v[28:31]
	v_mfma_f32_16x16x32_bf16 v[20:23], v[144:147], v[190:193], v[20:23]
	v_mfma_f32_16x16x32_bf16 v[12:15], v[152:155], v[190:193], v[12:15]
	v_mfma_f32_16x16x32_bf16 v[60:63], v[148:151], v[170:173], v[60:63]
	v_mfma_f32_16x16x32_bf16 v[56:59], v[162:165], v[170:173], v[56:59]
	v_mfma_f32_16x16x32_bf16 v[52:55], v[148:151], v[178:181], v[52:55]
	v_mfma_f32_16x16x32_bf16 v[44:47], v[162:165], v[178:181], v[44:47]
	v_mfma_f32_16x16x32_bf16 v[36:39], v[148:151], v[186:189], v[36:39]
	v_mfma_f32_16x16x32_bf16 v[28:31], v[162:165], v[186:189], v[28:31]
	v_mfma_f32_16x16x32_bf16 v[20:23], v[148:151], v[194:197], v[20:23]
	v_mfma_f32_16x16x32_bf16 v[12:15], v[162:165], v[194:197], v[12:15]
	s_barrier
; #define PG8_STAGE(bufoff, gbase, voff) do { _Pragma("unroll") for (int _i = 0; _i < 2; ++_i) \
;     __builtin_amdgcn_global_load_lds((const unsigned*)((const char*)(gbase) + (voff)[_i]), (LAS unsigned*)(lds + (bufoff) + ldsw + _i * 8192), 16, 0, 0); } while (0)
; #define PG8_MMA(ai, bj, At, Bt) do { __builtin_amdgcn_s_setprio(1); _Pragma("unroll") for (int m = 0; m < 4; ++m) _Pragma("unroll") for (int n = 0; n < 2; ++n) _Pragma("unroll") for (int k = 0; k < 2; ++k) \
;     acc[ai][bj][m][n] = __builtin_amdgcn_mfma_f32_16x16x32_bf16(Bt[n][k], At[m][k], acc[ai][bj][m][n], 0, 0, 0); __builtin_amdgcn_s_setprio(0); } while (0)
; #define PG8_WAIT_V(n) asm volatile("s_waitcnt vmcnt(" #n ")" ::: "memory")
; #define PG8_WAIT_L(n) asm volatile("s_waitcnt lgkmcnt(" #n ")" ::: "memory")
; #define PG8_BAR __builtin_amdgcn_s_barrier()
; #define PG8_SCHED __builtin_amdgcn_sched_barrier(0)
;   DI void operator()(const f32x4 (&acc)[2][2][4][2], const Unit& u, int wr, int wc, int fr, int fq) const {
;     const int row0 = u.pm * BM + wr * 64 + fr, col0 = u.pn * BM + wc * 32 + 8 * fq;
; #pragma unroll
;     for (int ai = 0; ai < 2; ++ai) {
;       f32x4 bv[4][2][2];
; #pragma unroll
;       for (int m = 0; m < 4; ++m)
; #pragma unroll
;         for (int bj = 0; bj < 2; ++bj) {
;           const float* bp = base + (size_t)(row0 + ai * HALF + m * 16) * 2048 + col0 + bj * HALF;
;           bv[m][bj][0] = *(const f32x4*)bp; bv[m][bj][1] = *(const f32x4*)(bp + 4);
;         }
; template <class Epi, class Sched = StaticOrder>
; DI void gemm_phase(LAS unsigned char* lds, const Gemm g, const Sched& S, const Epi& E) {
;     ...
;       PG8_BAR; PG8_WAIT_L(0); PG8_MMA(1, 0, At, B0); PG8_BAR; PG8_SCHED;
;       PG8_STAGE(PG8_SB(1, 1), b3 + hstep, voffB);
;       PG8_WAIT_V(6); PG8_BAR; PG8_MMA(1, 1, At, B1); PG8_BAR;
;     }
;     E(acc, cur, wr, wc, fr, fq);
	s_setprio 0
	s_mov_b32 m0, s36
	s_nop 0
	global_load_lds_dwordx4 v130, s[100:101]
	s_add_u32 s18, s18, 0x160080
	s_addc_u32 s19, s19, 0
	s_add_i32 s20, s20, s28
	s_mov_b32 m0, s20
	s_nop 0
	global_load_lds_dwordx4 v132, s[18:19]
	s_add_i32 m0, s20, 0x2000
	s_nop 0
	global_load_lds_dwordx4 v128, s[18:19]
	ds_read_b128 v[144:147], v159
	ds_read_b128 v[148:151], v159 offset:1024
	ds_read_b128 v[152:155], v159 offset:2048
	ds_read_b128 v[162:165], v159 offset:3072
	s_waitcnt vmcnt(6)
	s_setprio 1
	s_barrier
	v_mfma_f32_16x16x32_bf16 v[48:51], v[198:201], v[166:169], v[48:51]
	v_mfma_f32_16x16x32_bf16 v[40:43], v[206:209], v[166:169], v[40:43]
	v_mfma_f32_16x16x32_bf16 v[32:35], v[198:201], v[174:177], v[32:35]
	v_mfma_f32_16x16x32_bf16 v[24:27], v[206:209], v[174:177], v[24:27]
	v_mfma_f32_16x16x32_bf16 v[16:19], v[198:201], v[182:185], v[16:19]
	v_mfma_f32_16x16x32_bf16 v[8:11], v[206:209], v[182:185], v[8:11]
	v_mfma_f32_16x16x32_bf16 v[4:7], v[198:201], v[190:193], v[4:7]
	v_mfma_f32_16x16x32_bf16 v[0:3], v[206:209], v[190:193], v[0:3]
	v_mfma_f32_16x16x32_bf16 v[48:51], v[202:205], v[170:173], v[48:51]
	v_mfma_f32_16x16x32_bf16 v[40:43], v[210:213], v[170:173], v[40:43]
	v_mfma_f32_16x16x32_bf16 v[32:35], v[202:205], v[178:181], v[32:35]
	v_mfma_f32_16x16x32_bf16 v[24:27], v[210:213], v[178:181], v[24:27]
	v_mfma_f32_16x16x32_bf16 v[16:19], v[202:205], v[186:189], v[16:19]
	v_mfma_f32_16x16x32_bf16 v[8:11], v[210:213], v[186:189], v[8:11]
	v_mfma_f32_16x16x32_bf16 v[4:7], v[202:205], v[194:197], v[4:7]
	v_mfma_f32_16x16x32_bf16 v[0:3], v[210:213], v[194:197], v[0:3]
	s_add_i32 s47, s47, 2
	s_add_u32 s16, s16, 0x100
	s_addc_u32 s17, s17, 0
	s_add_u32 s45, s45, 0x100
	s_addc_u32 s46, s46, 0
	s_cmpk_gt_u32 s47, 0x55
	s_barrier
	s_setprio 0
	s_cbranch_scc0 .LBB0_1424
	s_waitcnt lgkmcnt(0)
	v_lshl_or_b32 v144, s44, 8, v158
	v_lshl_add_u32 v154, s43, 8, v156
	v_ashrrev_i32_e32 v145, 31, v144
	v_lshlrev_b64 v[144:145], 2, v[144:145]
	v_ashrrev_i32_e32 v155, 31, v154
	v_lshl_add_u64 v[146:147], s[54:55], 0, v[144:145]
	v_lshlrev_b64 v[148:149], 13, v[154:155]
	v_or_b32_e32 v174, 16, v154
	v_lshl_add_u64 v[170:171], v[146:147], 0, v[148:149]
	v_ashrrev_i32_e32 v175, 31, v174
	global_load_dwordx4 v[150:153], v[170:171], off offset:16
	global_load_dwordx4 v[162:165], v[170:171], off
	global_load_dwordx4 v[166:169], v[170:171], off offset:528
	s_nop 0
	global_load_dwordx4 v[170:173], v[170:171], off offset:512
	v_lshlrev_b64 v[222:223], 13, v[174:175]
	v_or_b32_e32 v190, 32, v154
	v_lshl_add_u64 v[186:187], v[146:147], 0, v[222:223]
	v_ashrrev_i32_e32 v191, 31, v190
	global_load_dwordx4 v[174:177], v[186:187], off offset:16
	global_load_dwordx4 v[178:181], v[186:187], off
	global_load_dwordx4 v[182:185], v[186:187], off offset:528
	s_nop 0
	global_load_dwordx4 v[186:189], v[186:187], off offset:512
	v_lshlrev_b64 v[224:225], 13, v[190:191]
	v_or_b32_e32 v154, 48, v154
	v_lshl_add_u64 v[202:203], v[146:147], 0, v[224:225]
	v_ashrrev_i32_e32 v155, 31, v154
	global_load_dwordx4 v[190:193], v[202:203], off offset:16
	global_load_dwordx4 v[194:197], v[202:203], off
	global_load_dwordx4 v[198:201], v[202:203], off offset:528
	s_nop 0
	global_load_dwordx4 v[202:205], v[202:203], off offset:512
	v_lshlrev_b64 v[154:155], 13, v[154:155]
	v_lshl_add_u64 v[218:219], v[146:147], 0, v[154:155]
	global_load_dwordx4 v[206:209], v[218:219], off offset:16
	global_load_dwordx4 v[210:213], v[218:219], off
	global_load_dwordx4 v[214:217], v[218:219], off offset:528
	s_nop 0
	global_load_dwordx4 v[218:221], v[218:219], off offset:512
	s_and_b64 vcc, exec, s[0:1]
	s_mov_b32 s44, s41
	s_mov_b32 s43, s42
	s_mov_b64 s[18:19], s[4:5]
	s_mov_b64 s[16:17], s[2:3]
	s_waitcnt vmcnt(0)
;   DI void operator()(const f32x4 (&acc)[2][2][4][2], const Unit& u, int wr, int wc, int fr, int fq) const {
;     ...
;           const float* bp = base + (size_t)(row0 + ai * HALF + m * 16) * 2048 + col0 + bj * HALF;
;           bv[m][bj][0] = *(const f32x4*)bp; bv[m][bj][1] = *(const f32x4*)(bp + 4);
;         }
; #pragma unroll
;       for (int m = 0; m < 4; ++m) {
;         const int row = row0 + ai * HALF + m * 16;
;         const size_t off = (size_t)row * 2048 + col0;
;         float ss = 0.f;
; #pragma unroll
;         for (int bj = 0; bj < 2; ++bj) {
;           const f32x4 v0 = acc[ai][bj][m][0] + bv[m][bj][0], v1 = acc[ai][bj][m][1] + bv[m][bj][1];
;           *(f32x4*)(C + off + bj * HALF) = v0; *(f32x4*)(C + off + bj * HALF + 4) = v1;
	v_pk_add_f32 v[120:121], v[120:121], v[150:151]
	v_lshl_add_u64 v[150:151], s[54:55], 0, v[148:149]
	v_pk_add_f32 v[126:127], v[126:127], v[164:165]
	v_pk_add_f32 v[124:125], v[124:125], v[162:163]
	v_lshl_add_u64 v[150:151], v[150:151], 0, v[144:145]
	v_pk_add_f32 v[110:111], v[110:111], v[172:173]
	v_pk_add_f32 v[108:109], v[108:109], v[170:171]
	v_pk_add_f32 v[122:123], v[122:123], v[152:153]
	global_store_dwordx4 v[150:151], v[124:127], off
	global_store_dwordx4 v[150:151], v[120:123], off offset:16
	v_pk_add_f32 v[102:103], v[102:103], v[168:169]
	v_pk_add_f32 v[100:101], v[100:101], v[166:167]
	global_store_dwordx4 v[150:151], v[108:111], off offset:512
	global_store_dwordx4 v[150:151], v[100:103], off offset:528
	v_pk_add_f32 v[94:95], v[94:95], v[188:189]
	v_pk_add_f32 v[108:109], v[112:113], v[174:175]
	v_lshl_add_u64 v[112:113], s[54:55], 0, v[222:223]
	v_pk_add_f32 v[102:103], v[118:119], v[180:181]
	v_pk_add_f32 v[100:101], v[116:117], v[178:179]
	v_lshl_add_u64 v[112:113], v[112:113], 0, v[144:145]
	v_pk_add_f32 v[92:93], v[92:93], v[186:187]
	v_pk_add_f32 v[110:111], v[114:115], v[176:177]
	global_store_dwordx4 v[112:113], v[100:103], off
	global_store_dwordx4 v[112:113], v[108:111], off offset:16
	v_pk_add_f32 v[86:87], v[86:87], v[184:185]
	v_pk_add_f32 v[84:85], v[84:85], v[182:183]
	global_store_dwordx4 v[112:113], v[92:95], off offset:512
	global_store_dwordx4 v[112:113], v[84:87], off offset:528
	v_pk_add_f32 v[78:79], v[78:79], v[204:205]
	v_pk_add_f32 v[92:93], v[96:97], v[190:191]
	v_lshl_add_u64 v[96:97], s[54:55], 0, v[224:225]
	v_pk_add_f32 v[86:87], v[106:107], v[196:197]
	v_pk_add_f32 v[84:85], v[104:105], v[194:195]
	v_lshl_add_u64 v[96:97], v[96:97], 0, v[144:145]
	v_pk_add_f32 v[76:77], v[76:77], v[202:203]
	v_pk_add_f32 v[94:95], v[98:99], v[192:193]
	global_store_dwordx4 v[96:97], v[84:87], off
	global_store_dwordx4 v[96:97], v[92:95], off offset:16
	v_pk_add_f32 v[74:75], v[74:75], v[200:201]
	v_pk_add_f32 v[72:73], v[72:73], v[198:199]
	global_store_dwordx4 v[96:97], v[76:79], off offset:512
	global_store_dwordx4 v[96:97], v[72:75], off offset:528
	v_pk_add_f32 v[70:71], v[70:71], v[220:221]
	v_pk_add_f32 v[76:77], v[80:81], v[206:207]
	v_lshl_add_u64 v[80:81], s[54:55], 0, v[154:155]
	v_pk_add_f32 v[74:75], v[90:91], v[212:213]
	v_pk_add_f32 v[72:73], v[88:89], v[210:211]
	v_lshl_add_u64 v[80:81], v[80:81], 0, v[144:145]
	v_pk_add_f32 v[68:69], v[68:69], v[218:219]
	v_pk_add_f32 v[64:65], v[64:65], v[214:215]
	v_lshl_add_u64 v[154:155], v[148:149], 0, s[10:11]
	v_pk_add_f32 v[78:79], v[82:83], v[208:209]
	global_store_dwordx4 v[80:81], v[72:75], off
	global_store_dwordx4 v[80:81], v[76:79], off offset:16
	v_pk_add_f32 v[66:67], v[66:67], v[216:217]
	global_store_dwordx4 v[80:81], v[68:71], off offset:512
	global_store_dwordx4 v[80:81], v[64:67], off offset:528
	v_lshl_add_u64 v[152:153], v[148:149], 0, s[12:13]
	v_lshl_add_u64 v[150:151], v[148:149], 0, s[14:15]
	v_lshl_add_u64 v[64:65], v[146:147], 0, v[154:155]
	global_load_dwordx4 v[108:111], v[64:65], off offset:16
	global_load_dwordx4 v[120:123], v[64:65], off
	global_load_dwordx4 v[92:95], v[64:65], off offset:528
	global_load_dwordx4 v[100:103], v[64:65], off offset:512
	v_lshl_add_u64 v[64:65], v[146:147], 0, v[152:153]
	global_load_dwordx4 v[88:91], v[64:65], off offset:16
	global_load_dwordx4 v[96:99], v[64:65], off
	global_load_dwordx4 v[76:79], v[64:65], off offset:528
	global_load_dwordx4 v[84:87], v[64:65], off offset:512
	v_lshl_add_u64 v[68:69], v[146:147], 0, v[150:151]
	global_load_dwordx4 v[72:75], v[68:69], off offset:16
	global_load_dwordx4 v[80:83], v[68:69], off
	global_load_dwordx4 v[64:67], v[68:69], off offset:528
	s_nop 0
	global_load_dwordx4 v[68:71], v[68:69], off offset:512
	v_lshl_add_u64 v[148:149], v[148:149], 0, s[6:7]
	v_lshl_add_u64 v[112:113], v[146:147], 0, v[148:149]
	global_load_dwordx4 v[116:119], v[112:113], off offset:16
	global_load_dwordx4 v[124:127], v[112:113], off
	global_load_dwordx4 v[104:107], v[112:113], off offset:528
	s_nop 0
	global_load_dwordx4 v[112:115], v[112:113], off offset:512
	s_waitcnt vmcnt(0)
	v_pk_add_f32 v[56:57], v[56:57], v[108:109]
	v_lshl_add_u64 v[108:109], s[54:55], 0, v[154:155]
	v_pk_add_f32 v[62:63], v[62:63], v[122:123]
	v_pk_add_f32 v[60:61], v[60:61], v[120:121]
	v_lshl_add_u64 v[108:109], v[108:109], 0, v[144:145]
	v_pk_add_f32 v[50:51], v[50:51], v[102:103]
	v_pk_add_f32 v[48:49], v[48:49], v[100:101]
	v_pk_add_f32 v[58:59], v[58:59], v[110:111]
	global_store_dwordx4 v[108:109], v[60:63], off
	global_store_dwordx4 v[108:109], v[56:59], off offset:16
	v_pk_add_f32 v[42:43], v[42:43], v[94:95]
	v_pk_add_f32 v[40:41], v[40:41], v[92:93]
	global_store_dwordx4 v[108:109], v[48:51], off offset:512
	global_store_dwordx4 v[108:109], v[40:43], off offset:528
	v_pk_add_f32 v[34:35], v[34:35], v[86:87]
	v_lshl_add_u64 v[48:49], s[54:55], 0, v[152:153]
	v_pk_add_f32 v[42:43], v[54:55], v[98:99]
	v_pk_add_f32 v[40:41], v[52:53], v[96:97]
	v_lshl_add_u64 v[48:49], v[48:49], 0, v[144:145]
	v_pk_add_f32 v[32:33], v[32:33], v[84:85]
	v_pk_add_f32 v[46:47], v[46:47], v[90:91]
	v_pk_add_f32 v[44:45], v[44:45], v[88:89]
	global_store_dwordx4 v[48:49], v[40:43], off
	global_store_dwordx4 v[48:49], v[44:47], off offset:16
	v_pk_add_f32 v[26:27], v[26:27], v[78:79]
	v_pk_add_f32 v[24:25], v[24:25], v[76:77]
	global_store_dwordx4 v[48:49], v[32:35], off offset:512
	global_store_dwordx4 v[48:49], v[24:27], off offset:528
	v_pk_add_f32 v[18:19], v[18:19], v[70:71]
	v_lshl_add_u64 v[32:33], s[54:55], 0, v[150:151]
	v_pk_add_f32 v[26:27], v[38:39], v[82:83]
	v_pk_add_f32 v[24:25], v[36:37], v[80:81]
	v_lshl_add_u64 v[32:33], v[32:33], 0, v[144:145]
	v_pk_add_f32 v[16:17], v[16:17], v[68:69]
	v_pk_add_f32 v[30:31], v[30:31], v[74:75]
	v_pk_add_f32 v[28:29], v[28:29], v[72:73]
	global_store_dwordx4 v[32:33], v[24:27], off
	global_store_dwordx4 v[32:33], v[28:31], off offset:16
	v_pk_add_f32 v[10:11], v[10:11], v[66:67]
	v_pk_add_f32 v[8:9], v[8:9], v[64:65]
	global_store_dwordx4 v[32:33], v[16:19], off offset:512
	global_store_dwordx4 v[32:33], v[8:11], off offset:528
	v_pk_add_f32 v[6:7], v[6:7], v[114:115]
	v_lshl_add_u64 v[16:17], s[54:55], 0, v[148:149]
	v_pk_add_f32 v[10:11], v[22:23], v[126:127]
	v_pk_add_f32 v[8:9], v[20:21], v[124:125]
	v_lshl_add_u64 v[16:17], v[16:17], 0, v[144:145]
	v_pk_add_f32 v[4:5], v[4:5], v[112:113]
	v_pk_add_f32 v[14:15], v[14:15], v[118:119]
	v_pk_add_f32 v[12:13], v[12:13], v[116:117]
	global_store_dwordx4 v[16:17], v[8:11], off
	global_store_dwordx4 v[16:17], v[12:15], off offset:16
	v_pk_add_f32 v[2:3], v[2:3], v[106:107]
	v_pk_add_f32 v[0:1], v[0:1], v[104:105]
	global_store_dwordx4 v[16:17], v[4:7], off offset:512
	global_store_dwordx4 v[16:17], v[0:3], off offset:528
	s_cbranch_vccz .LBB0_1417
	s_waitcnt vmcnt(0)
	s_cmpk_gt_u32 s23, 0xff
	s_cbranch_scc1 .LBB0_1428
	s_barrier
